# RG-LRU gate GEMM B fragments all in flight; Hyena I/O second-half loads pipelined; row_rstd loops unrolled with all loads in flight
# baseline (speedup 1.0000x reference)
; DI float bf2f(u16 v) { return __uint_as_float(((unsigned)v) << 16); }
;     ...
;   __syncthreads();
;   {
;     const int c = tid & 63, tq = tid >> 6, cg = g * 64 + c;
;     const float w0 = p->lru_conv_w[(l * 4 + 0) * 512 + cg], w1 = p->lru_conv_w[(l * 4 + 1) * 512 + cg];
;     const float w2 = p->lru_conv_w[(l * 4 + 2) * 512 + cg], w3 = p->lru_conv_w[(l * 4 + 3) * 512 + cg];
;     const float bias = p->lru_conv_b[l * 512 + cg];
;     auto ld = [&](int tt) -> float {
;       int tp = tpos0 + tt;
;       return (tp >= 0 && tp < seglen) ? bf2f(Zlx[(size_t)(base + tt) * 512 + cg]) : 0.f;
;     };
;     const int t0 = tq * 16;
;     float xv[19];
; #pragma unroll
;     for (int e = 0; e < 19; ++e) xv[e] = ld(t0 - 2 + e);
; #pragma unroll
;     for (int tt = 0; tt < 16; ++tt) {
;       const float y = w0 * xv[tt] + w1 * xv[tt + 1] + w2 * xv[tt + 2] + w3 * xv[tt + 3] + bias;
;       uf[(t0 + tt) * 65 + c] = y;
.LBB0_523:
	s_load_dwordx2 s[6:7], s[8:9], 0x130
	s_waitcnt lgkmcnt(0)
	s_barrier
	s_load_dwordx4 s[24:27], s[8:9], 0x68
	s_and_b32 s5, s4, 7
	v_and_b32_e32 v10, 63, v66
	s_lshl_b32 s4, s5, 6
	v_or_b32_e32 v11, s4, v10
	s_waitcnt lgkmcnt(0)
	v_mov_b32_e32 v2, s24
	v_mov_b32_e32 v3, s25
	v_or_b32_e32 v198, s77, v11
	v_lshl_add_u64 v[2:3], v[198:199], 2, v[2:3]
	v_add_co_u32_e32 v14, vcc, s47, v2
	v_mov_b32_e32 v12, s26
	v_mov_b32_e32 v13, s27
	v_addc_co_u32_e32 v15, vcc, 0, v3, vcc
	global_load_dword v5, v[2:3], off
	global_load_dword v8, v[2:3], off offset:2048
	global_load_dword v7, v[14:15], off
	global_load_dword v6, v[14:15], off offset:2048
	v_or_b32_e32 v198, s80, v11
	v_lshl_add_u64 v[2:3], v[198:199], 2, v[12:13]
	global_load_dword v9, v[2:3], off
	v_ashrrev_i32_e32 v4, 6, v66
	v_lshlrev_b32_e32 v14, 4, v4
	v_lshlrev_b32_e32 v31, 1, v11
	v_add_u32_e32 v38, s12, v14
	s_add_u32 s10, s6, 0x3850000
	s_addc_u32 s11, s7, 0
	v_lshl_add_u32 v31, v38, 10, v31
	v_add_u32_e32 v34, 0x1000, v31
	v_add_u32_e32 v35, 0x2000, v31
	v_add_u32_e32 v36, 0x3000, v31
	v_add_u32_e32 v37, 0x4000, v31
	global_load_ushort v12, v31, s[10:11] offset:-2048
	global_load_ushort v11, v31, s[10:11] offset:-1024
	global_load_ushort v15, v31, s[10:11]
	global_load_ushort v13, v31, s[10:11] offset:1024
	global_load_ushort v18, v31, s[10:11] offset:2048
	global_load_ushort v16, v31, s[10:11] offset:3072
	global_load_ushort v20, v34, s[10:11]
	global_load_ushort v19, v34, s[10:11] offset:1024
	global_load_ushort v22, v34, s[10:11] offset:2048
	global_load_ushort v21, v34, s[10:11] offset:3072
	global_load_ushort v24, v35, s[10:11]
	global_load_ushort v23, v35, s[10:11] offset:1024
	global_load_ushort v26, v35, s[10:11] offset:2048
	global_load_ushort v25, v35, s[10:11] offset:3072
	global_load_ushort v28, v36, s[10:11]
	global_load_ushort v27, v36, s[10:11] offset:1024
	global_load_ushort v30, v36, s[10:11] offset:2048
	global_load_ushort v29, v36, s[10:11] offset:3072
	global_load_ushort v39, v37, s[10:11]
	v_or_b32_e32 v17, 1, v14
	v_add_u32_e32 v38, s13, v14
	v_add_u32_e32 v40, -2, v38
	s_waitcnt vmcnt(0)
	v_cmp_gt_u32_e32 vcc, s15, v40
	v_lshlrev_b32_e32 v12, 16, v12
	v_add_u32_e32 v41, -1, v38
	v_cndmask_b32_e32 v12, 0, v12, vcc
	v_cmp_gt_u32_e32 vcc, s15, v41
	v_lshlrev_b32_e32 v11, 16, v11
	v_add_u32_e32 v40, 0, v38
	v_cndmask_b32_e32 v11, 0, v11, vcc
	v_cmp_gt_u32_e32 vcc, s15, v40
	v_lshlrev_b32_e32 v15, 16, v15
	v_add_u32_e32 v41, 1, v38
	v_cndmask_b32_e32 v15, 0, v15, vcc
	v_cmp_gt_u32_e32 vcc, s15, v41
	v_lshlrev_b32_e32 v13, 16, v13
	v_add_u32_e32 v40, 2, v38
	v_cndmask_b32_e32 v13, 0, v13, vcc
	v_cmp_gt_u32_e32 vcc, s15, v40
	v_lshlrev_b32_e32 v18, 16, v18
	v_add_u32_e32 v41, 3, v38
	v_cndmask_b32_e32 v18, 0, v18, vcc
	v_cmp_gt_u32_e32 vcc, s15, v41
	v_lshlrev_b32_e32 v16, 16, v16
	v_add_u32_e32 v40, 4, v38
	v_cndmask_b32_e32 v16, 0, v16, vcc
	v_cmp_gt_u32_e32 vcc, s15, v40
	v_lshlrev_b32_e32 v20, 16, v20
	v_add_u32_e32 v41, 5, v38
	v_cndmask_b32_e32 v20, 0, v20, vcc
	v_cmp_gt_u32_e32 vcc, s15, v41
	v_lshlrev_b32_e32 v19, 16, v19
	v_add_u32_e32 v40, 6, v38
	v_cndmask_b32_e32 v19, 0, v19, vcc
	v_cmp_gt_u32_e32 vcc, s15, v40
	v_lshlrev_b32_e32 v22, 16, v22
	v_add_u32_e32 v41, 7, v38
	v_cndmask_b32_e32 v22, 0, v22, vcc
	v_cmp_gt_u32_e32 vcc, s15, v41
	v_lshlrev_b32_e32 v21, 16, v21
	v_add_u32_e32 v40, 8, v38
	v_cndmask_b32_e32 v21, 0, v21, vcc
	v_cmp_gt_u32_e32 vcc, s15, v40
	v_lshlrev_b32_e32 v24, 16, v24
	v_add_u32_e32 v41, 9, v38
	v_cndmask_b32_e32 v24, 0, v24, vcc
	v_cmp_gt_u32_e32 vcc, s15, v41
	v_lshlrev_b32_e32 v23, 16, v23
	v_add_u32_e32 v40, 10, v38
	v_cndmask_b32_e32 v23, 0, v23, vcc
	v_cmp_gt_u32_e32 vcc, s15, v40
	v_lshlrev_b32_e32 v26, 16, v26
	v_add_u32_e32 v41, 11, v38
	v_cndmask_b32_e32 v26, 0, v26, vcc
	v_cmp_gt_u32_e32 vcc, s15, v41
	v_lshlrev_b32_e32 v25, 16, v25
	v_add_u32_e32 v40, 12, v38
	v_cndmask_b32_e32 v25, 0, v25, vcc
	v_cmp_gt_u32_e32 vcc, s15, v40
	v_lshlrev_b32_e32 v28, 16, v28
	v_add_u32_e32 v41, 13, v38
	v_cndmask_b32_e32 v28, 0, v28, vcc
	v_cmp_gt_u32_e32 vcc, s15, v41
	v_lshlrev_b32_e32 v27, 16, v27
	v_add_u32_e32 v40, 14, v38
	v_cndmask_b32_e32 v27, 0, v27, vcc
	v_cmp_gt_u32_e32 vcc, s15, v40
	v_lshlrev_b32_e32 v30, 16, v30
	v_add_u32_e32 v41, 15, v38
	v_cndmask_b32_e32 v30, 0, v30, vcc
	v_cmp_gt_u32_e32 vcc, s15, v41
	v_lshlrev_b32_e32 v29, 16, v29
	v_add_u32_e32 v40, 16, v38
	v_cndmask_b32_e32 v29, 0, v29, vcc
	v_cmp_gt_u32_e32 vcc, s15, v40
	v_lshlrev_b32_e32 v39, 16, v39
	s_nop 0
	v_cndmask_b32_e32 v39, 0, v39, vcc
	v_mov_b32_e32 v14, v39
	v_lshlrev_b32_e32 v2, 2, v10
	v_lshlrev_b32_e32 v3, 1, v10
	v_lshrrev_b32_e32 v74, 5, v10
	v_sub_u32_e32 v10, v2, v3
	s_waitcnt vmcnt(3)
	v_mul_f32_e32 v3, v8, v11
	v_fmac_f32_e32 v3, v5, v12
	s_waitcnt vmcnt(2)
	v_fmac_f32_e32 v3, v7, v15
	s_waitcnt vmcnt(1)
	v_fmac_f32_e32 v3, v6, v13
	s_waitcnt vmcnt(0)
;     ...
; #pragma unroll
;     for (int tt = 0; tt < 16; ++tt) {
;       const float y = w0 * xv[tt] + w1 * xv[tt + 1] + w2 * xv[tt + 2] + w3 * xv[tt + 3] + bias;
;       uf[(t0 + tt) * 65 + c] = y;
;       Au[(t0 + tt) * 72 + c] = f2bf(y);
;     }
;     ...
;   const u16* Wl = (const u16*)(p->ws + OFF_W) + W_LRU + (size_t)g * 256 * 64;
; #pragma unroll
;   for (int s = 0; s < 4; ++s) {
;     bf16x8 a = *(const bf16x8*)(Au + (th * 32 + l31) * 72 + s * 16 + hh * 8);
	v_add_f32_e32 v3, v9, v3
	s_movk_i32 s10, 0x1040
	v_mad_u64_u32 v[32:33], s[10:11], v4, s10, v[2:3]
	s_movk_i32 s10, 0x900
	ds_write_b32 v32, v3 offset:9216
	v_cvt_pk_bf16_f32 v3, v3, s0
	v_mad_u64_u32 v[32:33], s[10:11], v4, s10, v[10:11]
	ds_write_b16 v32, v3
	v_mul_f32_e32 v3, v8, v15
	v_fmac_f32_e32 v3, v5, v11
	v_fmac_f32_e32 v3, v7, v13
	v_fmac_f32_e32 v3, v6, v18
	v_add_f32_e32 v12, v9, v3
	v_mad_u64_u32 v[2:3], s[10:11], v17, s54, v[2:3]
	v_cvt_pk_bf16_f32 v3, v12, s0
	v_mad_u64_u32 v[10:11], s[10:11], v17, s60, v[10:11]
	ds_write_b16 v10, v3
	v_mul_f32_e32 v3, v8, v13
	v_fmac_f32_e32 v3, v5, v15
	v_fmac_f32_e32 v3, v7, v18
	v_fmac_f32_e32 v3, v6, v16
	v_add_f32_e32 v3, v9, v3
	v_add_u32_e32 v11, 0x2400, v2
	ds_write2_b32 v11, v12, v3 offset1:65
	v_cvt_pk_bf16_f32 v3, v3, s0
	ds_write_b16 v10, v3 offset:144
	v_mul_f32_e32 v3, v8, v18
	v_fmac_f32_e32 v3, v5, v13
	v_fmac_f32_e32 v3, v7, v16
	v_fmac_f32_e32 v3, v6, v20
	v_add_f32_e32 v3, v9, v3
	v_cvt_pk_bf16_f32 v12, v3, s0
	ds_write_b16 v10, v12 offset:288
	v_mul_f32_e32 v12, v8, v16
	v_fmac_f32_e32 v12, v5, v18
	v_fmac_f32_e32 v12, v7, v20
	v_fmac_f32_e32 v12, v6, v19
	v_add_f32_e32 v12, v9, v12
	ds_write2_b32 v11, v3, v12 offset0:130 offset1:195
	v_cvt_pk_bf16_f32 v3, v12, s0
	ds_write_b16 v10, v3 offset:432
	v_mul_f32_e32 v3, v8, v20
	v_fmac_f32_e32 v3, v5, v16
	v_fmac_f32_e32 v3, v7, v19
	v_fmac_f32_e32 v3, v6, v22
	v_add_f32_e32 v3, v9, v3
	v_cvt_pk_bf16_f32 v11, v3, s0
	ds_write_b16 v10, v11 offset:576
	v_mul_f32_e32 v11, v8, v19
	v_fmac_f32_e32 v11, v5, v20
	v_fmac_f32_e32 v11, v7, v22
	v_fmac_f32_e32 v11, v6, v21
	v_add_f32_e32 v11, v9, v11
	v_add_u32_e32 v12, 0x2800, v2
	ds_write2_b32 v12, v3, v11 offset0:4 offset1:69
	v_cvt_pk_bf16_f32 v3, v11, s0
	ds_write_b16 v10, v3 offset:720
	v_mul_f32_e32 v3, v8, v22
	v_fmac_f32_e32 v3, v5, v19
	v_fmac_f32_e32 v3, v7, v21
	v_fmac_f32_e32 v3, v6, v24
	v_add_f32_e32 v3, v9, v3
	v_cvt_pk_bf16_f32 v11, v3, s0
	ds_write_b16 v10, v11 offset:864
	v_mul_f32_e32 v11, v8, v21
	v_fmac_f32_e32 v11, v5, v22
	v_fmac_f32_e32 v11, v7, v24
	v_fmac_f32_e32 v11, v6, v23
	v_add_f32_e32 v11, v9, v11
	ds_write2_b32 v12, v3, v11 offset0:134 offset1:199
	v_cvt_pk_bf16_f32 v3, v11, s0
	ds_write_b16 v10, v3 offset:1008
	v_mul_f32_e32 v3, v8, v24
	v_fmac_f32_e32 v3, v5, v21
	v_fmac_f32_e32 v3, v7, v23
	v_fmac_f32_e32 v3, v6, v26
	v_add_f32_e32 v3, v9, v3
	v_cvt_pk_bf16_f32 v11, v3, s0
	ds_write_b16 v10, v11 offset:1152
	v_mul_f32_e32 v11, v8, v23
	v_fmac_f32_e32 v11, v5, v24
	v_fmac_f32_e32 v11, v7, v26
	v_fmac_f32_e32 v11, v6, v25
	v_add_f32_e32 v11, v9, v11
	v_add_u32_e32 v12, 0x2c00, v2
	ds_write2_b32 v12, v3, v11 offset0:8 offset1:73
	v_cvt_pk_bf16_f32 v3, v11, s0
	ds_write_b16 v10, v3 offset:1296
	v_mul_f32_e32 v3, v8, v26
	v_fmac_f32_e32 v3, v5, v23
	v_fmac_f32_e32 v3, v7, v25
	v_fmac_f32_e32 v3, v6, v28
	v_add_f32_e32 v3, v9, v3
	v_cvt_pk_bf16_f32 v11, v3, s0
	ds_write_b16 v10, v11 offset:1440
	v_mul_f32_e32 v11, v8, v25
	v_fmac_f32_e32 v11, v5, v26
	v_fmac_f32_e32 v11, v7, v28
	v_fmac_f32_e32 v11, v6, v27
	v_add_f32_e32 v11, v9, v11
	ds_write2_b32 v12, v3, v11 offset0:138 offset1:203
	v_cvt_pk_bf16_f32 v3, v11, s0
	ds_write_b16 v10, v3 offset:1584
	v_mul_f32_e32 v3, v8, v28
	v_fmac_f32_e32 v3, v5, v25
	v_fmac_f32_e32 v3, v7, v27
	v_fmac_f32_e32 v3, v6, v30
	v_add_f32_e32 v3, v9, v3
	v_cvt_pk_bf16_f32 v11, v3, s0
	ds_write_b16 v10, v11 offset:1728
	v_mul_f32_e32 v11, v8, v27
	v_fmac_f32_e32 v11, v5, v28
	v_fmac_f32_e32 v11, v7, v30
	v_fmac_f32_e32 v11, v6, v29
	v_add_f32_e32 v11, v9, v11
	v_add_u32_e32 v12, 0x3000, v2
	ds_write2_b32 v12, v3, v11 offset0:12 offset1:77
	v_cvt_pk_bf16_f32 v3, v11, s0
	ds_write_b16 v10, v3 offset:1872
	v_mul_f32_e32 v3, v8, v30
	v_fmac_f32_e32 v3, v5, v27
	v_fmac_f32_e32 v3, v7, v29
	v_fmac_f32_e32 v3, v6, v14
	v_add_f32_e32 v3, v9, v3
	s_lshl_b32 s5, s5, 15
	ds_write_b32 v2, v3 offset:12856
	v_cvt_pk_bf16_f32 v2, v3, s0
	s_add_u32 s10, s6, s5
	v_ashrrev_i32_e32 v78, 2, v66
	s_movk_i32 s5, 0xffe0
	ds_write_b16 v10, v2 offset:2016
	v_bfi_b32 v2, s5, v78, v66
	v_lshlrev_b32_e32 v198, 4, v74
	v_and_b32_e32 v31, 31, v66
	s_addc_u32 s11, s7, 0
	v_mad_u64_u32 v[72:73], s[12:13], v2, s60, v[198:199]
	v_lshlrev_b32_e32 v2, 5, v4
	v_lshl_add_u64 v[96:97], s[10:11], 0, v[198:199]
	s_mov_b64 s[10:11], 0xe3e0000
	v_and_or_b32 v77, v2, 32, v31
	v_lshl_add_u64 v[14:15], v[96:97], 0, s[10:11]
	v_lshlrev_b32_e32 v198, 7, v77
	v_lshl_add_u64 v[92:93], v[14:15], 0, v[198:199]
	s_waitcnt lgkmcnt(0)
	s_barrier
; #define MFMA32(a, b, c) __builtin_amdgcn_mfma_f32_32x32x16_bf16((a), (b), (c), 0, 0, 0)
;     ...
;   const u16* Wl = (const u16*)(p->ws + OFF_W) + W_LRU + (size_t)g * 256 * 64;
; #pragma unroll
;   for (int s = 0; s < 4; ++s) {
;     bf16x8 a = *(const bf16x8*)(Au + (th * 32 + l31) * 72 + s * 16 + hh * 8);
; #pragma unroll
;     for (int m = 0; m < 4; ++m) {
;       bf16x8 bb = *(const bf16x8*)(Wl + (size_t)(m * 64 + chh * 32 + l31) * 64 + s * 16 + hh * 8);
;       acc[m] = MFMA32(a, bb, acc[m]);
;     }
;   }
;   asm volatile("s_nop 15\n\ts_nop 15" ::: "memory");
;   const int cl = chh * 32 + l31, cg = g * 64 + cl;
;   float hsum[16];
; #pragma unroll
;   for (int dir = 0; dir < 2; ++dir) {
;     const float ba = p->lru_ba[(l * 2 + dir) * 512 + cg], bx = p->lru_bx[(l * 2 + dir) * 512 + cg];
;     const float lam = p->lru_lam[(l * 2 + dir) * 512 + cg];
;     const float ex = __expf(-lam);
;     const float sp = (ex < 0.03f) ? ex * (1.f - ex * (0.5f - ex * (0.33333334f - 0.25f * ex))) : __logf(1.f + ex);
	s_mov_b64 vcc, 0x2000
	v_lshl_add_u64 v[120:121], v[92:93], 0, vcc
	v_lshl_add_u64 v[122:123], v[120:121], 0, vcc
	v_lshl_add_u64 v[124:125], v[122:123], 0, vcc
	ds_read_b128 v[104:107], v72
	ds_read_b128 v[108:111], v72 offset:32
	ds_read_b128 v[112:115], v72 offset:64
	ds_read_b128 v[116:119], v72 offset:96
	global_load_dwordx4 v[132:135], v[92:93], off
	global_load_dwordx4 v[148:151], v[120:121], off
	global_load_dwordx4 v[164:167], v[122:123], off
	global_load_dwordx4 v[180:183], v[124:125], off
	global_load_dwordx4 v[136:139], v[92:93], off offset:32
	global_load_dwordx4 v[152:155], v[120:121], off offset:32
	global_load_dwordx4 v[168:171], v[122:123], off offset:32
	global_load_dwordx4 v[184:187], v[124:125], off offset:32
	global_load_dwordx4 v[140:143], v[92:93], off offset:64
	global_load_dwordx4 v[156:159], v[120:121], off offset:64
	global_load_dwordx4 v[172:175], v[122:123], off offset:64
	global_load_dwordx4 v[188:191], v[124:125], off offset:64
	global_load_dwordx4 v[144:147], v[92:93], off offset:96
	global_load_dwordx4 v[160:163], v[120:121], off offset:96
	global_load_dwordx4 v[176:179], v[122:123], off offset:96
	global_load_dwordx4 v[192:195], v[124:125], off offset:96
	s_mov_b64 s[10:11], 0xe3e0040
	v_lshl_add_u64 v[102:103], v[96:97], 0, s[10:11]
	s_or_b32 s5, s4, s74
	s_waitcnt lgkmcnt(1)
	s_waitcnt lgkmcnt(0)
	s_nop 0
	s_waitcnt lgkmcnt(0)
	s_nop 15
	s_nop 15
	s_load_dwordx4 s[24:27], s[8:9], 0x90
	v_or_b32_e32 v198, s5, v77
	v_lshlrev_b64 v[84:85], 2, v[198:199]
	s_load_dwordx2 s[8:9], s[8:9], 0x80
	s_waitcnt lgkmcnt(0)
	v_lshl_add_u64 v[68:69], s[26:27], 0, v[84:85]
	s_waitcnt lgkmcnt(0)
	s_waitcnt vmcnt(15)
	v_mfma_f32_32x32x16_bf16 v[50:65], v[104:107], v[132:135], 0
	s_waitcnt vmcnt(14)
	v_mfma_f32_32x32x16_bf16 v[34:49], v[104:107], v[148:151], 0
	s_waitcnt vmcnt(13)
	v_mfma_f32_32x32x16_bf16 v[18:33], v[104:107], v[164:167], 0
	s_waitcnt vmcnt(12)
	v_mfma_f32_32x32x16_bf16 v[2:17], v[104:107], v[180:183], 0
	s_waitcnt vmcnt(11)
	v_mfma_f32_32x32x16_bf16 v[50:65], v[108:111], v[136:139], v[50:65]
	s_waitcnt vmcnt(10)
	v_mfma_f32_32x32x16_bf16 v[34:49], v[108:111], v[152:155], v[34:49]
	s_waitcnt vmcnt(9)
	v_mfma_f32_32x32x16_bf16 v[18:33], v[108:111], v[168:171], v[18:33]
	s_waitcnt vmcnt(8)
	v_mfma_f32_32x32x16_bf16 v[2:17], v[108:111], v[184:187], v[2:17]
	s_waitcnt vmcnt(7)
	v_mfma_f32_32x32x16_bf16 v[50:65], v[112:115], v[140:143], v[50:65]
	s_waitcnt vmcnt(6)
	v_mfma_f32_32x32x16_bf16 v[34:49], v[112:115], v[156:159], v[34:49]
	s_waitcnt vmcnt(5)
	v_mfma_f32_32x32x16_bf16 v[18:33], v[112:115], v[172:175], v[18:33]
	s_waitcnt vmcnt(4)
	v_mfma_f32_32x32x16_bf16 v[2:17], v[112:115], v[188:191], v[2:17]
	s_waitcnt vmcnt(3)
	v_mfma_f32_32x32x16_bf16 v[50:65], v[116:119], v[144:147], v[50:65]
	s_waitcnt vmcnt(2)
	v_mfma_f32_32x32x16_bf16 v[34:49], v[116:119], v[160:163], v[34:49]
	s_waitcnt vmcnt(1)
	v_mfma_f32_32x32x16_bf16 v[18:33], v[116:119], v[176:179], v[18:33]
	s_waitcnt vmcnt(0)
	v_mfma_f32_32x32x16_bf16 v[2:17], v[116:119], v[192:195], v[2:17]
	global_load_dword v76, v[68:69], off
	s_mov_b32 s5, 0x3cf5c28f
	s_waitcnt vmcnt(0)
	v_mul_f32_e32 v76, 0xbfb8aa3b, v76
	v_lshl_add_u64 v[70:71], s[8:9], 0, v[84:85]
	v_lshl_add_u64 v[72:73], s[24:25], 0, v[84:85]
	global_load_dword v75, v[70:71], off
	global_load_dword v67, v[72:73], off
	v_exp_f32_e32 v79, v76
	v_cmp_ngt_f32_e32 vcc, s5, v79
	s_and_saveexec_b64 s[8:9], vcc
	s_xor_b64 s[10:11], exec, s[8:9]
	s_cbranch_execz .LBB0_563
	v_add_f32_e32 v76, 1.0, v79
	s_mov_b32 s5, 0x800000
	v_cmp_gt_f32_e32 vcc, s5, v76
	s_mov_b32 s5, 0x3f317217
	s_nop 0
	v_cndmask_b32_e64 v79, 0, 32, vcc
	v_ldexp_f32 v76, v76, v79
	v_log_f32_e32 v76, v76
	s_nop 0
	v_mul_f32_e32 v79, 0x3f317217, v76
	v_fma_f32 v79, v76, s5, -v79
	v_fmac_f32_e32 v79, 0x3377d1cf, v76
	s_mov_b32 s5, 0x7f800000
	v_fmac_f32_e32 v79, 0x3f317217, v76
	v_cmp_lt_f32_e64 s[8:9], |v76|, s5
	s_nop 1
	v_cndmask_b32_e64 v76, v76, v79, s[8:9]
	v_mov_b32_e32 v79, 0x41b17218
	v_cndmask_b32_e32 v79, 0, v79, vcc
	v_sub_f32_e32 v76, v76, v79

; DI float bf2f(u16 v) { return __uint_as_float(((unsigned)v) << 16); }
; DI float sconv3(const u16* row, int t, int n, float w0, float w1, float w2, float bias) {
;   float xm = (t > 0) ? bf2f(row[t - 1]) : 0.f, x0 = bf2f(row[t]), xp = (t + 1 < n) ? bf2f(row[t + 1]) : 0.f;
;   return w0 * xm + w1 * x0 + w2 * xp + bias;
; DI void hyena_unit(KP p, int l, int c, char* smem) {
;     ...
;     for (int pr = 0; pr < 2; ++pr) {
;       const int b0 = 2 * pr, b1 = b0 + 1;
;       u16* r0 = Zhy + (size_t)(b0 * 1536 + c) * 4096;
;       u16* r1 = Zhy + (size_t)(b1 * 1536 + c) * 4096;
;       u16* y0p = yct + (size_t)(b0 * 512 + c) * 4096;
;       u16* y1p = yct + (size_t)(b1 * 512 + c) * 4096;
;       __syncthreads();
; #pragma unroll 4
;       for (int jj = 0; jj < 16; ++jj) {
;         const int t = tid + 256 * jj;
;         float v0, v1;
;         if (o == 0) { v0 = sconv3(r0, t, 4096, vw0, vw1, vw2, vb); v1 = sconv3(r1, t, 4096, vw0, vw1, vw2, vb); }
;         else { v0 = bf2f(r0[t]); v1 = bf2f(r1[t]); }
;         buf[SW(t)] = mkf2(v0, v1);
;         buf[SW(t + 4096)] = mkf2(0.f, 0.f);
;       }
.LBB0_937:
	s_mul_i32 s82, s83, 0xc00
	s_add_i32 s28, s82, s86
	s_lshl_b32 s2, s83, 1
	s_ashr_i32 s29, s28, 31
	s_xor_b64 s[36:37], s[6:7], -1
	s_or_b32 s78, s2, 1
	s_lshl_b64 s[2:3], s[28:29], 13
	s_add_u32 s24, s80, s2
	s_mul_i32 s29, s78, 0x600
	s_addc_u32 s25, s76, s3
	s_add_i32 s6, s29, s86
	s_ashr_i32 s7, s6, 31
	s_lshl_b64 s[4:5], s[6:7], 13
	s_add_u32 s26, s80, s4
	s_addc_u32 s27, s76, s5
	s_add_i32 s4, s40, s82
	s_ashr_i32 s5, s4, 31
	s_lshl_b64 s[4:5], s[4:5], 13
	v_lshl_add_u64 v[2:3], v[70:71], 0, s[4:5]
	v_lshl_add_u64 v[4:5], v[70:71], 0, s[2:3]
	s_mov_b64 s[22:23], 0
	s_movk_i32 s2, 0x200
	s_barrier
	v_lshlrev_b32_e32 v6, 1, v66
	v_xor_b32_e32 v8, v66, v155
	v_add_u32_e32 v7, 0x1000, v6
	v_lshlrev_b32_e32 v8, 3, v8
	s_and_b64 vcc, exec, s[34:35]
	s_cbranch_vccnz .Lhy_inA_direct
	v_cmp_eq_u32_e64 s[8:9], 0, v66
	v_cmp_eq_u32_e32 vcc, 0xff, v66
	s_mov_b64 s[10:11], vcc
	global_load_ushort v18, v6, s[24:25] offset:-2
	global_load_ushort v16, v6, s[24:25] offset:0
	global_load_ushort v19, v6, s[24:25] offset:2
	global_load_ushort v20, v6, s[26:27] offset:-2
	global_load_ushort v17, v6, s[26:27] offset:0
	global_load_ushort v21, v6, s[26:27] offset:2
	global_load_ushort v24, v6, s[24:25] offset:510
	global_load_ushort v22, v6, s[24:25] offset:512
	global_load_ushort v25, v6, s[24:25] offset:514
	global_load_ushort v26, v6, s[26:27] offset:510
	global_load_ushort v23, v6, s[26:27] offset:512
	global_load_ushort v27, v6, s[26:27] offset:514
	global_load_ushort v30, v6, s[24:25] offset:1022
	global_load_ushort v28, v6, s[24:25] offset:1024
	global_load_ushort v31, v6, s[24:25] offset:1026
	global_load_ushort v32, v6, s[26:27] offset:1022
	global_load_ushort v29, v6, s[26:27] offset:1024
	global_load_ushort v33, v6, s[26:27] offset:1026
	global_load_ushort v36, v6, s[24:25] offset:1534
	global_load_ushort v34, v6, s[24:25] offset:1536
	global_load_ushort v37, v6, s[24:25] offset:1538
	global_load_ushort v38, v6, s[26:27] offset:1534
	global_load_ushort v35, v6, s[26:27] offset:1536
	global_load_ushort v39, v6, s[26:27] offset:1538
	global_load_ushort v42, v6, s[24:25] offset:2046
	global_load_ushort v40, v6, s[24:25] offset:2048
	global_load_ushort v43, v6, s[24:25] offset:2050
	global_load_ushort v44, v6, s[26:27] offset:2046
	global_load_ushort v41, v6, s[26:27] offset:2048
	global_load_ushort v45, v6, s[26:27] offset:2050
	global_load_ushort v48, v6, s[24:25] offset:2558
	global_load_ushort v46, v6, s[24:25] offset:2560
	global_load_ushort v49, v6, s[24:25] offset:2562
	global_load_ushort v50, v6, s[26:27] offset:2558
	global_load_ushort v47, v6, s[26:27] offset:2560
	global_load_ushort v51, v6, s[26:27] offset:2562
	global_load_ushort v54, v6, s[24:25] offset:3070
	global_load_ushort v52, v6, s[24:25] offset:3072
	global_load_ushort v55, v6, s[24:25] offset:3074
	global_load_ushort v56, v6, s[26:27] offset:3070
	global_load_ushort v53, v6, s[26:27] offset:3072
	global_load_ushort v57, v6, s[26:27] offset:3074
	global_load_ushort v60, v6, s[24:25] offset:3582
	global_load_ushort v58, v6, s[24:25] offset:3584
	global_load_ushort v61, v6, s[24:25] offset:3586
	global_load_ushort v62, v6, s[26:27] offset:3582
	global_load_ushort v59, v6, s[26:27] offset:3584
	global_load_ushort v63, v6, s[26:27] offset:3586
	s_waitcnt vmcnt(42)
	v_cndmask_b32_e64 v18, v18, 0, s[8:9]
	v_cndmask_b32_e64 v20, v20, 0, s[8:9]
	v_lshlrev_b32_e32 v16, 16, v16
	v_lshlrev_b32_e32 v17, 16, v17
	v_lshlrev_b32_e32 v18, 16, v18
	v_lshlrev_b32_e32 v19, 16, v19
	v_lshlrev_b32_e32 v20, 16, v20
	v_lshlrev_b32_e32 v21, 16, v21
	v_mul_f32_e32 v16, v197, v16
	v_mul_f32_e32 v17, v197, v17
	v_fmac_f32_e32 v16, v76, v18
	v_fmac_f32_e32 v17, v76, v20
	v_fmac_f32_e32 v16, v77, v19
	v_fmac_f32_e32 v17, v77, v21
	v_add_f32_e32 v16, v200, v16
	v_add_f32_e32 v17, v200, v17
	ds_write_b64 v8, v[16:17]
	global_load_ushort v18, v7, s[24:25] offset:-2
	global_load_ushort v16, v7, s[24:25] offset:0
	global_load_ushort v19, v7, s[24:25] offset:2
	global_load_ushort v20, v7, s[26:27] offset:-2
	global_load_ushort v17, v7, s[26:27] offset:0
	global_load_ushort v21, v7, s[26:27] offset:2
	s_waitcnt vmcnt(42)
	v_lshlrev_b32_e32 v22, 16, v22
	v_lshlrev_b32_e32 v23, 16, v23
	v_lshlrev_b32_e32 v24, 16, v24
	v_lshlrev_b32_e32 v25, 16, v25
	v_lshlrev_b32_e32 v26, 16, v26
	v_lshlrev_b32_e32 v27, 16, v27
	v_mul_f32_e32 v22, v197, v22
	v_mul_f32_e32 v23, v197, v23
	v_fmac_f32_e32 v22, v76, v24
	v_fmac_f32_e32 v23, v76, v26
	v_fmac_f32_e32 v22, v77, v25
	v_fmac_f32_e32 v23, v77, v27
	v_add_f32_e32 v22, v200, v22
	v_add_f32_e32 v23, v200, v23
	ds_write_b64 v8, v[22:23] offset:2048
	global_load_ushort v24, v7, s[24:25] offset:510
	global_load_ushort v22, v7, s[24:25] offset:512
	global_load_ushort v25, v7, s[24:25] offset:514
	global_load_ushort v26, v7, s[26:27] offset:510
	global_load_ushort v23, v7, s[26:27] offset:512
	global_load_ushort v27, v7, s[26:27] offset:514
	s_waitcnt vmcnt(42)
	v_lshlrev_b32_e32 v28, 16, v28
	v_lshlrev_b32_e32 v29, 16, v29
	v_lshlrev_b32_e32 v30, 16, v30
	v_lshlrev_b32_e32 v31, 16, v31
	v_lshlrev_b32_e32 v32, 16, v32
	v_lshlrev_b32_e32 v33, 16, v33
	v_mul_f32_e32 v28, v197, v28
	v_mul_f32_e32 v29, v197, v29
	v_fmac_f32_e32 v28, v76, v30
	v_fmac_f32_e32 v29, v76, v32
	v_fmac_f32_e32 v28, v77, v31
	v_fmac_f32_e32 v29, v77, v33
	v_add_f32_e32 v28, v200, v28
	v_add_f32_e32 v29, v200, v29
	ds_write_b64 v8, v[28:29] offset:4096
	global_load_ushort v30, v7, s[24:25] offset:1022
	global_load_ushort v28, v7, s[24:25] offset:1024
	global_load_ushort v31, v7, s[24:25] offset:1026
	global_load_ushort v32, v7, s[26:27] offset:1022
	global_load_ushort v29, v7, s[26:27] offset:1024
	global_load_ushort v33, v7, s[26:27] offset:1026
	s_waitcnt vmcnt(42)
; DI float bf2f(u16 v) { return __uint_as_float(((unsigned)v) << 16); }
; DI float sconv3(const u16* row, int t, int n, float w0, float w1, float w2, float bias) {
;   float xm = (t > 0) ? bf2f(row[t - 1]) : 0.f, x0 = bf2f(row[t]), xp = (t + 1 < n) ? bf2f(row[t + 1]) : 0.f;
;   return w0 * xm + w1 * x0 + w2 * xp + bias;
; DI void hyena_unit(KP p, int l, int c, char* smem) {
;     ...
;       __syncthreads();
; #pragma unroll 4
;       for (int jj = 0; jj < 16; ++jj) {
;         const int t = tid + 256 * jj;
;         float v0, v1;
;         if (o == 0) { v0 = sconv3(r0, t, 4096, vw0, vw1, vw2, vb); v1 = sconv3(r1, t, 4096, vw0, vw1, vw2, vb); }
;         else { v0 = bf2f(r0[t]); v1 = bf2f(r1[t]); }
;         buf[SW(t)] = mkf2(v0, v1);
;         buf[SW(t + 4096)] = mkf2(0.f, 0.f);
;       }
	v_lshlrev_b32_e32 v34, 16, v34
	v_lshlrev_b32_e32 v35, 16, v35
	v_lshlrev_b32_e32 v36, 16, v36
	v_lshlrev_b32_e32 v37, 16, v37
	v_lshlrev_b32_e32 v38, 16, v38
	v_lshlrev_b32_e32 v39, 16, v39
	v_mul_f32_e32 v34, v197, v34
	v_mul_f32_e32 v35, v197, v35
	v_fmac_f32_e32 v34, v76, v36
	v_fmac_f32_e32 v35, v76, v38
	v_fmac_f32_e32 v34, v77, v37
	v_fmac_f32_e32 v35, v77, v39
	v_add_f32_e32 v34, v200, v34
	v_add_f32_e32 v35, v200, v35
	ds_write_b64 v8, v[34:35] offset:6144
	global_load_ushort v36, v7, s[24:25] offset:1534
	global_load_ushort v34, v7, s[24:25] offset:1536
	global_load_ushort v37, v7, s[24:25] offset:1538
	global_load_ushort v38, v7, s[26:27] offset:1534
	global_load_ushort v35, v7, s[26:27] offset:1536
	global_load_ushort v39, v7, s[26:27] offset:1538
	s_waitcnt vmcnt(42)
	v_lshlrev_b32_e32 v40, 16, v40
	v_lshlrev_b32_e32 v41, 16, v41
	v_lshlrev_b32_e32 v42, 16, v42
	v_lshlrev_b32_e32 v43, 16, v43
	v_lshlrev_b32_e32 v44, 16, v44
	v_lshlrev_b32_e32 v45, 16, v45
	v_mul_f32_e32 v40, v197, v40
	v_mul_f32_e32 v41, v197, v41
	v_fmac_f32_e32 v40, v76, v42
	v_fmac_f32_e32 v41, v76, v44
	v_fmac_f32_e32 v40, v77, v43
	v_fmac_f32_e32 v41, v77, v45
	v_add_f32_e32 v40, v200, v40
	v_add_f32_e32 v41, v200, v41
	ds_write_b64 v8, v[40:41] offset:8192
	global_load_ushort v42, v7, s[24:25] offset:2046
	global_load_ushort v40, v7, s[24:25] offset:2048
	global_load_ushort v43, v7, s[24:25] offset:2050
	global_load_ushort v44, v7, s[26:27] offset:2046
	global_load_ushort v41, v7, s[26:27] offset:2048
	global_load_ushort v45, v7, s[26:27] offset:2050
	s_waitcnt vmcnt(42)
	v_lshlrev_b32_e32 v46, 16, v46
	v_lshlrev_b32_e32 v47, 16, v47
	v_lshlrev_b32_e32 v48, 16, v48
	v_lshlrev_b32_e32 v49, 16, v49
	v_lshlrev_b32_e32 v50, 16, v50
	v_lshlrev_b32_e32 v51, 16, v51
	v_mul_f32_e32 v46, v197, v46
	v_mul_f32_e32 v47, v197, v47
	v_fmac_f32_e32 v46, v76, v48
	v_fmac_f32_e32 v47, v76, v50
	v_fmac_f32_e32 v46, v77, v49
	v_fmac_f32_e32 v47, v77, v51
	v_add_f32_e32 v46, v200, v46
	v_add_f32_e32 v47, v200, v47
	ds_write_b64 v8, v[46:47] offset:10240
	global_load_ushort v48, v7, s[24:25] offset:2558
	global_load_ushort v46, v7, s[24:25] offset:2560
	global_load_ushort v49, v7, s[24:25] offset:2562
	global_load_ushort v50, v7, s[26:27] offset:2558
	global_load_ushort v47, v7, s[26:27] offset:2560
	global_load_ushort v51, v7, s[26:27] offset:2562
	s_waitcnt vmcnt(42)
	v_lshlrev_b32_e32 v52, 16, v52
	v_lshlrev_b32_e32 v53, 16, v53
	v_lshlrev_b32_e32 v54, 16, v54
	v_lshlrev_b32_e32 v55, 16, v55
	v_lshlrev_b32_e32 v56, 16, v56
	v_lshlrev_b32_e32 v57, 16, v57
	v_mul_f32_e32 v52, v197, v52
	v_mul_f32_e32 v53, v197, v53
	v_fmac_f32_e32 v52, v76, v54
	v_fmac_f32_e32 v53, v76, v56
	v_fmac_f32_e32 v52, v77, v55
	v_fmac_f32_e32 v53, v77, v57
	v_add_f32_e32 v52, v200, v52
	v_add_f32_e32 v53, v200, v53
	ds_write_b64 v8, v[52:53] offset:12288
	global_load_ushort v54, v7, s[24:25] offset:3070
	global_load_ushort v52, v7, s[24:25] offset:3072
	global_load_ushort v55, v7, s[24:25] offset:3074
	global_load_ushort v56, v7, s[26:27] offset:3070
	global_load_ushort v53, v7, s[26:27] offset:3072
	global_load_ushort v57, v7, s[26:27] offset:3074
	s_waitcnt vmcnt(42)
	v_lshlrev_b32_e32 v58, 16, v58
	v_lshlrev_b32_e32 v59, 16, v59
	v_lshlrev_b32_e32 v60, 16, v60
	v_lshlrev_b32_e32 v61, 16, v61
	v_lshlrev_b32_e32 v62, 16, v62
	v_lshlrev_b32_e32 v63, 16, v63
	v_mul_f32_e32 v58, v197, v58
	v_mul_f32_e32 v59, v197, v59
	v_fmac_f32_e32 v58, v76, v60
	v_fmac_f32_e32 v59, v76, v62
	v_fmac_f32_e32 v58, v77, v61
	v_fmac_f32_e32 v59, v77, v63
	v_add_f32_e32 v58, v200, v58
	v_add_f32_e32 v59, v200, v59
	ds_write_b64 v8, v[58:59] offset:14336
	global_load_ushort v60, v7, s[24:25] offset:3582
	global_load_ushort v58, v7, s[24:25] offset:3584
	global_load_ushort v61, v7, s[24:25] offset:3586
	global_load_ushort v62, v7, s[26:27] offset:3582
	global_load_ushort v59, v7, s[26:27] offset:3584
	global_load_ushort v63, v7, s[26:27] offset:3586
	s_waitcnt vmcnt(42)
; DI float bf2f(u16 v) { return __uint_as_float(((unsigned)v) << 16); }
; DI float sconv3(const u16* row, int t, int n, float w0, float w1, float w2, float bias) {
;   float xm = (t > 0) ? bf2f(row[t - 1]) : 0.f, x0 = bf2f(row[t]), xp = (t + 1 < n) ? bf2f(row[t + 1]) : 0.f;
;   return w0 * xm + w1 * x0 + w2 * xp + bias;
; DI void hyena_unit(KP p, int l, int c, char* smem) {
;     ...
;       __syncthreads();
; #pragma unroll 4
;       for (int jj = 0; jj < 16; ++jj) {
;         const int t = tid + 256 * jj;
;         float v0, v1;
;         if (o == 0) { v0 = sconv3(r0, t, 4096, vw0, vw1, vw2, vb); v1 = sconv3(r1, t, 4096, vw0, vw1, vw2, vb); }
;         else { v0 = bf2f(r0[t]); v1 = bf2f(r1[t]); }
;         buf[SW(t)] = mkf2(v0, v1);
;         buf[SW(t + 4096)] = mkf2(0.f, 0.f);
;       }
	v_lshlrev_b32_e32 v16, 16, v16
	v_lshlrev_b32_e32 v17, 16, v17
	v_lshlrev_b32_e32 v18, 16, v18
	v_lshlrev_b32_e32 v19, 16, v19
	v_lshlrev_b32_e32 v20, 16, v20
	v_lshlrev_b32_e32 v21, 16, v21
	v_mul_f32_e32 v16, v197, v16
	v_mul_f32_e32 v17, v197, v17
	v_fmac_f32_e32 v16, v76, v18
	v_fmac_f32_e32 v17, v76, v20
	v_fmac_f32_e32 v16, v77, v19
	v_fmac_f32_e32 v17, v77, v21
	v_add_f32_e32 v16, v200, v16
	v_add_f32_e32 v17, v200, v17
	ds_write_b64 v8, v[16:17] offset:16384
	s_waitcnt vmcnt(36)
	v_lshlrev_b32_e32 v22, 16, v22
	v_lshlrev_b32_e32 v23, 16, v23
	v_lshlrev_b32_e32 v24, 16, v24
	v_lshlrev_b32_e32 v25, 16, v25
	v_lshlrev_b32_e32 v26, 16, v26
	v_lshlrev_b32_e32 v27, 16, v27
	v_mul_f32_e32 v22, v197, v22
	v_mul_f32_e32 v23, v197, v23
	v_fmac_f32_e32 v22, v76, v24
	v_fmac_f32_e32 v23, v76, v26
	v_fmac_f32_e32 v22, v77, v25
	v_fmac_f32_e32 v23, v77, v27
	v_add_f32_e32 v22, v200, v22
	v_add_f32_e32 v23, v200, v23
	ds_write_b64 v8, v[22:23] offset:18432
	s_waitcnt vmcnt(30)
	v_lshlrev_b32_e32 v28, 16, v28
	v_lshlrev_b32_e32 v29, 16, v29
	v_lshlrev_b32_e32 v30, 16, v30
	v_lshlrev_b32_e32 v31, 16, v31
	v_lshlrev_b32_e32 v32, 16, v32
	v_lshlrev_b32_e32 v33, 16, v33
	v_mul_f32_e32 v28, v197, v28
	v_mul_f32_e32 v29, v197, v29
	v_fmac_f32_e32 v28, v76, v30
	v_fmac_f32_e32 v29, v76, v32
	v_fmac_f32_e32 v28, v77, v31
	v_fmac_f32_e32 v29, v77, v33
	v_add_f32_e32 v28, v200, v28
	v_add_f32_e32 v29, v200, v29
	ds_write_b64 v8, v[28:29] offset:20480
	s_waitcnt vmcnt(24)
	v_lshlrev_b32_e32 v34, 16, v34
	v_lshlrev_b32_e32 v35, 16, v35
	v_lshlrev_b32_e32 v36, 16, v36
	v_lshlrev_b32_e32 v37, 16, v37
	v_lshlrev_b32_e32 v38, 16, v38
	v_lshlrev_b32_e32 v39, 16, v39
	v_mul_f32_e32 v34, v197, v34
	v_mul_f32_e32 v35, v197, v35
	v_fmac_f32_e32 v34, v76, v36
	v_fmac_f32_e32 v35, v76, v38
	v_fmac_f32_e32 v34, v77, v37
	v_fmac_f32_e32 v35, v77, v39
	v_add_f32_e32 v34, v200, v34
	v_add_f32_e32 v35, v200, v35
	ds_write_b64 v8, v[34:35] offset:22528
	s_waitcnt vmcnt(18)
	v_lshlrev_b32_e32 v40, 16, v40
	v_lshlrev_b32_e32 v41, 16, v41
	v_lshlrev_b32_e32 v42, 16, v42
	v_lshlrev_b32_e32 v43, 16, v43
	v_lshlrev_b32_e32 v44, 16, v44
	v_lshlrev_b32_e32 v45, 16, v45
	v_mul_f32_e32 v40, v197, v40
	v_mul_f32_e32 v41, v197, v41
	v_fmac_f32_e32 v40, v76, v42
	v_fmac_f32_e32 v41, v76, v44
	v_fmac_f32_e32 v40, v77, v43
	v_fmac_f32_e32 v41, v77, v45
	v_add_f32_e32 v40, v200, v40
	v_add_f32_e32 v41, v200, v41
	ds_write_b64 v8, v[40:41] offset:24576
	s_waitcnt vmcnt(12)
	v_lshlrev_b32_e32 v46, 16, v46
	v_lshlrev_b32_e32 v47, 16, v47
	v_lshlrev_b32_e32 v48, 16, v48
	v_lshlrev_b32_e32 v49, 16, v49
	v_lshlrev_b32_e32 v50, 16, v50
	v_lshlrev_b32_e32 v51, 16, v51
	v_mul_f32_e32 v46, v197, v46
	v_mul_f32_e32 v47, v197, v47
	v_fmac_f32_e32 v46, v76, v48
	v_fmac_f32_e32 v47, v76, v50
	v_fmac_f32_e32 v46, v77, v49
	v_fmac_f32_e32 v47, v77, v51
	v_add_f32_e32 v46, v200, v46
	v_add_f32_e32 v47, v200, v47
	ds_write_b64 v8, v[46:47] offset:26624
	s_waitcnt vmcnt(6)
	v_lshlrev_b32_e32 v52, 16, v52
	v_lshlrev_b32_e32 v53, 16, v53
	v_lshlrev_b32_e32 v54, 16, v54
	v_lshlrev_b32_e32 v55, 16, v55
	v_lshlrev_b32_e32 v56, 16, v56
	v_lshlrev_b32_e32 v57, 16, v57
	v_mul_f32_e32 v52, v197, v52
	v_mul_f32_e32 v53, v197, v53
	v_fmac_f32_e32 v52, v76, v54
	v_fmac_f32_e32 v53, v76, v56
	v_fmac_f32_e32 v52, v77, v55
	v_fmac_f32_e32 v53, v77, v57
	v_add_f32_e32 v52, v200, v52
	v_add_f32_e32 v53, v200, v53
	ds_write_b64 v8, v[52:53] offset:28672
	s_waitcnt vmcnt(0)
	v_cndmask_b32_e64 v61, v61, 0, s[10:11]
	v_cndmask_b32_e64 v63, v63, 0, s[10:11]
	v_lshlrev_b32_e32 v58, 16, v58
	v_lshlrev_b32_e32 v59, 16, v59
	v_lshlrev_b32_e32 v60, 16, v60
	v_lshlrev_b32_e32 v61, 16, v61
	v_lshlrev_b32_e32 v62, 16, v62
	v_lshlrev_b32_e32 v63, 16, v63
	v_mul_f32_e32 v58, v197, v58
	v_mul_f32_e32 v59, v197, v59
	v_fmac_f32_e32 v58, v76, v60
	v_fmac_f32_e32 v59, v76, v62
	v_fmac_f32_e32 v58, v77, v61
	v_fmac_f32_e32 v59, v77, v63
	v_add_f32_e32 v58, v200, v58
	v_add_f32_e32 v59, v200, v59
	ds_write_b64 v8, v[58:59] offset:30720
	s_branch .Lhy_inA_done

; DI int tidx() { int t = __builtin_amdgcn_workitem_id_x(); asm volatile("" : "+v"(t)); return t; }
; DI f32x2 cmul(f32x2 a, f32x2 b) { return mkf2(a.x * b.x - a.y * b.y, a.x * b.y + a.y * b.x); }
; DI void fft8192(f32x2* buf, const f32x2* __restrict__ tw) {
;   const int tid = tidx();
; #pragma unroll 2
;   for (int ls = 0; ls < 12; ls += 2) {
;     const int s = 1 << ls;
;     f32x2 a[8], b[8], c[8], d[8];
;     __syncthreads();
; #pragma unroll
;     for (int e = 0; e < 8; ++e) {
;       const int i = tid + 256 * e;
;       const int pi = SW(i);
;       a[e] = buf[pi]; b[e] = buf[pi + 2048]; c[e] = buf[pi + 4096]; d[e] = buf[pi + 6144];
;     }
;     __syncthreads();
; #pragma unroll
;     for (int e = 0; e < 8; ++e) {
;       const int i = tid + 256 * e;
;       const int q = i & (s - 1);
;       const int ps = i - q;
;       const float rev = (float)ps * (1.f / 8192.f);
;       const f32x2 w1 = mkf2(__builtin_amdgcn_cosf(rev), -__builtin_amdgcn_sinf(rev));
;       const f32x2 w2 = cmul(w1, w1), w3 = cmul(w1, w2);
;       const f32x2 apc = mkf2(a[e].x + c[e].x, a[e].y + c[e].y), amc = mkf2(a[e].x - c[e].x, a[e].y - c[e].y);
;       const f32x2 bpd = mkf2(b[e].x + d[e].x, b[e].y + d[e].y), bmd = mkf2(b[e].x - d[e].x, b[e].y - d[e].y);
;       const int o = 4 * i - 3 * q;
;       buf[SW(o)] = mkf2(apc.x + bpd.x, apc.y + bpd.y);
;       buf[SW(o + s)] = cmul(w1, mkf2(amc.x + bmd.y, amc.y - bmd.x));
;       buf[SW(o + 2 * s)] = cmul(w2, mkf2(apc.x - bpd.x, apc.y - bpd.y));
;       buf[SW(o + 3 * s)] = cmul(w3, mkf2(amc.x - bmd.y, amc.y + bmd.x));
;     }
.Lhy_inA_done:
.LBB0_987:
	v_bfe_i32 v166, v0, 5, 1
	v_bfe_i32 v168, v0, 6, 1
	v_and_b32_e32 v166, 5, v166
	v_and_b32_e32 v168, 26, v168
	v_xor_b32_e32 v166, v166, v168
	v_xor_b32_e32 v166, v166, v0
	v_lshlrev_b32_e32 v154, 3, v166
	s_waitcnt lgkmcnt(0)
	s_barrier
	ds_read2st64_b64 v[2:5], v154 offset0:0 offset1:32
	ds_read2st64_b64 v[10:13], v154 offset0:4 offset1:36
	ds_read2st64_b64 v[18:21], v154 offset0:8 offset1:40
	ds_read2st64_b64 v[26:29], v154 offset0:12 offset1:44
	ds_read2st64_b64 v[34:37], v154 offset0:16 offset1:48
	ds_read2st64_b64 v[42:45], v154 offset0:20 offset1:52
	ds_read2st64_b64 v[50:53], v154 offset0:24 offset1:56
	ds_read2st64_b64 v[58:61], v154 offset0:28 offset1:60
	v_cvt_f32_u32_e32 v201, v0
	v_lshlrev_b32_e32 v164, 4, v0
	v_bfe_i32 v166, v164, 5, 1
	v_bfe_i32 v168, v164, 6, 1
	v_and_b32_e32 v166, 5, v166
	v_and_b32_e32 v168, 26, v168
	v_xor_b32_e32 v166, v166, v168
	v_xor_b32_e32 v166, v166, v164
	v_lshlrev_b32_e32 v164, 3, v166
	v_mul_f32_e32 v201, 0x39000000, v201
	v_cos_f32_e32 v210, v201
	v_sin_f32_e64 v211, -v201
	s_waitcnt lgkmcnt(7)
	v_pk_add_f32 v[6:7], v[2:3], v[4:5]
	v_pk_add_f32 v[8:9], v[2:3], v[4:5] neg_lo:[0,1] neg_hi:[0,1]
	v_pk_add_f32 v[202:203], v[2:3], v[4:5] op_sel:[0,1] op_sel_hi:[1,0] neg_hi:[0,1]
	v_pk_add_f32 v[204:205], v[2:3], v[4:5] op_sel:[0,1] op_sel_hi:[1,0] neg_lo:[0,1]
	v_pk_mul_f32 v[206:207], v[210:211], v[210:211] op_sel:[1,1] op_sel_hi:[1,0]
	v_pk_fma_f32 v[212:213], v[210:211], v[210:211], v[206:207] op_sel_hi:[0,1,1] neg_lo:[0,0,1]
	v_pk_mul_f32 v[206:207], v[210:211], v[212:213] op_sel:[1,1] op_sel_hi:[1,0]
	v_pk_fma_f32 v[220:221], v[210:211], v[212:213], v[206:207] op_sel_hi:[0,1,1] neg_lo:[0,0,1]
	v_pk_mul_f32 v[2:3], v[210:211], v[202:203] op_sel:[1,1] op_sel_hi:[1,0]
	v_pk_fma_f32 v[2:3], v[210:211], v[202:203], v[2:3] op_sel_hi:[0,1,1] neg_lo:[0,0,1]
	v_pk_mul_f32 v[4:5], v[212:213], v[8:9] op_sel:[1,1] op_sel_hi:[1,0]
	v_pk_fma_f32 v[4:5], v[212:213], v[8:9], v[4:5] op_sel_hi:[0,1,1] neg_lo:[0,0,1]
	v_pk_mul_f32 v[8:9], v[220:221], v[204:205] op_sel:[1,1] op_sel_hi:[1,0]
	v_pk_fma_f32 v[8:9], v[220:221], v[204:205], v[8:9] op_sel_hi:[0,1,1] neg_lo:[0,0,1]
	v_add_f32_e32 v214, 0x3d000000, v201
	v_cos_f32_e32 v210, v214
	v_sin_f32_e64 v211, -v214
	s_waitcnt lgkmcnt(6)
	v_pk_add_f32 v[14:15], v[10:11], v[12:13]
	v_pk_add_f32 v[16:17], v[10:11], v[12:13] neg_lo:[0,1] neg_hi:[0,1]
	v_pk_add_f32 v[202:203], v[10:11], v[12:13] op_sel:[0,1] op_sel_hi:[1,0] neg_hi:[0,1]
	v_pk_add_f32 v[204:205], v[10:11], v[12:13] op_sel:[0,1] op_sel_hi:[1,0] neg_lo:[0,1]
	v_pk_mul_f32 v[206:207], v[210:211], v[210:211] op_sel:[1,1] op_sel_hi:[1,0]
	v_pk_fma_f32 v[212:213], v[210:211], v[210:211], v[206:207] op_sel_hi:[0,1,1] neg_lo:[0,0,1]
	v_pk_mul_f32 v[206:207], v[210:211], v[212:213] op_sel:[1,1] op_sel_hi:[1,0]
	v_pk_fma_f32 v[220:221], v[210:211], v[212:213], v[206:207] op_sel_hi:[0,1,1] neg_lo:[0,0,1]
	v_pk_mul_f32 v[10:11], v[210:211], v[202:203] op_sel:[1,1] op_sel_hi:[1,0]
	v_pk_fma_f32 v[10:11], v[210:211], v[202:203], v[10:11] op_sel_hi:[0,1,1] neg_lo:[0,0,1]
	v_pk_mul_f32 v[12:13], v[212:213], v[16:17] op_sel:[1,1] op_sel_hi:[1,0]
	v_pk_fma_f32 v[12:13], v[212:213], v[16:17], v[12:13] op_sel_hi:[0,1,1] neg_lo:[0,0,1]
	v_pk_mul_f32 v[16:17], v[220:221], v[204:205] op_sel:[1,1] op_sel_hi:[1,0]
	v_pk_fma_f32 v[16:17], v[220:221], v[204:205], v[16:17] op_sel_hi:[0,1,1] neg_lo:[0,0,1]
	v_add_f32_e32 v214, 0x3d800000, v201
	v_cos_f32_e32 v210, v214
	v_sin_f32_e64 v211, -v214
	s_waitcnt lgkmcnt(5)
	v_pk_add_f32 v[22:23], v[18:19], v[20:21]
	v_pk_add_f32 v[24:25], v[18:19], v[20:21] neg_lo:[0,1] neg_hi:[0,1]
	v_pk_add_f32 v[202:203], v[18:19], v[20:21] op_sel:[0,1] op_sel_hi:[1,0] neg_hi:[0,1]
	v_pk_add_f32 v[204:205], v[18:19], v[20:21] op_sel:[0,1] op_sel_hi:[1,0] neg_lo:[0,1]
	v_pk_mul_f32 v[206:207], v[210:211], v[210:211] op_sel:[1,1] op_sel_hi:[1,0]
	v_pk_fma_f32 v[212:213], v[210:211], v[210:211], v[206:207] op_sel_hi:[0,1,1] neg_lo:[0,0,1]
	v_pk_mul_f32 v[206:207], v[210:211], v[212:213] op_sel:[1,1] op_sel_hi:[1,0]
	v_pk_fma_f32 v[220:221], v[210:211], v[212:213], v[206:207] op_sel_hi:[0,1,1] neg_lo:[0,0,1]
	v_pk_mul_f32 v[18:19], v[210:211], v[202:203] op_sel:[1,1] op_sel_hi:[1,0]
	v_pk_fma_f32 v[18:19], v[210:211], v[202:203], v[18:19] op_sel_hi:[0,1,1] neg_lo:[0,0,1]
	v_pk_mul_f32 v[20:21], v[212:213], v[24:25] op_sel:[1,1] op_sel_hi:[1,0]
	v_pk_fma_f32 v[20:21], v[212:213], v[24:25], v[20:21] op_sel_hi:[0,1,1] neg_lo:[0,0,1]
	v_pk_mul_f32 v[24:25], v[220:221], v[204:205] op_sel:[1,1] op_sel_hi:[1,0]
	v_pk_fma_f32 v[24:25], v[220:221], v[204:205], v[24:25] op_sel_hi:[0,1,1] neg_lo:[0,0,1]
	v_add_f32_e32 v214, 0x3dc00000, v201
	v_cos_f32_e32 v210, v214
	v_sin_f32_e64 v211, -v214
	s_waitcnt lgkmcnt(4)
	v_pk_add_f32 v[30:31], v[26:27], v[28:29]
	v_pk_add_f32 v[32:33], v[26:27], v[28:29] neg_lo:[0,1] neg_hi:[0,1]
	v_pk_add_f32 v[202:203], v[26:27], v[28:29] op_sel:[0,1] op_sel_hi:[1,0] neg_hi:[0,1]
	v_pk_add_f32 v[204:205], v[26:27], v[28:29] op_sel:[0,1] op_sel_hi:[1,0] neg_lo:[0,1]
	v_pk_mul_f32 v[206:207], v[210:211], v[210:211] op_sel:[1,1] op_sel_hi:[1,0]
	v_pk_fma_f32 v[212:213], v[210:211], v[210:211], v[206:207] op_sel_hi:[0,1,1] neg_lo:[0,0,1]
	v_pk_mul_f32 v[206:207], v[210:211], v[212:213] op_sel:[1,1] op_sel_hi:[1,0]
	v_pk_fma_f32 v[220:221], v[210:211], v[212:213], v[206:207] op_sel_hi:[0,1,1] neg_lo:[0,0,1]
	v_pk_mul_f32 v[26:27], v[210:211], v[202:203] op_sel:[1,1] op_sel_hi:[1,0]
	v_pk_fma_f32 v[26:27], v[210:211], v[202:203], v[26:27] op_sel_hi:[0,1,1] neg_lo:[0,0,1]
	v_pk_mul_f32 v[28:29], v[212:213], v[32:33] op_sel:[1,1] op_sel_hi:[1,0]
	v_pk_fma_f32 v[28:29], v[212:213], v[32:33], v[28:29] op_sel_hi:[0,1,1] neg_lo:[0,0,1]
	v_pk_mul_f32 v[32:33], v[220:221], v[204:205] op_sel:[1,1] op_sel_hi:[1,0]
	v_pk_fma_f32 v[32:33], v[220:221], v[204:205], v[32:33] op_sel_hi:[0,1,1] neg_lo:[0,0,1]
	v_add_f32_e32 v214, 0x3e000000, v201
	v_cos_f32_e32 v210, v214
	v_sin_f32_e64 v211, -v214
	s_waitcnt lgkmcnt(3)
; DI f32x2 cmul(f32x2 a, f32x2 b) { return mkf2(a.x * b.x - a.y * b.y, a.x * b.y + a.y * b.x); }
; DI void fft8192(f32x2* buf, const f32x2* __restrict__ tw) {
;     ...
; #pragma unroll
;     for (int e = 0; e < 8; ++e) {
;       const int i = tid + 256 * e;
;       const int pi = SW(i);
;       a[e] = buf[pi]; b[e] = buf[pi + 2048]; c[e] = buf[pi + 4096]; d[e] = buf[pi + 6144];
;     }
;     __syncthreads();
; #pragma unroll
;     for (int e = 0; e < 8; ++e) {
;       const int i = tid + 256 * e;
;       const int q = i & (s - 1);
;       const int ps = i - q;
;       const float rev = (float)ps * (1.f / 8192.f);
;       const f32x2 w1 = mkf2(__builtin_amdgcn_cosf(rev), -__builtin_amdgcn_sinf(rev));
;       const f32x2 w2 = cmul(w1, w1), w3 = cmul(w1, w2);
;       const f32x2 apc = mkf2(a[e].x + c[e].x, a[e].y + c[e].y), amc = mkf2(a[e].x - c[e].x, a[e].y - c[e].y);
;       const f32x2 bpd = mkf2(b[e].x + d[e].x, b[e].y + d[e].y), bmd = mkf2(b[e].x - d[e].x, b[e].y - d[e].y);
;       const int o = 4 * i - 3 * q;
;       buf[SW(o)] = mkf2(apc.x + bpd.x, apc.y + bpd.y);
;       buf[SW(o + s)] = cmul(w1, mkf2(amc.x + bmd.y, amc.y - bmd.x));
;       buf[SW(o + 2 * s)] = cmul(w2, mkf2(apc.x - bpd.x, apc.y - bpd.y));
;       buf[SW(o + 3 * s)] = cmul(w3, mkf2(amc.x - bmd.y, amc.y + bmd.x));
;     }
	v_pk_add_f32 v[38:39], v[34:35], v[36:37]
	v_pk_add_f32 v[40:41], v[34:35], v[36:37] neg_lo:[0,1] neg_hi:[0,1]
	v_pk_add_f32 v[202:203], v[34:35], v[36:37] op_sel:[0,1] op_sel_hi:[1,0] neg_hi:[0,1]
	v_pk_add_f32 v[204:205], v[34:35], v[36:37] op_sel:[0,1] op_sel_hi:[1,0] neg_lo:[0,1]
	v_pk_mul_f32 v[206:207], v[210:211], v[210:211] op_sel:[1,1] op_sel_hi:[1,0]
	v_pk_fma_f32 v[212:213], v[210:211], v[210:211], v[206:207] op_sel_hi:[0,1,1] neg_lo:[0,0,1]
	v_pk_mul_f32 v[206:207], v[210:211], v[212:213] op_sel:[1,1] op_sel_hi:[1,0]
	v_pk_fma_f32 v[220:221], v[210:211], v[212:213], v[206:207] op_sel_hi:[0,1,1] neg_lo:[0,0,1]
	v_pk_mul_f32 v[34:35], v[210:211], v[202:203] op_sel:[1,1] op_sel_hi:[1,0]
	v_pk_fma_f32 v[34:35], v[210:211], v[202:203], v[34:35] op_sel_hi:[0,1,1] neg_lo:[0,0,1]
	v_pk_mul_f32 v[36:37], v[212:213], v[40:41] op_sel:[1,1] op_sel_hi:[1,0]
	v_pk_fma_f32 v[36:37], v[212:213], v[40:41], v[36:37] op_sel_hi:[0,1,1] neg_lo:[0,0,1]
	v_pk_mul_f32 v[40:41], v[220:221], v[204:205] op_sel:[1,1] op_sel_hi:[1,0]
	v_pk_fma_f32 v[40:41], v[220:221], v[204:205], v[40:41] op_sel_hi:[0,1,1] neg_lo:[0,0,1]
	v_add_f32_e32 v214, 0x3e200000, v201
	v_cos_f32_e32 v210, v214
	v_sin_f32_e64 v211, -v214
	s_waitcnt lgkmcnt(2)
	v_pk_add_f32 v[46:47], v[42:43], v[44:45]
	v_pk_add_f32 v[48:49], v[42:43], v[44:45] neg_lo:[0,1] neg_hi:[0,1]
	v_pk_add_f32 v[202:203], v[42:43], v[44:45] op_sel:[0,1] op_sel_hi:[1,0] neg_hi:[0,1]
	v_pk_add_f32 v[204:205], v[42:43], v[44:45] op_sel:[0,1] op_sel_hi:[1,0] neg_lo:[0,1]
	v_pk_mul_f32 v[206:207], v[210:211], v[210:211] op_sel:[1,1] op_sel_hi:[1,0]
	v_pk_fma_f32 v[212:213], v[210:211], v[210:211], v[206:207] op_sel_hi:[0,1,1] neg_lo:[0,0,1]
	v_pk_mul_f32 v[206:207], v[210:211], v[212:213] op_sel:[1,1] op_sel_hi:[1,0]
	v_pk_fma_f32 v[220:221], v[210:211], v[212:213], v[206:207] op_sel_hi:[0,1,1] neg_lo:[0,0,1]
	v_pk_mul_f32 v[42:43], v[210:211], v[202:203] op_sel:[1,1] op_sel_hi:[1,0]
	v_pk_fma_f32 v[42:43], v[210:211], v[202:203], v[42:43] op_sel_hi:[0,1,1] neg_lo:[0,0,1]
	v_pk_mul_f32 v[44:45], v[212:213], v[48:49] op_sel:[1,1] op_sel_hi:[1,0]
	v_pk_fma_f32 v[44:45], v[212:213], v[48:49], v[44:45] op_sel_hi:[0,1,1] neg_lo:[0,0,1]
	v_pk_mul_f32 v[48:49], v[220:221], v[204:205] op_sel:[1,1] op_sel_hi:[1,0]
	v_pk_fma_f32 v[48:49], v[220:221], v[204:205], v[48:49] op_sel_hi:[0,1,1] neg_lo:[0,0,1]
	v_add_f32_e32 v214, 0x3e400000, v201
	v_cos_f32_e32 v210, v214
	v_sin_f32_e64 v211, -v214
	s_waitcnt lgkmcnt(1)
	v_pk_add_f32 v[54:55], v[50:51], v[52:53]
	v_pk_add_f32 v[56:57], v[50:51], v[52:53] neg_lo:[0,1] neg_hi:[0,1]
	v_pk_add_f32 v[202:203], v[50:51], v[52:53] op_sel:[0,1] op_sel_hi:[1,0] neg_hi:[0,1]
	v_pk_add_f32 v[204:205], v[50:51], v[52:53] op_sel:[0,1] op_sel_hi:[1,0] neg_lo:[0,1]
	v_pk_mul_f32 v[206:207], v[210:211], v[210:211] op_sel:[1,1] op_sel_hi:[1,0]
	v_pk_fma_f32 v[212:213], v[210:211], v[210:211], v[206:207] op_sel_hi:[0,1,1] neg_lo:[0,0,1]
	v_pk_mul_f32 v[206:207], v[210:211], v[212:213] op_sel:[1,1] op_sel_hi:[1,0]
	v_pk_fma_f32 v[220:221], v[210:211], v[212:213], v[206:207] op_sel_hi:[0,1,1] neg_lo:[0,0,1]
	v_pk_mul_f32 v[50:51], v[210:211], v[202:203] op_sel:[1,1] op_sel_hi:[1,0]
	v_pk_fma_f32 v[50:51], v[210:211], v[202:203], v[50:51] op_sel_hi:[0,1,1] neg_lo:[0,0,1]
	v_pk_mul_f32 v[52:53], v[212:213], v[56:57] op_sel:[1,1] op_sel_hi:[1,0]
	v_pk_fma_f32 v[52:53], v[212:213], v[56:57], v[52:53] op_sel_hi:[0,1,1] neg_lo:[0,0,1]
	v_pk_mul_f32 v[56:57], v[220:221], v[204:205] op_sel:[1,1] op_sel_hi:[1,0]
	v_pk_fma_f32 v[56:57], v[220:221], v[204:205], v[56:57] op_sel_hi:[0,1,1] neg_lo:[0,0,1]
	v_add_f32_e32 v214, 0x3e600000, v201
	v_cos_f32_e32 v210, v214
	v_sin_f32_e64 v211, -v214
	s_waitcnt lgkmcnt(0)
	v_pk_add_f32 v[62:63], v[58:59], v[60:61]
	v_pk_add_f32 v[64:65], v[58:59], v[60:61] neg_lo:[0,1] neg_hi:[0,1]
	v_pk_add_f32 v[202:203], v[58:59], v[60:61] op_sel:[0,1] op_sel_hi:[1,0] neg_hi:[0,1]
	v_pk_add_f32 v[204:205], v[58:59], v[60:61] op_sel:[0,1] op_sel_hi:[1,0] neg_lo:[0,1]
	v_pk_mul_f32 v[206:207], v[210:211], v[210:211] op_sel:[1,1] op_sel_hi:[1,0]
	v_pk_fma_f32 v[212:213], v[210:211], v[210:211], v[206:207] op_sel_hi:[0,1,1] neg_lo:[0,0,1]
	v_pk_mul_f32 v[206:207], v[210:211], v[212:213] op_sel:[1,1] op_sel_hi:[1,0]
	v_pk_fma_f32 v[220:221], v[210:211], v[212:213], v[206:207] op_sel_hi:[0,1,1] neg_lo:[0,0,1]
	v_pk_mul_f32 v[58:59], v[210:211], v[202:203] op_sel:[1,1] op_sel_hi:[1,0]
	v_pk_fma_f32 v[58:59], v[210:211], v[202:203], v[58:59] op_sel_hi:[0,1,1] neg_lo:[0,0,1]
	v_pk_mul_f32 v[60:61], v[212:213], v[64:65] op_sel:[1,1] op_sel_hi:[1,0]
	v_pk_fma_f32 v[60:61], v[212:213], v[64:65], v[60:61] op_sel_hi:[0,1,1] neg_lo:[0,0,1]
	v_pk_mul_f32 v[64:65], v[220:221], v[204:205] op_sel:[1,1] op_sel_hi:[1,0]
	v_pk_fma_f32 v[64:65], v[220:221], v[204:205], v[64:65] op_sel_hi:[0,1,1] neg_lo:[0,0,1]
	s_barrier
; DI f32x2 cmul(f32x2 a, f32x2 b) { return mkf2(a.x * b.x - a.y * b.y, a.x * b.y + a.y * b.x); }
; DI void fft8192(f32x2* buf, const f32x2* __restrict__ tw) {
;     ...
; #pragma unroll
;     for (int e = 0; e < 8; ++e) {
;       const int i = tid + 256 * e;
;       const int pi = SW(i);
;       a[e] = buf[pi]; b[e] = buf[pi + 2048]; c[e] = buf[pi + 4096]; d[e] = buf[pi + 6144];
;     }
;     __syncthreads();
; #pragma unroll
;     for (int e = 0; e < 8; ++e) {
;       const int i = tid + 256 * e;
;       const int q = i & (s - 1);
;       const int ps = i - q;
;       const float rev = (float)ps * (1.f / 8192.f);
;       const f32x2 w1 = mkf2(__builtin_amdgcn_cosf(rev), -__builtin_amdgcn_sinf(rev));
;       const f32x2 w2 = cmul(w1, w1), w3 = cmul(w1, w2);
;       const f32x2 apc = mkf2(a[e].x + c[e].x, a[e].y + c[e].y), amc = mkf2(a[e].x - c[e].x, a[e].y - c[e].y);
;       const f32x2 bpd = mkf2(b[e].x + d[e].x, b[e].y + d[e].y), bmd = mkf2(b[e].x - d[e].x, b[e].y - d[e].y);
;       const int o = 4 * i - 3 * q;
;       buf[SW(o)] = mkf2(apc.x + bpd.x, apc.y + bpd.y);
;       buf[SW(o + s)] = cmul(w1, mkf2(amc.x + bmd.y, amc.y - bmd.x));
;       buf[SW(o + 2 * s)] = cmul(w2, mkf2(apc.x - bpd.x, apc.y - bpd.y));
;       buf[SW(o + 3 * s)] = cmul(w3, mkf2(amc.x - bmd.y, amc.y + bmd.x));
;     }
	v_mul_f32_e32 v214, 4.0, v201
	v_cos_f32_e32 v224, v214
	v_sin_f32_e64 v225, -v214
	s_nop 0
	v_pk_mul_f32 v[206:207], v[224:225], v[224:225] op_sel:[1,1] op_sel_hi:[1,0]
	v_pk_fma_f32 v[226:227], v[224:225], v[224:225], v[206:207] op_sel_hi:[0,1,1] neg_lo:[0,0,1]
	v_pk_mul_f32 v[206:207], v[224:225], v[226:227] op_sel:[1,1] op_sel_hi:[1,0]
	v_pk_fma_f32 v[230:231], v[224:225], v[226:227], v[206:207] op_sel_hi:[0,1,1] neg_lo:[0,0,1]
	v_pk_add_f32 v[202:203], v[6:7], v[38:39]
	v_pk_add_f32 v[6:7], v[6:7], v[38:39] neg_lo:[0,1] neg_hi:[0,1]
	v_pk_add_f32 v[204:205], v[22:23], v[54:55]
	v_pk_add_f32 v[22:23], v[22:23], v[54:55] neg_lo:[0,1] neg_hi:[0,1]
	v_pk_add_f32 v[38:39], v[202:203], v[204:205]
	v_pk_add_f32 v[54:55], v[202:203], v[204:205] neg_lo:[0,1] neg_hi:[0,1]
	v_pk_add_f32 v[202:203], v[6:7], v[22:23] op_sel:[0,1] op_sel_hi:[1,0] neg_hi:[0,1]
	v_pk_add_f32 v[204:205], v[6:7], v[22:23] op_sel:[0,1] op_sel_hi:[1,0] neg_lo:[0,1]
	v_pk_mul_f32 v[6:7], v[224:225], v[202:203] op_sel:[1,1] op_sel_hi:[1,0]
	v_pk_fma_f32 v[6:7], v[224:225], v[202:203], v[6:7] op_sel_hi:[0,1,1] neg_lo:[0,0,1]
	v_pk_mul_f32 v[22:23], v[226:227], v[54:55] op_sel:[1,1] op_sel_hi:[1,0]
	v_pk_fma_f32 v[22:23], v[226:227], v[54:55], v[22:23] op_sel_hi:[0,1,1] neg_lo:[0,0,1]
	v_pk_mul_f32 v[54:55], v[230:231], v[204:205] op_sel:[1,1] op_sel_hi:[1,0]
	v_pk_fma_f32 v[54:55], v[230:231], v[204:205], v[54:55] op_sel_hi:[0,1,1] neg_lo:[0,0,1]
	v_pk_add_f32 v[202:203], v[2:3], v[34:35]
	v_pk_add_f32 v[2:3], v[2:3], v[34:35] neg_lo:[0,1] neg_hi:[0,1]
	v_pk_add_f32 v[204:205], v[18:19], v[50:51]
	v_pk_add_f32 v[18:19], v[18:19], v[50:51] neg_lo:[0,1] neg_hi:[0,1]
	v_pk_add_f32 v[34:35], v[202:203], v[204:205]
	v_pk_add_f32 v[50:51], v[202:203], v[204:205] neg_lo:[0,1] neg_hi:[0,1]
	v_pk_add_f32 v[202:203], v[2:3], v[18:19] op_sel:[0,1] op_sel_hi:[1,0] neg_hi:[0,1]
	v_pk_add_f32 v[204:205], v[2:3], v[18:19] op_sel:[0,1] op_sel_hi:[1,0] neg_lo:[0,1]
	v_pk_mul_f32 v[2:3], v[224:225], v[202:203] op_sel:[1,1] op_sel_hi:[1,0]
	v_pk_fma_f32 v[2:3], v[224:225], v[202:203], v[2:3] op_sel_hi:[0,1,1] neg_lo:[0,0,1]
	v_pk_mul_f32 v[18:19], v[226:227], v[50:51] op_sel:[1,1] op_sel_hi:[1,0]
	v_pk_fma_f32 v[18:19], v[226:227], v[50:51], v[18:19] op_sel_hi:[0,1,1] neg_lo:[0,0,1]
	v_pk_mul_f32 v[50:51], v[230:231], v[204:205] op_sel:[1,1] op_sel_hi:[1,0]
	v_pk_fma_f32 v[50:51], v[230:231], v[204:205], v[50:51] op_sel_hi:[0,1,1] neg_lo:[0,0,1]
	v_pk_add_f32 v[202:203], v[4:5], v[36:37]
	v_pk_add_f32 v[4:5], v[4:5], v[36:37] neg_lo:[0,1] neg_hi:[0,1]
	v_pk_add_f32 v[204:205], v[20:21], v[52:53]
	v_pk_add_f32 v[20:21], v[20:21], v[52:53] neg_lo:[0,1] neg_hi:[0,1]
	v_pk_add_f32 v[36:37], v[202:203], v[204:205]
	v_pk_add_f32 v[52:53], v[202:203], v[204:205] neg_lo:[0,1] neg_hi:[0,1]
	v_pk_add_f32 v[202:203], v[4:5], v[20:21] op_sel:[0,1] op_sel_hi:[1,0] neg_hi:[0,1]
	v_pk_add_f32 v[204:205], v[4:5], v[20:21] op_sel:[0,1] op_sel_hi:[1,0] neg_lo:[0,1]
	v_pk_mul_f32 v[4:5], v[224:225], v[202:203] op_sel:[1,1] op_sel_hi:[1,0]
	v_pk_fma_f32 v[4:5], v[224:225], v[202:203], v[4:5] op_sel_hi:[0,1,1] neg_lo:[0,0,1]
	v_pk_mul_f32 v[20:21], v[226:227], v[52:53] op_sel:[1,1] op_sel_hi:[1,0]
	v_pk_fma_f32 v[20:21], v[226:227], v[52:53], v[20:21] op_sel_hi:[0,1,1] neg_lo:[0,0,1]
	v_pk_mul_f32 v[52:53], v[230:231], v[204:205] op_sel:[1,1] op_sel_hi:[1,0]
	v_pk_fma_f32 v[52:53], v[230:231], v[204:205], v[52:53] op_sel_hi:[0,1,1] neg_lo:[0,0,1]
	v_pk_add_f32 v[202:203], v[8:9], v[40:41]
	v_pk_add_f32 v[8:9], v[8:9], v[40:41] neg_lo:[0,1] neg_hi:[0,1]
	v_pk_add_f32 v[204:205], v[24:25], v[56:57]
	v_pk_add_f32 v[24:25], v[24:25], v[56:57] neg_lo:[0,1] neg_hi:[0,1]
	v_pk_add_f32 v[40:41], v[202:203], v[204:205]
	v_pk_add_f32 v[56:57], v[202:203], v[204:205] neg_lo:[0,1] neg_hi:[0,1]
	v_pk_add_f32 v[202:203], v[8:9], v[24:25] op_sel:[0,1] op_sel_hi:[1,0] neg_hi:[0,1]
	v_pk_add_f32 v[204:205], v[8:9], v[24:25] op_sel:[0,1] op_sel_hi:[1,0] neg_lo:[0,1]
	v_pk_mul_f32 v[8:9], v[224:225], v[202:203] op_sel:[1,1] op_sel_hi:[1,0]
	v_pk_fma_f32 v[8:9], v[224:225], v[202:203], v[8:9] op_sel_hi:[0,1,1] neg_lo:[0,0,1]
	v_pk_mul_f32 v[24:25], v[226:227], v[56:57] op_sel:[1,1] op_sel_hi:[1,0]
	v_pk_fma_f32 v[24:25], v[226:227], v[56:57], v[24:25] op_sel_hi:[0,1,1] neg_lo:[0,0,1]
	v_pk_mul_f32 v[56:57], v[230:231], v[204:205] op_sel:[1,1] op_sel_hi:[1,0]
	v_pk_fma_f32 v[56:57], v[230:231], v[204:205], v[56:57] op_sel_hi:[0,1,1] neg_lo:[0,0,1]
	v_mul_f32_e32 v214, 4.0, v201
	v_add_f32_e32 v214, 0x3e000000, v214
	v_cos_f32_e32 v224, v214
	v_sin_f32_e64 v225, -v214
	s_nop 0
	v_pk_mul_f32 v[206:207], v[224:225], v[224:225] op_sel:[1,1] op_sel_hi:[1,0]
	v_pk_fma_f32 v[226:227], v[224:225], v[224:225], v[206:207] op_sel_hi:[0,1,1] neg_lo:[0,0,1]
	v_pk_mul_f32 v[206:207], v[224:225], v[226:227] op_sel:[1,1] op_sel_hi:[1,0]
	v_pk_fma_f32 v[230:231], v[224:225], v[226:227], v[206:207] op_sel_hi:[0,1,1] neg_lo:[0,0,1]
	v_pk_add_f32 v[202:203], v[14:15], v[46:47]
	v_pk_add_f32 v[14:15], v[14:15], v[46:47] neg_lo:[0,1] neg_hi:[0,1]
	v_pk_add_f32 v[204:205], v[30:31], v[62:63]
	v_pk_add_f32 v[30:31], v[30:31], v[62:63] neg_lo:[0,1] neg_hi:[0,1]
	v_pk_add_f32 v[46:47], v[202:203], v[204:205]
	v_pk_add_f32 v[62:63], v[202:203], v[204:205] neg_lo:[0,1] neg_hi:[0,1]
	v_pk_add_f32 v[202:203], v[14:15], v[30:31] op_sel:[0,1] op_sel_hi:[1,0] neg_hi:[0,1]
	v_pk_add_f32 v[204:205], v[14:15], v[30:31] op_sel:[0,1] op_sel_hi:[1,0] neg_lo:[0,1]
	v_pk_mul_f32 v[14:15], v[224:225], v[202:203] op_sel:[1,1] op_sel_hi:[1,0]
	v_pk_fma_f32 v[14:15], v[224:225], v[202:203], v[14:15] op_sel_hi:[0,1,1] neg_lo:[0,0,1]
	v_pk_mul_f32 v[30:31], v[226:227], v[62:63] op_sel:[1,1] op_sel_hi:[1,0]
; DI f32x2 cmul(f32x2 a, f32x2 b) { return mkf2(a.x * b.x - a.y * b.y, a.x * b.y + a.y * b.x); }
; DI void fft8192(f32x2* buf, const f32x2* __restrict__ tw) {
;     ...
; #pragma unroll
;     for (int e = 0; e < 8; ++e) {
;       const int i = tid + 256 * e;
;       const int pi = SW(i);
;       a[e] = buf[pi]; b[e] = buf[pi + 2048]; c[e] = buf[pi + 4096]; d[e] = buf[pi + 6144];
;     }
;     __syncthreads();
; #pragma unroll
;     for (int e = 0; e < 8; ++e) {
;       const int i = tid + 256 * e;
;       const int q = i & (s - 1);
;       const int ps = i - q;
;       const float rev = (float)ps * (1.f / 8192.f);
;       const f32x2 w1 = mkf2(__builtin_amdgcn_cosf(rev), -__builtin_amdgcn_sinf(rev));
;       const f32x2 w2 = cmul(w1, w1), w3 = cmul(w1, w2);
;       const f32x2 apc = mkf2(a[e].x + c[e].x, a[e].y + c[e].y), amc = mkf2(a[e].x - c[e].x, a[e].y - c[e].y);
;       const f32x2 bpd = mkf2(b[e].x + d[e].x, b[e].y + d[e].y), bmd = mkf2(b[e].x - d[e].x, b[e].y - d[e].y);
;       const int o = 4 * i - 3 * q;
;       buf[SW(o)] = mkf2(apc.x + bpd.x, apc.y + bpd.y);
;       buf[SW(o + s)] = cmul(w1, mkf2(amc.x + bmd.y, amc.y - bmd.x));
;       buf[SW(o + 2 * s)] = cmul(w2, mkf2(apc.x - bpd.x, apc.y - bpd.y));
;       buf[SW(o + 3 * s)] = cmul(w3, mkf2(amc.x - bmd.y, amc.y + bmd.x));
;     }
	v_pk_fma_f32 v[30:31], v[226:227], v[62:63], v[30:31] op_sel_hi:[0,1,1] neg_lo:[0,0,1]
	v_pk_mul_f32 v[62:63], v[230:231], v[204:205] op_sel:[1,1] op_sel_hi:[1,0]
	v_pk_fma_f32 v[62:63], v[230:231], v[204:205], v[62:63] op_sel_hi:[0,1,1] neg_lo:[0,0,1]
	v_pk_add_f32 v[202:203], v[10:11], v[42:43]
	v_pk_add_f32 v[10:11], v[10:11], v[42:43] neg_lo:[0,1] neg_hi:[0,1]
	v_pk_add_f32 v[204:205], v[26:27], v[58:59]
	v_pk_add_f32 v[26:27], v[26:27], v[58:59] neg_lo:[0,1] neg_hi:[0,1]
	v_pk_add_f32 v[42:43], v[202:203], v[204:205]
	v_pk_add_f32 v[58:59], v[202:203], v[204:205] neg_lo:[0,1] neg_hi:[0,1]
	v_pk_add_f32 v[202:203], v[10:11], v[26:27] op_sel:[0,1] op_sel_hi:[1,0] neg_hi:[0,1]
	v_pk_add_f32 v[204:205], v[10:11], v[26:27] op_sel:[0,1] op_sel_hi:[1,0] neg_lo:[0,1]
	v_pk_mul_f32 v[10:11], v[224:225], v[202:203] op_sel:[1,1] op_sel_hi:[1,0]
	v_pk_fma_f32 v[10:11], v[224:225], v[202:203], v[10:11] op_sel_hi:[0,1,1] neg_lo:[0,0,1]
	v_pk_mul_f32 v[26:27], v[226:227], v[58:59] op_sel:[1,1] op_sel_hi:[1,0]
	v_pk_fma_f32 v[26:27], v[226:227], v[58:59], v[26:27] op_sel_hi:[0,1,1] neg_lo:[0,0,1]
	v_pk_mul_f32 v[58:59], v[230:231], v[204:205] op_sel:[1,1] op_sel_hi:[1,0]
	v_pk_fma_f32 v[58:59], v[230:231], v[204:205], v[58:59] op_sel_hi:[0,1,1] neg_lo:[0,0,1]
	v_pk_add_f32 v[202:203], v[12:13], v[44:45]
	v_pk_add_f32 v[12:13], v[12:13], v[44:45] neg_lo:[0,1] neg_hi:[0,1]
	v_pk_add_f32 v[204:205], v[28:29], v[60:61]
	v_pk_add_f32 v[28:29], v[28:29], v[60:61] neg_lo:[0,1] neg_hi:[0,1]
	v_pk_add_f32 v[44:45], v[202:203], v[204:205]
	v_pk_add_f32 v[60:61], v[202:203], v[204:205] neg_lo:[0,1] neg_hi:[0,1]
	v_pk_add_f32 v[202:203], v[12:13], v[28:29] op_sel:[0,1] op_sel_hi:[1,0] neg_hi:[0,1]
	v_pk_add_f32 v[204:205], v[12:13], v[28:29] op_sel:[0,1] op_sel_hi:[1,0] neg_lo:[0,1]
	v_pk_mul_f32 v[12:13], v[224:225], v[202:203] op_sel:[1,1] op_sel_hi:[1,0]
	v_pk_fma_f32 v[12:13], v[224:225], v[202:203], v[12:13] op_sel_hi:[0,1,1] neg_lo:[0,0,1]
	v_pk_mul_f32 v[28:29], v[226:227], v[60:61] op_sel:[1,1] op_sel_hi:[1,0]
	v_pk_fma_f32 v[28:29], v[226:227], v[60:61], v[28:29] op_sel_hi:[0,1,1] neg_lo:[0,0,1]
	v_pk_mul_f32 v[60:61], v[230:231], v[204:205] op_sel:[1,1] op_sel_hi:[1,0]
	v_pk_fma_f32 v[60:61], v[230:231], v[204:205], v[60:61] op_sel_hi:[0,1,1] neg_lo:[0,0,1]
	v_pk_add_f32 v[202:203], v[16:17], v[48:49]
	v_pk_add_f32 v[16:17], v[16:17], v[48:49] neg_lo:[0,1] neg_hi:[0,1]
	v_pk_add_f32 v[204:205], v[32:33], v[64:65]
	v_pk_add_f32 v[32:33], v[32:33], v[64:65] neg_lo:[0,1] neg_hi:[0,1]
	v_pk_add_f32 v[48:49], v[202:203], v[204:205]
	v_pk_add_f32 v[64:65], v[202:203], v[204:205] neg_lo:[0,1] neg_hi:[0,1]
	v_pk_add_f32 v[202:203], v[16:17], v[32:33] op_sel:[0,1] op_sel_hi:[1,0] neg_hi:[0,1]
	v_pk_add_f32 v[204:205], v[16:17], v[32:33] op_sel:[0,1] op_sel_hi:[1,0] neg_lo:[0,1]
	v_pk_mul_f32 v[16:17], v[224:225], v[202:203] op_sel:[1,1] op_sel_hi:[1,0]
	v_pk_fma_f32 v[16:17], v[224:225], v[202:203], v[16:17] op_sel_hi:[0,1,1] neg_lo:[0,0,1]
	v_pk_mul_f32 v[32:33], v[226:227], v[64:65] op_sel:[1,1] op_sel_hi:[1,0]
	v_pk_fma_f32 v[32:33], v[226:227], v[64:65], v[32:33] op_sel_hi:[0,1,1] neg_lo:[0,0,1]
	v_pk_mul_f32 v[64:65], v[230:231], v[204:205] op_sel:[1,1] op_sel_hi:[1,0]
	v_pk_fma_f32 v[64:65], v[230:231], v[204:205], v[64:65] op_sel_hi:[0,1,1] neg_lo:[0,0,1]
	ds_write_b64 v164, v[38:39] offset:0
	v_xor_b32_e32 v156, 8, v164
	ds_write_b64 v156, v[34:35] offset:0
	v_xor_b32_e32 v158, 16, v164
	ds_write_b64 v158, v[36:37] offset:0
	v_xor_b32_e32 v160, 24, v164
	ds_write_b64 v160, v[40:41] offset:0
	v_xor_b32_e32 v162, 32, v164
	ds_write_b64 v162, v[6:7] offset:0
	v_xor_b32_e32 v156, 40, v164
	ds_write_b64 v156, v[2:3] offset:0
	v_xor_b32_e32 v158, 48, v164
	ds_write_b64 v158, v[4:5] offset:0
	v_xor_b32_e32 v160, 56, v164
	ds_write_b64 v160, v[8:9] offset:0
	v_xor_b32_e32 v162, 64, v164
	ds_write_b64 v162, v[22:23] offset:0
	v_xor_b32_e32 v156, 0x48, v164
	ds_write_b64 v156, v[18:19] offset:0
	v_xor_b32_e32 v158, 0x50, v164
	ds_write_b64 v158, v[20:21] offset:0
	v_xor_b32_e32 v160, 0x58, v164
	ds_write_b64 v160, v[24:25] offset:0
	v_xor_b32_e32 v162, 0x60, v164
	ds_write_b64 v162, v[54:55] offset:0
	v_xor_b32_e32 v156, 0x68, v164
	ds_write_b64 v156, v[50:51] offset:0
	v_xor_b32_e32 v158, 0x70, v164
	ds_write_b64 v158, v[52:53] offset:0
	v_xor_b32_e32 v160, 0x78, v164
	ds_write_b64 v160, v[56:57] offset:0
	ds_write_b64 v164, v[46:47] offset:32768
	v_xor_b32_e32 v162, 8, v164
	ds_write_b64 v162, v[42:43] offset:32768
	v_xor_b32_e32 v156, 16, v164
	ds_write_b64 v156, v[44:45] offset:32768
	v_xor_b32_e32 v158, 24, v164
	ds_write_b64 v158, v[48:49] offset:32768
	v_xor_b32_e32 v160, 32, v164
	ds_write_b64 v160, v[14:15] offset:32768
	v_xor_b32_e32 v162, 40, v164
	ds_write_b64 v162, v[10:11] offset:32768
	v_xor_b32_e32 v156, 48, v164
	ds_write_b64 v156, v[12:13] offset:32768
	v_xor_b32_e32 v158, 56, v164
	ds_write_b64 v158, v[16:17] offset:32768
	v_xor_b32_e32 v160, 64, v164
	ds_write_b64 v160, v[30:31] offset:32768
	v_xor_b32_e32 v162, 0x48, v164
	ds_write_b64 v162, v[26:27] offset:32768
	v_xor_b32_e32 v156, 0x50, v164
	ds_write_b64 v156, v[28:29] offset:32768
	v_xor_b32_e32 v158, 0x58, v164
	ds_write_b64 v158, v[32:33] offset:32768
	v_xor_b32_e32 v160, 0x60, v164
	ds_write_b64 v160, v[62:63] offset:32768
	v_xor_b32_e32 v162, 0x68, v164
	ds_write_b64 v162, v[58:59] offset:32768
	v_xor_b32_e32 v156, 0x70, v164
	ds_write_b64 v156, v[60:61] offset:32768
	v_xor_b32_e32 v158, 0x78, v164
	ds_write_b64 v158, v[64:65] offset:32768
	s_waitcnt lgkmcnt(0)
	s_barrier
; DI f32x2 cmul(f32x2 a, f32x2 b) { return mkf2(a.x * b.x - a.y * b.y, a.x * b.y + a.y * b.x); }
; DI void fft8192(f32x2* buf, const f32x2* __restrict__ tw) {
;     ...
; #pragma unroll
;     for (int e = 0; e < 8; ++e) {
;       const int i = tid + 256 * e;
;       const int pi = SW(i);
;       a[e] = buf[pi]; b[e] = buf[pi + 2048]; c[e] = buf[pi + 4096]; d[e] = buf[pi + 6144];
;     }
;     __syncthreads();
; #pragma unroll
;     for (int e = 0; e < 8; ++e) {
;       const int i = tid + 256 * e;
;       const int q = i & (s - 1);
;       const int ps = i - q;
;       const float rev = (float)ps * (1.f / 8192.f);
;       const f32x2 w1 = mkf2(__builtin_amdgcn_cosf(rev), -__builtin_amdgcn_sinf(rev));
;       const f32x2 w2 = cmul(w1, w1), w3 = cmul(w1, w2);
;       const f32x2 apc = mkf2(a[e].x + c[e].x, a[e].y + c[e].y), amc = mkf2(a[e].x - c[e].x, a[e].y - c[e].y);
;       const f32x2 bpd = mkf2(b[e].x + d[e].x, b[e].y + d[e].y), bmd = mkf2(b[e].x - d[e].x, b[e].y - d[e].y);
;       const int o = 4 * i - 3 * q;
;       buf[SW(o)] = mkf2(apc.x + bpd.x, apc.y + bpd.y);
;       buf[SW(o + s)] = cmul(w1, mkf2(amc.x + bmd.y, amc.y - bmd.x));
;       buf[SW(o + 2 * s)] = cmul(w2, mkf2(apc.x - bpd.x, apc.y - bpd.y));
;       buf[SW(o + 3 * s)] = cmul(w3, mkf2(amc.x - bmd.y, amc.y + bmd.x));
	ds_read2st64_b64 v[2:5], v154 offset0:0 offset1:32
	ds_read2st64_b64 v[6:9], v154 offset0:64 offset1:96
	ds_read2st64_b64 v[10:13], v154 offset0:4 offset1:36
	ds_read2st64_b64 v[14:17], v154 offset0:68 offset1:100
	ds_read2st64_b64 v[18:21], v154 offset0:8 offset1:40
	ds_read2st64_b64 v[22:25], v154 offset0:72 offset1:104
	ds_read2st64_b64 v[26:29], v154 offset0:12 offset1:44
	ds_read2st64_b64 v[30:33], v154 offset0:76 offset1:108
	ds_read2st64_b64 v[34:37], v154 offset0:16 offset1:48
	ds_read2st64_b64 v[38:41], v154 offset0:80 offset1:112
	ds_read2st64_b64 v[42:45], v154 offset0:20 offset1:52
	ds_read2st64_b64 v[46:49], v154 offset0:84 offset1:116
	ds_read2st64_b64 v[50:53], v154 offset0:24 offset1:56
	ds_read2st64_b64 v[54:57], v154 offset0:88 offset1:120
	ds_read2st64_b64 v[58:61], v154 offset0:28 offset1:60
	ds_read2st64_b64 v[62:65], v154 offset0:92 offset1:124
	v_and_b32_e32 v166, 15, v0
	v_sub_u32_e32 v168, v0, v166
	v_cvt_f32_u32_e32 v201, v168
	v_lshl_add_u32 v164, v168, 4, v166
	v_lshlrev_b32_e32 v164, 3, v164
	v_mul_f32_e32 v201, 0x39000000, v201
	v_cos_f32_e32 v210, v201
	v_sin_f32_e64 v211, -v201
	s_waitcnt lgkmcnt(14)
	v_pk_add_f32 v[202:203], v[2:3], v[6:7]
	v_pk_add_f32 v[2:3], v[2:3], v[6:7] neg_lo:[0,1] neg_hi:[0,1]
	v_pk_add_f32 v[204:205], v[4:5], v[8:9]
	v_pk_add_f32 v[4:5], v[4:5], v[8:9] neg_lo:[0,1] neg_hi:[0,1]
	v_pk_add_f32 v[6:7], v[202:203], v[204:205]
	v_pk_add_f32 v[8:9], v[202:203], v[204:205] neg_lo:[0,1] neg_hi:[0,1]
	v_pk_add_f32 v[202:203], v[2:3], v[4:5] op_sel:[0,1] op_sel_hi:[1,0] neg_hi:[0,1]
	v_pk_add_f32 v[204:205], v[2:3], v[4:5] op_sel:[0,1] op_sel_hi:[1,0] neg_lo:[0,1]
	v_pk_mul_f32 v[206:207], v[210:211], v[210:211] op_sel:[1,1] op_sel_hi:[1,0]
	v_pk_fma_f32 v[212:213], v[210:211], v[210:211], v[206:207] op_sel_hi:[0,1,1] neg_lo:[0,0,1]
	v_pk_mul_f32 v[206:207], v[210:211], v[212:213] op_sel:[1,1] op_sel_hi:[1,0]
	v_pk_fma_f32 v[220:221], v[210:211], v[212:213], v[206:207] op_sel_hi:[0,1,1] neg_lo:[0,0,1]
	v_pk_mul_f32 v[2:3], v[210:211], v[202:203] op_sel:[1,1] op_sel_hi:[1,0]
	v_pk_fma_f32 v[2:3], v[210:211], v[202:203], v[2:3] op_sel_hi:[0,1,1] neg_lo:[0,0,1]
	v_pk_mul_f32 v[4:5], v[212:213], v[8:9] op_sel:[1,1] op_sel_hi:[1,0]
	v_pk_fma_f32 v[4:5], v[212:213], v[8:9], v[4:5] op_sel_hi:[0,1,1] neg_lo:[0,0,1]
	v_pk_mul_f32 v[8:9], v[220:221], v[204:205] op_sel:[1,1] op_sel_hi:[1,0]
	v_pk_fma_f32 v[8:9], v[220:221], v[204:205], v[8:9] op_sel_hi:[0,1,1] neg_lo:[0,0,1]
	v_add_f32_e32 v214, 0x3d000000, v201
	v_cos_f32_e32 v210, v214
	v_sin_f32_e64 v211, -v214
	s_waitcnt lgkmcnt(12)
	v_pk_add_f32 v[202:203], v[10:11], v[14:15]
	v_pk_add_f32 v[10:11], v[10:11], v[14:15] neg_lo:[0,1] neg_hi:[0,1]
	v_pk_add_f32 v[204:205], v[12:13], v[16:17]
	v_pk_add_f32 v[12:13], v[12:13], v[16:17] neg_lo:[0,1] neg_hi:[0,1]
	v_pk_add_f32 v[14:15], v[202:203], v[204:205]
	v_pk_add_f32 v[16:17], v[202:203], v[204:205] neg_lo:[0,1] neg_hi:[0,1]
	v_pk_add_f32 v[202:203], v[10:11], v[12:13] op_sel:[0,1] op_sel_hi:[1,0] neg_hi:[0,1]
	v_pk_add_f32 v[204:205], v[10:11], v[12:13] op_sel:[0,1] op_sel_hi:[1,0] neg_lo:[0,1]
	v_pk_mul_f32 v[206:207], v[210:211], v[210:211] op_sel:[1,1] op_sel_hi:[1,0]
	v_pk_fma_f32 v[212:213], v[210:211], v[210:211], v[206:207] op_sel_hi:[0,1,1] neg_lo:[0,0,1]
	v_pk_mul_f32 v[206:207], v[210:211], v[212:213] op_sel:[1,1] op_sel_hi:[1,0]
	v_pk_fma_f32 v[220:221], v[210:211], v[212:213], v[206:207] op_sel_hi:[0,1,1] neg_lo:[0,0,1]
	v_pk_mul_f32 v[10:11], v[210:211], v[202:203] op_sel:[1,1] op_sel_hi:[1,0]
	v_pk_fma_f32 v[10:11], v[210:211], v[202:203], v[10:11] op_sel_hi:[0,1,1] neg_lo:[0,0,1]
	v_pk_mul_f32 v[12:13], v[212:213], v[16:17] op_sel:[1,1] op_sel_hi:[1,0]
	v_pk_fma_f32 v[12:13], v[212:213], v[16:17], v[12:13] op_sel_hi:[0,1,1] neg_lo:[0,0,1]
	v_pk_mul_f32 v[16:17], v[220:221], v[204:205] op_sel:[1,1] op_sel_hi:[1,0]
	v_pk_fma_f32 v[16:17], v[220:221], v[204:205], v[16:17] op_sel_hi:[0,1,1] neg_lo:[0,0,1]
	v_add_f32_e32 v214, 0x3d800000, v201
	v_cos_f32_e32 v210, v214
	v_sin_f32_e64 v211, -v214
	s_waitcnt lgkmcnt(10)
	v_pk_add_f32 v[202:203], v[18:19], v[22:23]
	v_pk_add_f32 v[18:19], v[18:19], v[22:23] neg_lo:[0,1] neg_hi:[0,1]
	v_pk_add_f32 v[204:205], v[20:21], v[24:25]
	v_pk_add_f32 v[20:21], v[20:21], v[24:25] neg_lo:[0,1] neg_hi:[0,1]
	v_pk_add_f32 v[22:23], v[202:203], v[204:205]
	v_pk_add_f32 v[24:25], v[202:203], v[204:205] neg_lo:[0,1] neg_hi:[0,1]
	v_pk_add_f32 v[202:203], v[18:19], v[20:21] op_sel:[0,1] op_sel_hi:[1,0] neg_hi:[0,1]
	v_pk_add_f32 v[204:205], v[18:19], v[20:21] op_sel:[0,1] op_sel_hi:[1,0] neg_lo:[0,1]
	v_pk_mul_f32 v[206:207], v[210:211], v[210:211] op_sel:[1,1] op_sel_hi:[1,0]
	v_pk_fma_f32 v[212:213], v[210:211], v[210:211], v[206:207] op_sel_hi:[0,1,1] neg_lo:[0,0,1]
	v_pk_mul_f32 v[206:207], v[210:211], v[212:213] op_sel:[1,1] op_sel_hi:[1,0]
	v_pk_fma_f32 v[220:221], v[210:211], v[212:213], v[206:207] op_sel_hi:[0,1,1] neg_lo:[0,0,1]
	v_pk_mul_f32 v[18:19], v[210:211], v[202:203] op_sel:[1,1] op_sel_hi:[1,0]
	v_pk_fma_f32 v[18:19], v[210:211], v[202:203], v[18:19] op_sel_hi:[0,1,1] neg_lo:[0,0,1]
	v_pk_mul_f32 v[20:21], v[212:213], v[24:25] op_sel:[1,1] op_sel_hi:[1,0]
	v_pk_fma_f32 v[20:21], v[212:213], v[24:25], v[20:21] op_sel_hi:[0,1,1] neg_lo:[0,0,1]
	v_pk_mul_f32 v[24:25], v[220:221], v[204:205] op_sel:[1,1] op_sel_hi:[1,0]
	v_pk_fma_f32 v[24:25], v[220:221], v[204:205], v[24:25] op_sel_hi:[0,1,1] neg_lo:[0,0,1]
	v_add_f32_e32 v214, 0x3dc00000, v201
	v_cos_f32_e32 v210, v214
	v_sin_f32_e64 v211, -v214
	s_waitcnt lgkmcnt(8)
; DI f32x2 cmul(f32x2 a, f32x2 b) { return mkf2(a.x * b.x - a.y * b.y, a.x * b.y + a.y * b.x); }
; DI void fft8192(f32x2* buf, const f32x2* __restrict__ tw) {
;     ...
; #pragma unroll
;     for (int e = 0; e < 8; ++e) {
;       const int i = tid + 256 * e;
;       const int pi = SW(i);
;       a[e] = buf[pi]; b[e] = buf[pi + 2048]; c[e] = buf[pi + 4096]; d[e] = buf[pi + 6144];
;     }
;     __syncthreads();
; #pragma unroll
;     for (int e = 0; e < 8; ++e) {
;       const int i = tid + 256 * e;
;       const int q = i & (s - 1);
;       const int ps = i - q;
;       const float rev = (float)ps * (1.f / 8192.f);
;       const f32x2 w1 = mkf2(__builtin_amdgcn_cosf(rev), -__builtin_amdgcn_sinf(rev));
;       const f32x2 w2 = cmul(w1, w1), w3 = cmul(w1, w2);
;       const f32x2 apc = mkf2(a[e].x + c[e].x, a[e].y + c[e].y), amc = mkf2(a[e].x - c[e].x, a[e].y - c[e].y);
;       const f32x2 bpd = mkf2(b[e].x + d[e].x, b[e].y + d[e].y), bmd = mkf2(b[e].x - d[e].x, b[e].y - d[e].y);
;       const int o = 4 * i - 3 * q;
;       buf[SW(o)] = mkf2(apc.x + bpd.x, apc.y + bpd.y);
;       buf[SW(o + s)] = cmul(w1, mkf2(amc.x + bmd.y, amc.y - bmd.x));
;       buf[SW(o + 2 * s)] = cmul(w2, mkf2(apc.x - bpd.x, apc.y - bpd.y));
;       buf[SW(o + 3 * s)] = cmul(w3, mkf2(amc.x - bmd.y, amc.y + bmd.x));
	v_pk_add_f32 v[202:203], v[26:27], v[30:31]
	v_pk_add_f32 v[26:27], v[26:27], v[30:31] neg_lo:[0,1] neg_hi:[0,1]
	v_pk_add_f32 v[204:205], v[28:29], v[32:33]
	v_pk_add_f32 v[28:29], v[28:29], v[32:33] neg_lo:[0,1] neg_hi:[0,1]
	v_pk_add_f32 v[30:31], v[202:203], v[204:205]
	v_pk_add_f32 v[32:33], v[202:203], v[204:205] neg_lo:[0,1] neg_hi:[0,1]
	v_pk_add_f32 v[202:203], v[26:27], v[28:29] op_sel:[0,1] op_sel_hi:[1,0] neg_hi:[0,1]
	v_pk_add_f32 v[204:205], v[26:27], v[28:29] op_sel:[0,1] op_sel_hi:[1,0] neg_lo:[0,1]
	v_pk_mul_f32 v[206:207], v[210:211], v[210:211] op_sel:[1,1] op_sel_hi:[1,0]
	v_pk_fma_f32 v[212:213], v[210:211], v[210:211], v[206:207] op_sel_hi:[0,1,1] neg_lo:[0,0,1]
	v_pk_mul_f32 v[206:207], v[210:211], v[212:213] op_sel:[1,1] op_sel_hi:[1,0]
	v_pk_fma_f32 v[220:221], v[210:211], v[212:213], v[206:207] op_sel_hi:[0,1,1] neg_lo:[0,0,1]
	v_pk_mul_f32 v[26:27], v[210:211], v[202:203] op_sel:[1,1] op_sel_hi:[1,0]
	v_pk_fma_f32 v[26:27], v[210:211], v[202:203], v[26:27] op_sel_hi:[0,1,1] neg_lo:[0,0,1]
	v_pk_mul_f32 v[28:29], v[212:213], v[32:33] op_sel:[1,1] op_sel_hi:[1,0]
	v_pk_fma_f32 v[28:29], v[212:213], v[32:33], v[28:29] op_sel_hi:[0,1,1] neg_lo:[0,0,1]
	v_pk_mul_f32 v[32:33], v[220:221], v[204:205] op_sel:[1,1] op_sel_hi:[1,0]
	v_pk_fma_f32 v[32:33], v[220:221], v[204:205], v[32:33] op_sel_hi:[0,1,1] neg_lo:[0,0,1]
	v_add_f32_e32 v214, 0x3e000000, v201
	v_cos_f32_e32 v210, v214
	v_sin_f32_e64 v211, -v214
	s_waitcnt lgkmcnt(6)
	v_pk_add_f32 v[202:203], v[34:35], v[38:39]
	v_pk_add_f32 v[34:35], v[34:35], v[38:39] neg_lo:[0,1] neg_hi:[0,1]
	v_pk_add_f32 v[204:205], v[36:37], v[40:41]
	v_pk_add_f32 v[36:37], v[36:37], v[40:41] neg_lo:[0,1] neg_hi:[0,1]
	v_pk_add_f32 v[38:39], v[202:203], v[204:205]
	v_pk_add_f32 v[40:41], v[202:203], v[204:205] neg_lo:[0,1] neg_hi:[0,1]
	v_pk_add_f32 v[202:203], v[34:35], v[36:37] op_sel:[0,1] op_sel_hi:[1,0] neg_hi:[0,1]
	v_pk_add_f32 v[204:205], v[34:35], v[36:37] op_sel:[0,1] op_sel_hi:[1,0] neg_lo:[0,1]
	v_pk_mul_f32 v[206:207], v[210:211], v[210:211] op_sel:[1,1] op_sel_hi:[1,0]
	v_pk_fma_f32 v[212:213], v[210:211], v[210:211], v[206:207] op_sel_hi:[0,1,1] neg_lo:[0,0,1]
	v_pk_mul_f32 v[206:207], v[210:211], v[212:213] op_sel:[1,1] op_sel_hi:[1,0]
	v_pk_fma_f32 v[220:221], v[210:211], v[212:213], v[206:207] op_sel_hi:[0,1,1] neg_lo:[0,0,1]
	v_pk_mul_f32 v[34:35], v[210:211], v[202:203] op_sel:[1,1] op_sel_hi:[1,0]
	v_pk_fma_f32 v[34:35], v[210:211], v[202:203], v[34:35] op_sel_hi:[0,1,1] neg_lo:[0,0,1]
	v_pk_mul_f32 v[36:37], v[212:213], v[40:41] op_sel:[1,1] op_sel_hi:[1,0]
	v_pk_fma_f32 v[36:37], v[212:213], v[40:41], v[36:37] op_sel_hi:[0,1,1] neg_lo:[0,0,1]
	v_pk_mul_f32 v[40:41], v[220:221], v[204:205] op_sel:[1,1] op_sel_hi:[1,0]
	v_pk_fma_f32 v[40:41], v[220:221], v[204:205], v[40:41] op_sel_hi:[0,1,1] neg_lo:[0,0,1]
	v_add_f32_e32 v214, 0x3e200000, v201
	v_cos_f32_e32 v210, v214
	v_sin_f32_e64 v211, -v214
	s_waitcnt lgkmcnt(4)
	v_pk_add_f32 v[202:203], v[42:43], v[46:47]
	v_pk_add_f32 v[42:43], v[42:43], v[46:47] neg_lo:[0,1] neg_hi:[0,1]
	v_pk_add_f32 v[204:205], v[44:45], v[48:49]
	v_pk_add_f32 v[44:45], v[44:45], v[48:49] neg_lo:[0,1] neg_hi:[0,1]
	v_pk_add_f32 v[46:47], v[202:203], v[204:205]
	v_pk_add_f32 v[48:49], v[202:203], v[204:205] neg_lo:[0,1] neg_hi:[0,1]
	v_pk_add_f32 v[202:203], v[42:43], v[44:45] op_sel:[0,1] op_sel_hi:[1,0] neg_hi:[0,1]
	v_pk_add_f32 v[204:205], v[42:43], v[44:45] op_sel:[0,1] op_sel_hi:[1,0] neg_lo:[0,1]
	v_pk_mul_f32 v[206:207], v[210:211], v[210:211] op_sel:[1,1] op_sel_hi:[1,0]
	v_pk_fma_f32 v[212:213], v[210:211], v[210:211], v[206:207] op_sel_hi:[0,1,1] neg_lo:[0,0,1]
	v_pk_mul_f32 v[206:207], v[210:211], v[212:213] op_sel:[1,1] op_sel_hi:[1,0]
	v_pk_fma_f32 v[220:221], v[210:211], v[212:213], v[206:207] op_sel_hi:[0,1,1] neg_lo:[0,0,1]
	v_pk_mul_f32 v[42:43], v[210:211], v[202:203] op_sel:[1,1] op_sel_hi:[1,0]
	v_pk_fma_f32 v[42:43], v[210:211], v[202:203], v[42:43] op_sel_hi:[0,1,1] neg_lo:[0,0,1]
	v_pk_mul_f32 v[44:45], v[212:213], v[48:49] op_sel:[1,1] op_sel_hi:[1,0]
	v_pk_fma_f32 v[44:45], v[212:213], v[48:49], v[44:45] op_sel_hi:[0,1,1] neg_lo:[0,0,1]
	v_pk_mul_f32 v[48:49], v[220:221], v[204:205] op_sel:[1,1] op_sel_hi:[1,0]
	v_pk_fma_f32 v[48:49], v[220:221], v[204:205], v[48:49] op_sel_hi:[0,1,1] neg_lo:[0,0,1]
	v_add_f32_e32 v214, 0x3e400000, v201
	v_cos_f32_e32 v210, v214
	v_sin_f32_e64 v211, -v214
	s_waitcnt lgkmcnt(2)
	v_pk_add_f32 v[202:203], v[50:51], v[54:55]
	v_pk_add_f32 v[50:51], v[50:51], v[54:55] neg_lo:[0,1] neg_hi:[0,1]
	v_pk_add_f32 v[204:205], v[52:53], v[56:57]
	v_pk_add_f32 v[52:53], v[52:53], v[56:57] neg_lo:[0,1] neg_hi:[0,1]
	v_pk_add_f32 v[54:55], v[202:203], v[204:205]
	v_pk_add_f32 v[56:57], v[202:203], v[204:205] neg_lo:[0,1] neg_hi:[0,1]
	v_pk_add_f32 v[202:203], v[50:51], v[52:53] op_sel:[0,1] op_sel_hi:[1,0] neg_hi:[0,1]
	v_pk_add_f32 v[204:205], v[50:51], v[52:53] op_sel:[0,1] op_sel_hi:[1,0] neg_lo:[0,1]
	v_pk_mul_f32 v[206:207], v[210:211], v[210:211] op_sel:[1,1] op_sel_hi:[1,0]
	v_pk_fma_f32 v[212:213], v[210:211], v[210:211], v[206:207] op_sel_hi:[0,1,1] neg_lo:[0,0,1]
	v_pk_mul_f32 v[206:207], v[210:211], v[212:213] op_sel:[1,1] op_sel_hi:[1,0]
	v_pk_fma_f32 v[220:221], v[210:211], v[212:213], v[206:207] op_sel_hi:[0,1,1] neg_lo:[0,0,1]
	v_pk_mul_f32 v[50:51], v[210:211], v[202:203] op_sel:[1,1] op_sel_hi:[1,0]
	v_pk_fma_f32 v[50:51], v[210:211], v[202:203], v[50:51] op_sel_hi:[0,1,1] neg_lo:[0,0,1]
	v_pk_mul_f32 v[52:53], v[212:213], v[56:57] op_sel:[1,1] op_sel_hi:[1,0]
	v_pk_fma_f32 v[52:53], v[212:213], v[56:57], v[52:53] op_sel_hi:[0,1,1] neg_lo:[0,0,1]
	v_pk_mul_f32 v[56:57], v[220:221], v[204:205] op_sel:[1,1] op_sel_hi:[1,0]
	v_pk_fma_f32 v[56:57], v[220:221], v[204:205], v[56:57] op_sel_hi:[0,1,1] neg_lo:[0,0,1]
	v_add_f32_e32 v214, 0x3e600000, v201
	v_cos_f32_e32 v210, v214
	v_sin_f32_e64 v211, -v214
	s_waitcnt lgkmcnt(0)
; DI f32x2 cmul(f32x2 a, f32x2 b) { return mkf2(a.x * b.x - a.y * b.y, a.x * b.y + a.y * b.x); }
; DI void fft8192(f32x2* buf, const f32x2* __restrict__ tw) {
;     ...
; #pragma unroll
;     for (int e = 0; e < 8; ++e) {
;       const int i = tid + 256 * e;
;       const int pi = SW(i);
;       a[e] = buf[pi]; b[e] = buf[pi + 2048]; c[e] = buf[pi + 4096]; d[e] = buf[pi + 6144];
;     }
;     __syncthreads();
; #pragma unroll
;     for (int e = 0; e < 8; ++e) {
;       const int i = tid + 256 * e;
;       const int q = i & (s - 1);
;       const int ps = i - q;
;       const float rev = (float)ps * (1.f / 8192.f);
;       const f32x2 w1 = mkf2(__builtin_amdgcn_cosf(rev), -__builtin_amdgcn_sinf(rev));
;       const f32x2 w2 = cmul(w1, w1), w3 = cmul(w1, w2);
;       const f32x2 apc = mkf2(a[e].x + c[e].x, a[e].y + c[e].y), amc = mkf2(a[e].x - c[e].x, a[e].y - c[e].y);
;       const f32x2 bpd = mkf2(b[e].x + d[e].x, b[e].y + d[e].y), bmd = mkf2(b[e].x - d[e].x, b[e].y - d[e].y);
;       const int o = 4 * i - 3 * q;
;       buf[SW(o)] = mkf2(apc.x + bpd.x, apc.y + bpd.y);
;       buf[SW(o + s)] = cmul(w1, mkf2(amc.x + bmd.y, amc.y - bmd.x));
;       buf[SW(o + 2 * s)] = cmul(w2, mkf2(apc.x - bpd.x, apc.y - bpd.y));
;       buf[SW(o + 3 * s)] = cmul(w3, mkf2(amc.x - bmd.y, amc.y + bmd.x));
;     }
	v_pk_add_f32 v[202:203], v[58:59], v[62:63]
	v_pk_add_f32 v[58:59], v[58:59], v[62:63] neg_lo:[0,1] neg_hi:[0,1]
	v_pk_add_f32 v[204:205], v[60:61], v[64:65]
	v_pk_add_f32 v[60:61], v[60:61], v[64:65] neg_lo:[0,1] neg_hi:[0,1]
	v_pk_add_f32 v[62:63], v[202:203], v[204:205]
	v_pk_add_f32 v[64:65], v[202:203], v[204:205] neg_lo:[0,1] neg_hi:[0,1]
	v_pk_add_f32 v[202:203], v[58:59], v[60:61] op_sel:[0,1] op_sel_hi:[1,0] neg_hi:[0,1]
	v_pk_add_f32 v[204:205], v[58:59], v[60:61] op_sel:[0,1] op_sel_hi:[1,0] neg_lo:[0,1]
	v_pk_mul_f32 v[206:207], v[210:211], v[210:211] op_sel:[1,1] op_sel_hi:[1,0]
	v_pk_fma_f32 v[212:213], v[210:211], v[210:211], v[206:207] op_sel_hi:[0,1,1] neg_lo:[0,0,1]
	v_pk_mul_f32 v[206:207], v[210:211], v[212:213] op_sel:[1,1] op_sel_hi:[1,0]
	v_pk_fma_f32 v[220:221], v[210:211], v[212:213], v[206:207] op_sel_hi:[0,1,1] neg_lo:[0,0,1]
	v_pk_mul_f32 v[58:59], v[210:211], v[202:203] op_sel:[1,1] op_sel_hi:[1,0]
	v_pk_fma_f32 v[58:59], v[210:211], v[202:203], v[58:59] op_sel_hi:[0,1,1] neg_lo:[0,0,1]
	v_pk_mul_f32 v[60:61], v[212:213], v[64:65] op_sel:[1,1] op_sel_hi:[1,0]
	v_pk_fma_f32 v[60:61], v[212:213], v[64:65], v[60:61] op_sel_hi:[0,1,1] neg_lo:[0,0,1]
	v_pk_mul_f32 v[64:65], v[220:221], v[204:205] op_sel:[1,1] op_sel_hi:[1,0]
	v_pk_fma_f32 v[64:65], v[220:221], v[204:205], v[64:65] op_sel_hi:[0,1,1] neg_lo:[0,0,1]
	s_barrier
	v_mul_f32_e32 v214, 4.0, v201
	v_cos_f32_e32 v224, v214
	v_sin_f32_e64 v225, -v214
	s_nop 0
	v_pk_mul_f32 v[206:207], v[224:225], v[224:225] op_sel:[1,1] op_sel_hi:[1,0]
	v_pk_fma_f32 v[226:227], v[224:225], v[224:225], v[206:207] op_sel_hi:[0,1,1] neg_lo:[0,0,1]
	v_pk_mul_f32 v[206:207], v[224:225], v[226:227] op_sel:[1,1] op_sel_hi:[1,0]
	v_pk_fma_f32 v[230:231], v[224:225], v[226:227], v[206:207] op_sel_hi:[0,1,1] neg_lo:[0,0,1]
	v_pk_add_f32 v[202:203], v[6:7], v[38:39]
	v_pk_add_f32 v[6:7], v[6:7], v[38:39] neg_lo:[0,1] neg_hi:[0,1]
	v_pk_add_f32 v[204:205], v[22:23], v[54:55]
	v_pk_add_f32 v[22:23], v[22:23], v[54:55] neg_lo:[0,1] neg_hi:[0,1]
	v_pk_add_f32 v[38:39], v[202:203], v[204:205]
	v_pk_add_f32 v[54:55], v[202:203], v[204:205] neg_lo:[0,1] neg_hi:[0,1]
	v_pk_add_f32 v[202:203], v[6:7], v[22:23] op_sel:[0,1] op_sel_hi:[1,0] neg_hi:[0,1]
	v_pk_add_f32 v[204:205], v[6:7], v[22:23] op_sel:[0,1] op_sel_hi:[1,0] neg_lo:[0,1]
	v_pk_mul_f32 v[6:7], v[224:225], v[202:203] op_sel:[1,1] op_sel_hi:[1,0]
	v_pk_fma_f32 v[6:7], v[224:225], v[202:203], v[6:7] op_sel_hi:[0,1,1] neg_lo:[0,0,1]
	v_pk_mul_f32 v[22:23], v[226:227], v[54:55] op_sel:[1,1] op_sel_hi:[1,0]
	v_pk_fma_f32 v[22:23], v[226:227], v[54:55], v[22:23] op_sel_hi:[0,1,1] neg_lo:[0,0,1]
	v_pk_mul_f32 v[54:55], v[230:231], v[204:205] op_sel:[1,1] op_sel_hi:[1,0]
	v_pk_fma_f32 v[54:55], v[230:231], v[204:205], v[54:55] op_sel_hi:[0,1,1] neg_lo:[0,0,1]
	v_pk_add_f32 v[202:203], v[2:3], v[34:35]
	v_pk_add_f32 v[2:3], v[2:3], v[34:35] neg_lo:[0,1] neg_hi:[0,1]
	v_pk_add_f32 v[204:205], v[18:19], v[50:51]
	v_pk_add_f32 v[18:19], v[18:19], v[50:51] neg_lo:[0,1] neg_hi:[0,1]
	v_pk_add_f32 v[34:35], v[202:203], v[204:205]
	v_pk_add_f32 v[50:51], v[202:203], v[204:205] neg_lo:[0,1] neg_hi:[0,1]
	v_pk_add_f32 v[202:203], v[2:3], v[18:19] op_sel:[0,1] op_sel_hi:[1,0] neg_hi:[0,1]
	v_pk_add_f32 v[204:205], v[2:3], v[18:19] op_sel:[0,1] op_sel_hi:[1,0] neg_lo:[0,1]
	v_pk_mul_f32 v[2:3], v[224:225], v[202:203] op_sel:[1,1] op_sel_hi:[1,0]
	v_pk_fma_f32 v[2:3], v[224:225], v[202:203], v[2:3] op_sel_hi:[0,1,1] neg_lo:[0,0,1]
	v_pk_mul_f32 v[18:19], v[226:227], v[50:51] op_sel:[1,1] op_sel_hi:[1,0]
	v_pk_fma_f32 v[18:19], v[226:227], v[50:51], v[18:19] op_sel_hi:[0,1,1] neg_lo:[0,0,1]
	v_pk_mul_f32 v[50:51], v[230:231], v[204:205] op_sel:[1,1] op_sel_hi:[1,0]
	v_pk_fma_f32 v[50:51], v[230:231], v[204:205], v[50:51] op_sel_hi:[0,1,1] neg_lo:[0,0,1]
	v_pk_add_f32 v[202:203], v[4:5], v[36:37]
	v_pk_add_f32 v[4:5], v[4:5], v[36:37] neg_lo:[0,1] neg_hi:[0,1]
	v_pk_add_f32 v[204:205], v[20:21], v[52:53]
	v_pk_add_f32 v[20:21], v[20:21], v[52:53] neg_lo:[0,1] neg_hi:[0,1]
	v_pk_add_f32 v[36:37], v[202:203], v[204:205]
	v_pk_add_f32 v[52:53], v[202:203], v[204:205] neg_lo:[0,1] neg_hi:[0,1]
	v_pk_add_f32 v[202:203], v[4:5], v[20:21] op_sel:[0,1] op_sel_hi:[1,0] neg_hi:[0,1]
	v_pk_add_f32 v[204:205], v[4:5], v[20:21] op_sel:[0,1] op_sel_hi:[1,0] neg_lo:[0,1]
	v_pk_mul_f32 v[4:5], v[224:225], v[202:203] op_sel:[1,1] op_sel_hi:[1,0]
	v_pk_fma_f32 v[4:5], v[224:225], v[202:203], v[4:5] op_sel_hi:[0,1,1] neg_lo:[0,0,1]
	v_pk_mul_f32 v[20:21], v[226:227], v[52:53] op_sel:[1,1] op_sel_hi:[1,0]
	v_pk_fma_f32 v[20:21], v[226:227], v[52:53], v[20:21] op_sel_hi:[0,1,1] neg_lo:[0,0,1]
	v_pk_mul_f32 v[52:53], v[230:231], v[204:205] op_sel:[1,1] op_sel_hi:[1,0]
	v_pk_fma_f32 v[52:53], v[230:231], v[204:205], v[52:53] op_sel_hi:[0,1,1] neg_lo:[0,0,1]
	v_pk_add_f32 v[202:203], v[8:9], v[40:41]
	v_pk_add_f32 v[8:9], v[8:9], v[40:41] neg_lo:[0,1] neg_hi:[0,1]
	v_pk_add_f32 v[204:205], v[24:25], v[56:57]
	v_pk_add_f32 v[24:25], v[24:25], v[56:57] neg_lo:[0,1] neg_hi:[0,1]
	v_pk_add_f32 v[40:41], v[202:203], v[204:205]
	v_pk_add_f32 v[56:57], v[202:203], v[204:205] neg_lo:[0,1] neg_hi:[0,1]
	v_pk_add_f32 v[202:203], v[8:9], v[24:25] op_sel:[0,1] op_sel_hi:[1,0] neg_hi:[0,1]
	v_pk_add_f32 v[204:205], v[8:9], v[24:25] op_sel:[0,1] op_sel_hi:[1,0] neg_lo:[0,1]
	v_pk_mul_f32 v[8:9], v[224:225], v[202:203] op_sel:[1,1] op_sel_hi:[1,0]
	v_pk_fma_f32 v[8:9], v[224:225], v[202:203], v[8:9] op_sel_hi:[0,1,1] neg_lo:[0,0,1]
	v_pk_mul_f32 v[24:25], v[226:227], v[56:57] op_sel:[1,1] op_sel_hi:[1,0]
	v_pk_fma_f32 v[24:25], v[226:227], v[56:57], v[24:25] op_sel_hi:[0,1,1] neg_lo:[0,0,1]
; DI f32x2 cmul(f32x2 a, f32x2 b) { return mkf2(a.x * b.x - a.y * b.y, a.x * b.y + a.y * b.x); }
; DI void fft8192(f32x2* buf, const f32x2* __restrict__ tw) {
;     ...
; #pragma unroll
;     for (int e = 0; e < 8; ++e) {
;       const int i = tid + 256 * e;
;       const int q = i & (s - 1);
;       const int ps = i - q;
;       const float rev = (float)ps * (1.f / 8192.f);
;       const f32x2 w1 = mkf2(__builtin_amdgcn_cosf(rev), -__builtin_amdgcn_sinf(rev));
;       const f32x2 w2 = cmul(w1, w1), w3 = cmul(w1, w2);
;       const f32x2 apc = mkf2(a[e].x + c[e].x, a[e].y + c[e].y), amc = mkf2(a[e].x - c[e].x, a[e].y - c[e].y);
;       const f32x2 bpd = mkf2(b[e].x + d[e].x, b[e].y + d[e].y), bmd = mkf2(b[e].x - d[e].x, b[e].y - d[e].y);
;       const int o = 4 * i - 3 * q;
;       buf[SW(o)] = mkf2(apc.x + bpd.x, apc.y + bpd.y);
;       buf[SW(o + s)] = cmul(w1, mkf2(amc.x + bmd.y, amc.y - bmd.x));
;       buf[SW(o + 2 * s)] = cmul(w2, mkf2(apc.x - bpd.x, apc.y - bpd.y));
;       buf[SW(o + 3 * s)] = cmul(w3, mkf2(amc.x - bmd.y, amc.y + bmd.x));
;     }
	v_pk_mul_f32 v[56:57], v[230:231], v[204:205] op_sel:[1,1] op_sel_hi:[1,0]
	v_pk_fma_f32 v[56:57], v[230:231], v[204:205], v[56:57] op_sel_hi:[0,1,1] neg_lo:[0,0,1]
	v_mul_f32_e32 v214, 4.0, v201
	v_add_f32_e32 v214, 0x3e000000, v214
	v_cos_f32_e32 v224, v214
	v_sin_f32_e64 v225, -v214
	s_nop 0
	v_pk_mul_f32 v[206:207], v[224:225], v[224:225] op_sel:[1,1] op_sel_hi:[1,0]
	v_pk_fma_f32 v[226:227], v[224:225], v[224:225], v[206:207] op_sel_hi:[0,1,1] neg_lo:[0,0,1]
	v_pk_mul_f32 v[206:207], v[224:225], v[226:227] op_sel:[1,1] op_sel_hi:[1,0]
	v_pk_fma_f32 v[230:231], v[224:225], v[226:227], v[206:207] op_sel_hi:[0,1,1] neg_lo:[0,0,1]
	v_pk_add_f32 v[202:203], v[14:15], v[46:47]
	v_pk_add_f32 v[14:15], v[14:15], v[46:47] neg_lo:[0,1] neg_hi:[0,1]
	v_pk_add_f32 v[204:205], v[30:31], v[62:63]
	v_pk_add_f32 v[30:31], v[30:31], v[62:63] neg_lo:[0,1] neg_hi:[0,1]
	v_pk_add_f32 v[46:47], v[202:203], v[204:205]
	v_pk_add_f32 v[62:63], v[202:203], v[204:205] neg_lo:[0,1] neg_hi:[0,1]
	v_pk_add_f32 v[202:203], v[14:15], v[30:31] op_sel:[0,1] op_sel_hi:[1,0] neg_hi:[0,1]
	v_pk_add_f32 v[204:205], v[14:15], v[30:31] op_sel:[0,1] op_sel_hi:[1,0] neg_lo:[0,1]
	v_pk_mul_f32 v[14:15], v[224:225], v[202:203] op_sel:[1,1] op_sel_hi:[1,0]
	v_pk_fma_f32 v[14:15], v[224:225], v[202:203], v[14:15] op_sel_hi:[0,1,1] neg_lo:[0,0,1]
	v_pk_mul_f32 v[30:31], v[226:227], v[62:63] op_sel:[1,1] op_sel_hi:[1,0]
	v_pk_fma_f32 v[30:31], v[226:227], v[62:63], v[30:31] op_sel_hi:[0,1,1] neg_lo:[0,0,1]
	v_pk_mul_f32 v[62:63], v[230:231], v[204:205] op_sel:[1,1] op_sel_hi:[1,0]
	v_pk_fma_f32 v[62:63], v[230:231], v[204:205], v[62:63] op_sel_hi:[0,1,1] neg_lo:[0,0,1]
	v_pk_add_f32 v[202:203], v[10:11], v[42:43]
	v_pk_add_f32 v[10:11], v[10:11], v[42:43] neg_lo:[0,1] neg_hi:[0,1]
	v_pk_add_f32 v[204:205], v[26:27], v[58:59]
	v_pk_add_f32 v[26:27], v[26:27], v[58:59] neg_lo:[0,1] neg_hi:[0,1]
	v_pk_add_f32 v[42:43], v[202:203], v[204:205]
	v_pk_add_f32 v[58:59], v[202:203], v[204:205] neg_lo:[0,1] neg_hi:[0,1]
	v_pk_add_f32 v[202:203], v[10:11], v[26:27] op_sel:[0,1] op_sel_hi:[1,0] neg_hi:[0,1]
	v_pk_add_f32 v[204:205], v[10:11], v[26:27] op_sel:[0,1] op_sel_hi:[1,0] neg_lo:[0,1]
	v_pk_mul_f32 v[10:11], v[224:225], v[202:203] op_sel:[1,1] op_sel_hi:[1,0]
	v_pk_fma_f32 v[10:11], v[224:225], v[202:203], v[10:11] op_sel_hi:[0,1,1] neg_lo:[0,0,1]
	v_pk_mul_f32 v[26:27], v[226:227], v[58:59] op_sel:[1,1] op_sel_hi:[1,0]
	v_pk_fma_f32 v[26:27], v[226:227], v[58:59], v[26:27] op_sel_hi:[0,1,1] neg_lo:[0,0,1]
	v_pk_mul_f32 v[58:59], v[230:231], v[204:205] op_sel:[1,1] op_sel_hi:[1,0]
	v_pk_fma_f32 v[58:59], v[230:231], v[204:205], v[58:59] op_sel_hi:[0,1,1] neg_lo:[0,0,1]
	v_pk_add_f32 v[202:203], v[12:13], v[44:45]
	v_pk_add_f32 v[12:13], v[12:13], v[44:45] neg_lo:[0,1] neg_hi:[0,1]
	v_pk_add_f32 v[204:205], v[28:29], v[60:61]
	v_pk_add_f32 v[28:29], v[28:29], v[60:61] neg_lo:[0,1] neg_hi:[0,1]
	v_pk_add_f32 v[44:45], v[202:203], v[204:205]
	v_pk_add_f32 v[60:61], v[202:203], v[204:205] neg_lo:[0,1] neg_hi:[0,1]
	v_pk_add_f32 v[202:203], v[12:13], v[28:29] op_sel:[0,1] op_sel_hi:[1,0] neg_hi:[0,1]
	v_pk_add_f32 v[204:205], v[12:13], v[28:29] op_sel:[0,1] op_sel_hi:[1,0] neg_lo:[0,1]
	v_pk_mul_f32 v[12:13], v[224:225], v[202:203] op_sel:[1,1] op_sel_hi:[1,0]
	v_pk_fma_f32 v[12:13], v[224:225], v[202:203], v[12:13] op_sel_hi:[0,1,1] neg_lo:[0,0,1]
	v_pk_mul_f32 v[28:29], v[226:227], v[60:61] op_sel:[1,1] op_sel_hi:[1,0]
	v_pk_fma_f32 v[28:29], v[226:227], v[60:61], v[28:29] op_sel_hi:[0,1,1] neg_lo:[0,0,1]
	v_pk_mul_f32 v[60:61], v[230:231], v[204:205] op_sel:[1,1] op_sel_hi:[1,0]
	v_pk_fma_f32 v[60:61], v[230:231], v[204:205], v[60:61] op_sel_hi:[0,1,1] neg_lo:[0,0,1]
	v_pk_add_f32 v[202:203], v[16:17], v[48:49]
	v_pk_add_f32 v[16:17], v[16:17], v[48:49] neg_lo:[0,1] neg_hi:[0,1]
	v_pk_add_f32 v[204:205], v[32:33], v[64:65]
	v_pk_add_f32 v[32:33], v[32:33], v[64:65] neg_lo:[0,1] neg_hi:[0,1]
	v_pk_add_f32 v[48:49], v[202:203], v[204:205]
	v_pk_add_f32 v[64:65], v[202:203], v[204:205] neg_lo:[0,1] neg_hi:[0,1]
	v_pk_add_f32 v[202:203], v[16:17], v[32:33] op_sel:[0,1] op_sel_hi:[1,0] neg_hi:[0,1]
	v_pk_add_f32 v[204:205], v[16:17], v[32:33] op_sel:[0,1] op_sel_hi:[1,0] neg_lo:[0,1]
	v_pk_mul_f32 v[16:17], v[224:225], v[202:203] op_sel:[1,1] op_sel_hi:[1,0]
	v_pk_fma_f32 v[16:17], v[224:225], v[202:203], v[16:17] op_sel_hi:[0,1,1] neg_lo:[0,0,1]
	v_pk_mul_f32 v[32:33], v[226:227], v[64:65] op_sel:[1,1] op_sel_hi:[1,0]
	v_pk_fma_f32 v[32:33], v[226:227], v[64:65], v[32:33] op_sel_hi:[0,1,1] neg_lo:[0,0,1]
	v_pk_mul_f32 v[64:65], v[230:231], v[204:205] op_sel:[1,1] op_sel_hi:[1,0]
	v_pk_fma_f32 v[64:65], v[230:231], v[204:205], v[64:65] op_sel_hi:[0,1,1] neg_lo:[0,0,1]
	ds_write_b64 v164, v[38:39] offset:0
	v_xor_b32_e32 v156, 0x80, v164
	ds_write_b64 v156, v[34:35] offset:0
	v_xor_b32_e32 v158, 0x128, v164
	ds_write_b64 v158, v[36:37] offset:0
	v_xor_b32_e32 v160, 0x1a8, v164
	ds_write_b64 v160, v[40:41] offset:0
	v_xor_b32_e32 v162, 0x2d0, v164
	ds_write_b64 v162, v[6:7] offset:0
	v_xor_b32_e32 v156, 0x250, v164
	ds_write_b64 v156, v[2:3] offset:0
	v_xor_b32_e32 v158, 0x3f8, v164
	ds_write_b64 v158, v[4:5] offset:0
	v_xor_b32_e32 v160, 0x378, v164
	ds_write_b64 v160, v[8:9] offset:0
	v_xor_b32_e32 v162, 0x400, v164
	ds_write_b64 v162, v[22:23] offset:0
	v_xor_b32_e32 v156, 0x480, v164
	ds_write_b64 v156, v[18:19] offset:0
	v_xor_b32_e32 v158, 0x528, v164
	ds_write_b64 v158, v[20:21] offset:0
	v_xor_b32_e32 v160, 0x5a8, v164
	ds_write_b64 v160, v[24:25] offset:0
	v_xor_b32_e32 v162, 0x6d0, v164
	ds_write_b64 v162, v[54:55] offset:0
	v_xor_b32_e32 v156, 0x650, v164
	ds_write_b64 v156, v[50:51] offset:0
	v_xor_b32_e32 v158, 0x7f8, v164
	ds_write_b64 v158, v[52:53] offset:0
	v_xor_b32_e32 v160, 0x778, v164
	ds_write_b64 v160, v[56:57] offset:0
	ds_write_b64 v164, v[46:47] offset:32768
	v_xor_b32_e32 v162, 0x80, v164
	ds_write_b64 v162, v[42:43] offset:32768
	v_xor_b32_e32 v156, 0x128, v164
	ds_write_b64 v156, v[44:45] offset:32768
	v_xor_b32_e32 v158, 0x1a8, v164
	ds_write_b64 v158, v[48:49] offset:32768
	v_xor_b32_e32 v160, 0x2d0, v164
	ds_write_b64 v160, v[14:15] offset:32768
	v_xor_b32_e32 v162, 0x250, v164
	ds_write_b64 v162, v[10:11] offset:32768
	v_xor_b32_e32 v156, 0x3f8, v164
	ds_write_b64 v156, v[12:13] offset:32768
	v_xor_b32_e32 v158, 0x378, v164
	ds_write_b64 v158, v[16:17] offset:32768
	v_xor_b32_e32 v160, 0x400, v164
	ds_write_b64 v160, v[30:31] offset:32768
	v_xor_b32_e32 v162, 0x480, v164
	ds_write_b64 v162, v[26:27] offset:32768
	v_xor_b32_e32 v156, 0x528, v164
	ds_write_b64 v156, v[28:29] offset:32768
	v_xor_b32_e32 v158, 0x5a8, v164
	ds_write_b64 v158, v[32:33] offset:32768
	v_xor_b32_e32 v160, 0x6d0, v164
	ds_write_b64 v160, v[62:63] offset:32768
	v_xor_b32_e32 v162, 0x650, v164
	ds_write_b64 v162, v[58:59] offset:32768
	v_xor_b32_e32 v156, 0x7f8, v164
	ds_write_b64 v156, v[60:61] offset:32768
	v_xor_b32_e32 v158, 0x778, v164
	ds_write_b64 v158, v[64:65] offset:32768
	s_waitcnt lgkmcnt(0)
	s_barrier
; DI f32x2 cmul(f32x2 a, f32x2 b) { return mkf2(a.x * b.x - a.y * b.y, a.x * b.y + a.y * b.x); }
; DI void fft8192(f32x2* buf, const f32x2* __restrict__ tw) {
;     ...
; #pragma unroll
;     for (int e = 0; e < 8; ++e) {
;       const int i = tid + 256 * e;
;       const int pi = SW(i);
;       a[e] = buf[pi]; b[e] = buf[pi + 2048]; c[e] = buf[pi + 4096]; d[e] = buf[pi + 6144];
;     }
;     __syncthreads();
; #pragma unroll
;     for (int e = 0; e < 8; ++e) {
;       const int i = tid + 256 * e;
;       const int q = i & (s - 1);
;       const int ps = i - q;
;       const float rev = (float)ps * (1.f / 8192.f);
;       const f32x2 w1 = mkf2(__builtin_amdgcn_cosf(rev), -__builtin_amdgcn_sinf(rev));
;       const f32x2 w2 = cmul(w1, w1), w3 = cmul(w1, w2);
;       const f32x2 apc = mkf2(a[e].x + c[e].x, a[e].y + c[e].y), amc = mkf2(a[e].x - c[e].x, a[e].y - c[e].y);
;       const f32x2 bpd = mkf2(b[e].x + d[e].x, b[e].y + d[e].y), bmd = mkf2(b[e].x - d[e].x, b[e].y - d[e].y);
;       const int o = 4 * i - 3 * q;
;       buf[SW(o)] = mkf2(apc.x + bpd.x, apc.y + bpd.y);
;       buf[SW(o + s)] = cmul(w1, mkf2(amc.x + bmd.y, amc.y - bmd.x));
;       buf[SW(o + 2 * s)] = cmul(w2, mkf2(apc.x - bpd.x, apc.y - bpd.y));
;       buf[SW(o + 3 * s)] = cmul(w3, mkf2(amc.x - bmd.y, amc.y + bmd.x));
;     }
	ds_read2st64_b64 v[2:5], v154 offset0:0 offset1:32
	ds_read2st64_b64 v[6:9], v154 offset0:64 offset1:96
	ds_read2st64_b64 v[10:13], v154 offset0:4 offset1:36
	ds_read2st64_b64 v[14:17], v154 offset0:68 offset1:100
	ds_read2st64_b64 v[18:21], v154 offset0:8 offset1:40
	ds_read2st64_b64 v[22:25], v154 offset0:72 offset1:104
	ds_read2st64_b64 v[26:29], v154 offset0:12 offset1:44
	ds_read2st64_b64 v[30:33], v154 offset0:76 offset1:108
	ds_read2st64_b64 v[34:37], v154 offset0:16 offset1:48
	ds_read2st64_b64 v[38:41], v154 offset0:80 offset1:112
	ds_read2st64_b64 v[42:45], v154 offset0:20 offset1:52
	ds_read2st64_b64 v[46:49], v154 offset0:84 offset1:116
	ds_read2st64_b64 v[50:53], v154 offset0:24 offset1:56
	ds_read2st64_b64 v[54:57], v154 offset0:88 offset1:120
	ds_read2st64_b64 v[58:61], v154 offset0:28 offset1:60
	ds_read2st64_b64 v[62:65], v154 offset0:92 offset1:124
	s_waitcnt lgkmcnt(14)
	v_pk_add_f32 v[202:203], v[2:3], v[6:7]
	v_pk_add_f32 v[2:3], v[2:3], v[6:7] neg_lo:[0,1] neg_hi:[0,1]
	v_pk_add_f32 v[204:205], v[4:5], v[8:9]
	v_pk_add_f32 v[4:5], v[4:5], v[8:9] neg_lo:[0,1] neg_hi:[0,1]
	v_pk_add_f32 v[6:7], v[202:203], v[204:205]
	v_pk_add_f32 v[8:9], v[202:203], v[204:205] neg_lo:[0,1] neg_hi:[0,1]
	v_pk_add_f32 v[202:203], v[2:3], v[4:5] op_sel:[0,1] op_sel_hi:[1,0] neg_hi:[0,1]
	v_pk_add_f32 v[4:5], v[2:3], v[4:5] op_sel:[0,1] op_sel_hi:[1,0] neg_lo:[0,1]
	v_pk_mov_b32 v[2:3], v[202:203], v[202:203] op_sel:[0,1]
	v_cos_f32_e32 v210, 0x3d000000
	v_sin_f32_e32 v211, 0xbd000000
	s_waitcnt lgkmcnt(12)
	v_pk_add_f32 v[202:203], v[10:11], v[14:15]
	v_pk_add_f32 v[10:11], v[10:11], v[14:15] neg_lo:[0,1] neg_hi:[0,1]
	v_pk_add_f32 v[204:205], v[12:13], v[16:17]
	v_pk_add_f32 v[12:13], v[12:13], v[16:17] neg_lo:[0,1] neg_hi:[0,1]
	v_pk_add_f32 v[14:15], v[202:203], v[204:205]
	v_pk_add_f32 v[16:17], v[202:203], v[204:205] neg_lo:[0,1] neg_hi:[0,1]
	v_pk_add_f32 v[202:203], v[10:11], v[12:13] op_sel:[0,1] op_sel_hi:[1,0] neg_hi:[0,1]
	v_pk_add_f32 v[204:205], v[10:11], v[12:13] op_sel:[0,1] op_sel_hi:[1,0] neg_lo:[0,1]
	v_pk_mul_f32 v[206:207], v[210:211], v[210:211] op_sel:[1,1] op_sel_hi:[1,0]
	v_pk_fma_f32 v[212:213], v[210:211], v[210:211], v[206:207] op_sel_hi:[0,1,1] neg_lo:[0,0,1]
	v_pk_mul_f32 v[206:207], v[210:211], v[212:213] op_sel:[1,1] op_sel_hi:[1,0]
	v_pk_fma_f32 v[220:221], v[210:211], v[212:213], v[206:207] op_sel_hi:[0,1,1] neg_lo:[0,0,1]
	v_pk_mul_f32 v[10:11], v[210:211], v[202:203] op_sel:[1,1] op_sel_hi:[1,0]
	v_pk_fma_f32 v[10:11], v[210:211], v[202:203], v[10:11] op_sel_hi:[0,1,1] neg_lo:[0,0,1]
	v_pk_mul_f32 v[12:13], v[212:213], v[16:17] op_sel:[1,1] op_sel_hi:[1,0]
	v_pk_fma_f32 v[12:13], v[212:213], v[16:17], v[12:13] op_sel_hi:[0,1,1] neg_lo:[0,0,1]
	v_pk_mul_f32 v[16:17], v[220:221], v[204:205] op_sel:[1,1] op_sel_hi:[1,0]
	v_pk_fma_f32 v[16:17], v[220:221], v[204:205], v[16:17] op_sel_hi:[0,1,1] neg_lo:[0,0,1]
	v_cos_f32_e32 v210, 0x3d800000
	v_sin_f32_e32 v211, 0xbd800000
	s_waitcnt lgkmcnt(10)
	v_pk_add_f32 v[202:203], v[18:19], v[22:23]
	v_pk_add_f32 v[18:19], v[18:19], v[22:23] neg_lo:[0,1] neg_hi:[0,1]
	v_pk_add_f32 v[204:205], v[20:21], v[24:25]
	v_pk_add_f32 v[20:21], v[20:21], v[24:25] neg_lo:[0,1] neg_hi:[0,1]
	v_pk_add_f32 v[22:23], v[202:203], v[204:205]
	v_pk_add_f32 v[24:25], v[202:203], v[204:205] neg_lo:[0,1] neg_hi:[0,1]
	v_pk_add_f32 v[202:203], v[18:19], v[20:21] op_sel:[0,1] op_sel_hi:[1,0] neg_hi:[0,1]
	v_pk_add_f32 v[204:205], v[18:19], v[20:21] op_sel:[0,1] op_sel_hi:[1,0] neg_lo:[0,1]
	v_pk_mul_f32 v[206:207], v[210:211], v[210:211] op_sel:[1,1] op_sel_hi:[1,0]
	v_pk_fma_f32 v[212:213], v[210:211], v[210:211], v[206:207] op_sel_hi:[0,1,1] neg_lo:[0,0,1]
	v_pk_mul_f32 v[206:207], v[210:211], v[212:213] op_sel:[1,1] op_sel_hi:[1,0]
	v_pk_fma_f32 v[220:221], v[210:211], v[212:213], v[206:207] op_sel_hi:[0,1,1] neg_lo:[0,0,1]
	v_pk_mul_f32 v[18:19], v[210:211], v[202:203] op_sel:[1,1] op_sel_hi:[1,0]
	v_pk_fma_f32 v[18:19], v[210:211], v[202:203], v[18:19] op_sel_hi:[0,1,1] neg_lo:[0,0,1]
	v_pk_mul_f32 v[20:21], v[212:213], v[24:25] op_sel:[1,1] op_sel_hi:[1,0]
	v_pk_fma_f32 v[20:21], v[212:213], v[24:25], v[20:21] op_sel_hi:[0,1,1] neg_lo:[0,0,1]
	v_pk_mul_f32 v[24:25], v[220:221], v[204:205] op_sel:[1,1] op_sel_hi:[1,0]
	v_pk_fma_f32 v[24:25], v[220:221], v[204:205], v[24:25] op_sel_hi:[0,1,1] neg_lo:[0,0,1]
	v_cos_f32_e32 v210, 0x3dc00000
	v_sin_f32_e32 v211, 0xbdc00000
	s_waitcnt lgkmcnt(8)
	v_pk_add_f32 v[202:203], v[26:27], v[30:31]
	v_pk_add_f32 v[26:27], v[26:27], v[30:31] neg_lo:[0,1] neg_hi:[0,1]
	v_pk_add_f32 v[204:205], v[28:29], v[32:33]
	v_pk_add_f32 v[28:29], v[28:29], v[32:33] neg_lo:[0,1] neg_hi:[0,1]
	v_pk_add_f32 v[30:31], v[202:203], v[204:205]
	v_pk_add_f32 v[32:33], v[202:203], v[204:205] neg_lo:[0,1] neg_hi:[0,1]
	v_pk_add_f32 v[202:203], v[26:27], v[28:29] op_sel:[0,1] op_sel_hi:[1,0] neg_hi:[0,1]
	v_pk_add_f32 v[204:205], v[26:27], v[28:29] op_sel:[0,1] op_sel_hi:[1,0] neg_lo:[0,1]
	v_pk_mul_f32 v[206:207], v[210:211], v[210:211] op_sel:[1,1] op_sel_hi:[1,0]
	v_pk_fma_f32 v[212:213], v[210:211], v[210:211], v[206:207] op_sel_hi:[0,1,1] neg_lo:[0,0,1]
	v_pk_mul_f32 v[206:207], v[210:211], v[212:213] op_sel:[1,1] op_sel_hi:[1,0]
	v_pk_fma_f32 v[220:221], v[210:211], v[212:213], v[206:207] op_sel_hi:[0,1,1] neg_lo:[0,0,1]
	v_pk_mul_f32 v[26:27], v[210:211], v[202:203] op_sel:[1,1] op_sel_hi:[1,0]
	v_pk_fma_f32 v[26:27], v[210:211], v[202:203], v[26:27] op_sel_hi:[0,1,1] neg_lo:[0,0,1]
	v_pk_mul_f32 v[28:29], v[212:213], v[32:33] op_sel:[1,1] op_sel_hi:[1,0]
	v_pk_fma_f32 v[28:29], v[212:213], v[32:33], v[28:29] op_sel_hi:[0,1,1] neg_lo:[0,0,1]
	v_pk_mul_f32 v[32:33], v[220:221], v[204:205] op_sel:[1,1] op_sel_hi:[1,0]
	v_pk_fma_f32 v[32:33], v[220:221], v[204:205], v[32:33] op_sel_hi:[0,1,1] neg_lo:[0,0,1]
	v_cos_f32_e32 v210, 0x3e000000
	v_sin_f32_e32 v211, 0xbe000000
	s_waitcnt lgkmcnt(6)
; DI f32x2 cmul(f32x2 a, f32x2 b) { return mkf2(a.x * b.x - a.y * b.y, a.x * b.y + a.y * b.x); }
; DI void fft8192(f32x2* buf, const f32x2* __restrict__ tw) {
;     ...
; #pragma unroll
;     for (int e = 0; e < 8; ++e) {
;       const int i = tid + 256 * e;
;       const int q = i & (s - 1);
;       const int ps = i - q;
;       const float rev = (float)ps * (1.f / 8192.f);
;       const f32x2 w1 = mkf2(__builtin_amdgcn_cosf(rev), -__builtin_amdgcn_sinf(rev));
;       const f32x2 w2 = cmul(w1, w1), w3 = cmul(w1, w2);
;       const f32x2 apc = mkf2(a[e].x + c[e].x, a[e].y + c[e].y), amc = mkf2(a[e].x - c[e].x, a[e].y - c[e].y);
;       const f32x2 bpd = mkf2(b[e].x + d[e].x, b[e].y + d[e].y), bmd = mkf2(b[e].x - d[e].x, b[e].y - d[e].y);
;       const int o = 4 * i - 3 * q;
;       buf[SW(o)] = mkf2(apc.x + bpd.x, apc.y + bpd.y);
;       buf[SW(o + s)] = cmul(w1, mkf2(amc.x + bmd.y, amc.y - bmd.x));
;       buf[SW(o + 2 * s)] = cmul(w2, mkf2(apc.x - bpd.x, apc.y - bpd.y));
;       buf[SW(o + 3 * s)] = cmul(w3, mkf2(amc.x - bmd.y, amc.y + bmd.x));
;     }
	v_pk_add_f32 v[202:203], v[34:35], v[38:39]
	v_pk_add_f32 v[34:35], v[34:35], v[38:39] neg_lo:[0,1] neg_hi:[0,1]
	v_pk_add_f32 v[204:205], v[36:37], v[40:41]
	v_pk_add_f32 v[36:37], v[36:37], v[40:41] neg_lo:[0,1] neg_hi:[0,1]
	v_pk_add_f32 v[38:39], v[202:203], v[204:205]
	v_pk_add_f32 v[40:41], v[202:203], v[204:205] neg_lo:[0,1] neg_hi:[0,1]
	v_pk_add_f32 v[202:203], v[34:35], v[36:37] op_sel:[0,1] op_sel_hi:[1,0] neg_hi:[0,1]
	v_pk_add_f32 v[204:205], v[34:35], v[36:37] op_sel:[0,1] op_sel_hi:[1,0] neg_lo:[0,1]
	v_pk_mul_f32 v[206:207], v[210:211], v[210:211] op_sel:[1,1] op_sel_hi:[1,0]
	v_pk_fma_f32 v[212:213], v[210:211], v[210:211], v[206:207] op_sel_hi:[0,1,1] neg_lo:[0,0,1]
	v_pk_mul_f32 v[206:207], v[210:211], v[212:213] op_sel:[1,1] op_sel_hi:[1,0]
	v_pk_fma_f32 v[220:221], v[210:211], v[212:213], v[206:207] op_sel_hi:[0,1,1] neg_lo:[0,0,1]
	v_pk_mul_f32 v[34:35], v[210:211], v[202:203] op_sel:[1,1] op_sel_hi:[1,0]
	v_pk_fma_f32 v[34:35], v[210:211], v[202:203], v[34:35] op_sel_hi:[0,1,1] neg_lo:[0,0,1]
	v_pk_mul_f32 v[36:37], v[212:213], v[40:41] op_sel:[1,1] op_sel_hi:[1,0]
	v_pk_fma_f32 v[36:37], v[212:213], v[40:41], v[36:37] op_sel_hi:[0,1,1] neg_lo:[0,0,1]
	v_pk_mul_f32 v[40:41], v[220:221], v[204:205] op_sel:[1,1] op_sel_hi:[1,0]
	v_pk_fma_f32 v[40:41], v[220:221], v[204:205], v[40:41] op_sel_hi:[0,1,1] neg_lo:[0,0,1]
	v_cos_f32_e32 v210, 0x3e200000
	v_sin_f32_e32 v211, 0xbe200000
	s_waitcnt lgkmcnt(4)
	v_pk_add_f32 v[202:203], v[42:43], v[46:47]
	v_pk_add_f32 v[42:43], v[42:43], v[46:47] neg_lo:[0,1] neg_hi:[0,1]
	v_pk_add_f32 v[204:205], v[44:45], v[48:49]
	v_pk_add_f32 v[44:45], v[44:45], v[48:49] neg_lo:[0,1] neg_hi:[0,1]
	v_pk_add_f32 v[46:47], v[202:203], v[204:205]
	v_pk_add_f32 v[48:49], v[202:203], v[204:205] neg_lo:[0,1] neg_hi:[0,1]
	v_pk_add_f32 v[202:203], v[42:43], v[44:45] op_sel:[0,1] op_sel_hi:[1,0] neg_hi:[0,1]
	v_pk_add_f32 v[204:205], v[42:43], v[44:45] op_sel:[0,1] op_sel_hi:[1,0] neg_lo:[0,1]
	v_pk_mul_f32 v[206:207], v[210:211], v[210:211] op_sel:[1,1] op_sel_hi:[1,0]
	v_pk_fma_f32 v[212:213], v[210:211], v[210:211], v[206:207] op_sel_hi:[0,1,1] neg_lo:[0,0,1]
	v_pk_mul_f32 v[206:207], v[210:211], v[212:213] op_sel:[1,1] op_sel_hi:[1,0]
	v_pk_fma_f32 v[220:221], v[210:211], v[212:213], v[206:207] op_sel_hi:[0,1,1] neg_lo:[0,0,1]
	v_pk_mul_f32 v[42:43], v[210:211], v[202:203] op_sel:[1,1] op_sel_hi:[1,0]
	v_pk_fma_f32 v[42:43], v[210:211], v[202:203], v[42:43] op_sel_hi:[0,1,1] neg_lo:[0,0,1]
	v_pk_mul_f32 v[44:45], v[212:213], v[48:49] op_sel:[1,1] op_sel_hi:[1,0]
	v_pk_fma_f32 v[44:45], v[212:213], v[48:49], v[44:45] op_sel_hi:[0,1,1] neg_lo:[0,0,1]
	v_pk_mul_f32 v[48:49], v[220:221], v[204:205] op_sel:[1,1] op_sel_hi:[1,0]
	v_pk_fma_f32 v[48:49], v[220:221], v[204:205], v[48:49] op_sel_hi:[0,1,1] neg_lo:[0,0,1]
	v_cos_f32_e32 v210, 0x3e400000
	v_sin_f32_e32 v211, 0xbe400000
	s_waitcnt lgkmcnt(2)
	v_pk_add_f32 v[202:203], v[50:51], v[54:55]
	v_pk_add_f32 v[50:51], v[50:51], v[54:55] neg_lo:[0,1] neg_hi:[0,1]
	v_pk_add_f32 v[204:205], v[52:53], v[56:57]
	v_pk_add_f32 v[52:53], v[52:53], v[56:57] neg_lo:[0,1] neg_hi:[0,1]
	v_pk_add_f32 v[54:55], v[202:203], v[204:205]
	v_pk_add_f32 v[56:57], v[202:203], v[204:205] neg_lo:[0,1] neg_hi:[0,1]
	v_pk_add_f32 v[202:203], v[50:51], v[52:53] op_sel:[0,1] op_sel_hi:[1,0] neg_hi:[0,1]
	v_pk_add_f32 v[204:205], v[50:51], v[52:53] op_sel:[0,1] op_sel_hi:[1,0] neg_lo:[0,1]
	v_pk_mul_f32 v[206:207], v[210:211], v[210:211] op_sel:[1,1] op_sel_hi:[1,0]
	v_pk_fma_f32 v[212:213], v[210:211], v[210:211], v[206:207] op_sel_hi:[0,1,1] neg_lo:[0,0,1]
	v_pk_mul_f32 v[206:207], v[210:211], v[212:213] op_sel:[1,1] op_sel_hi:[1,0]
	v_pk_fma_f32 v[220:221], v[210:211], v[212:213], v[206:207] op_sel_hi:[0,1,1] neg_lo:[0,0,1]
	v_pk_mul_f32 v[50:51], v[210:211], v[202:203] op_sel:[1,1] op_sel_hi:[1,0]
	v_pk_fma_f32 v[50:51], v[210:211], v[202:203], v[50:51] op_sel_hi:[0,1,1] neg_lo:[0,0,1]
	v_pk_mul_f32 v[52:53], v[212:213], v[56:57] op_sel:[1,1] op_sel_hi:[1,0]
	v_pk_fma_f32 v[52:53], v[212:213], v[56:57], v[52:53] op_sel_hi:[0,1,1] neg_lo:[0,0,1]
	v_pk_mul_f32 v[56:57], v[220:221], v[204:205] op_sel:[1,1] op_sel_hi:[1,0]
	v_pk_fma_f32 v[56:57], v[220:221], v[204:205], v[56:57] op_sel_hi:[0,1,1] neg_lo:[0,0,1]
	v_cos_f32_e32 v210, 0x3e600000
	v_sin_f32_e32 v211, 0xbe600000
	s_waitcnt lgkmcnt(0)
	v_pk_add_f32 v[202:203], v[58:59], v[62:63]
	v_pk_add_f32 v[58:59], v[58:59], v[62:63] neg_lo:[0,1] neg_hi:[0,1]
	v_pk_add_f32 v[204:205], v[60:61], v[64:65]
	v_pk_add_f32 v[60:61], v[60:61], v[64:65] neg_lo:[0,1] neg_hi:[0,1]
	v_pk_add_f32 v[62:63], v[202:203], v[204:205]
	v_pk_add_f32 v[64:65], v[202:203], v[204:205] neg_lo:[0,1] neg_hi:[0,1]
	v_pk_add_f32 v[202:203], v[58:59], v[60:61] op_sel:[0,1] op_sel_hi:[1,0] neg_hi:[0,1]
	v_pk_add_f32 v[204:205], v[58:59], v[60:61] op_sel:[0,1] op_sel_hi:[1,0] neg_lo:[0,1]
	v_pk_mul_f32 v[206:207], v[210:211], v[210:211] op_sel:[1,1] op_sel_hi:[1,0]
	v_pk_fma_f32 v[212:213], v[210:211], v[210:211], v[206:207] op_sel_hi:[0,1,1] neg_lo:[0,0,1]
	v_pk_mul_f32 v[206:207], v[210:211], v[212:213] op_sel:[1,1] op_sel_hi:[1,0]
	v_pk_fma_f32 v[220:221], v[210:211], v[212:213], v[206:207] op_sel_hi:[0,1,1] neg_lo:[0,0,1]
	v_pk_mul_f32 v[58:59], v[210:211], v[202:203] op_sel:[1,1] op_sel_hi:[1,0]
	v_pk_fma_f32 v[58:59], v[210:211], v[202:203], v[58:59] op_sel_hi:[0,1,1] neg_lo:[0,0,1]
	v_pk_mul_f32 v[60:61], v[212:213], v[64:65] op_sel:[1,1] op_sel_hi:[1,0]
	v_pk_fma_f32 v[60:61], v[212:213], v[64:65], v[60:61] op_sel_hi:[0,1,1] neg_lo:[0,0,1]
	v_pk_mul_f32 v[64:65], v[220:221], v[204:205] op_sel:[1,1] op_sel_hi:[1,0]
	v_pk_fma_f32 v[64:65], v[220:221], v[204:205], v[64:65] op_sel_hi:[0,1,1] neg_lo:[0,0,1]
	s_barrier
; DI f32x2 cmul(f32x2 a, f32x2 b) { return mkf2(a.x * b.x - a.y * b.y, a.x * b.y + a.y * b.x); }
; DI void fft8192(f32x2* buf, const f32x2* __restrict__ tw) {
;     ...
; #pragma unroll
;     for (int e = 0; e < 8; ++e) {
;       const int i = tid + 256 * e;
;       const int q = i & (s - 1);
;       const int ps = i - q;
;       const float rev = (float)ps * (1.f / 8192.f);
;       const f32x2 w1 = mkf2(__builtin_amdgcn_cosf(rev), -__builtin_amdgcn_sinf(rev));
;       const f32x2 w2 = cmul(w1, w1), w3 = cmul(w1, w2);
;       const f32x2 apc = mkf2(a[e].x + c[e].x, a[e].y + c[e].y), amc = mkf2(a[e].x - c[e].x, a[e].y - c[e].y);
;       const f32x2 bpd = mkf2(b[e].x + d[e].x, b[e].y + d[e].y), bmd = mkf2(b[e].x - d[e].x, b[e].y - d[e].y);
;       const int o = 4 * i - 3 * q;
;       buf[SW(o)] = mkf2(apc.x + bpd.x, apc.y + bpd.y);
;       buf[SW(o + s)] = cmul(w1, mkf2(amc.x + bmd.y, amc.y - bmd.x));
;       buf[SW(o + 2 * s)] = cmul(w2, mkf2(apc.x - bpd.x, apc.y - bpd.y));
;       buf[SW(o + 3 * s)] = cmul(w3, mkf2(amc.x - bmd.y, amc.y + bmd.x));
;     }
	v_pk_add_f32 v[202:203], v[6:7], v[38:39]
	v_pk_add_f32 v[6:7], v[6:7], v[38:39] neg_lo:[0,1] neg_hi:[0,1]
	v_pk_add_f32 v[204:205], v[22:23], v[54:55]
	v_pk_add_f32 v[22:23], v[22:23], v[54:55] neg_lo:[0,1] neg_hi:[0,1]
	v_pk_add_f32 v[38:39], v[202:203], v[204:205]
	v_pk_add_f32 v[54:55], v[202:203], v[204:205] neg_lo:[0,1] neg_hi:[0,1]
	v_pk_add_f32 v[202:203], v[6:7], v[22:23] op_sel:[0,1] op_sel_hi:[1,0] neg_hi:[0,1]
	v_pk_add_f32 v[22:23], v[6:7], v[22:23] op_sel:[0,1] op_sel_hi:[1,0] neg_lo:[0,1]
	v_pk_mov_b32 v[6:7], v[202:203], v[202:203] op_sel:[0,1]
	v_pk_add_f32 v[202:203], v[2:3], v[34:35]
	v_pk_add_f32 v[2:3], v[2:3], v[34:35] neg_lo:[0,1] neg_hi:[0,1]
	v_pk_add_f32 v[204:205], v[18:19], v[50:51]
	v_pk_add_f32 v[18:19], v[18:19], v[50:51] neg_lo:[0,1] neg_hi:[0,1]
	v_pk_add_f32 v[34:35], v[202:203], v[204:205]
	v_pk_add_f32 v[50:51], v[202:203], v[204:205] neg_lo:[0,1] neg_hi:[0,1]
	v_pk_add_f32 v[202:203], v[2:3], v[18:19] op_sel:[0,1] op_sel_hi:[1,0] neg_hi:[0,1]
	v_pk_add_f32 v[18:19], v[2:3], v[18:19] op_sel:[0,1] op_sel_hi:[1,0] neg_lo:[0,1]
	v_pk_mov_b32 v[2:3], v[202:203], v[202:203] op_sel:[0,1]
	v_pk_add_f32 v[202:203], v[8:9], v[36:37]
	v_pk_add_f32 v[8:9], v[8:9], v[36:37] neg_lo:[0,1] neg_hi:[0,1]
	v_pk_add_f32 v[204:205], v[20:21], v[52:53]
	v_pk_add_f32 v[20:21], v[20:21], v[52:53] neg_lo:[0,1] neg_hi:[0,1]
	v_pk_add_f32 v[36:37], v[202:203], v[204:205]
	v_pk_add_f32 v[52:53], v[202:203], v[204:205] neg_lo:[0,1] neg_hi:[0,1]
	v_pk_add_f32 v[202:203], v[8:9], v[20:21] op_sel:[0,1] op_sel_hi:[1,0] neg_hi:[0,1]
	v_pk_add_f32 v[20:21], v[8:9], v[20:21] op_sel:[0,1] op_sel_hi:[1,0] neg_lo:[0,1]
	v_pk_mov_b32 v[8:9], v[202:203], v[202:203] op_sel:[0,1]
	v_pk_add_f32 v[202:203], v[4:5], v[40:41]
	v_pk_add_f32 v[4:5], v[4:5], v[40:41] neg_lo:[0,1] neg_hi:[0,1]
	v_pk_add_f32 v[204:205], v[24:25], v[56:57]
	v_pk_add_f32 v[24:25], v[24:25], v[56:57] neg_lo:[0,1] neg_hi:[0,1]
	v_pk_add_f32 v[40:41], v[202:203], v[204:205]
	v_pk_add_f32 v[56:57], v[202:203], v[204:205] neg_lo:[0,1] neg_hi:[0,1]
	v_pk_add_f32 v[202:203], v[4:5], v[24:25] op_sel:[0,1] op_sel_hi:[1,0] neg_hi:[0,1]
	v_pk_add_f32 v[24:25], v[4:5], v[24:25] op_sel:[0,1] op_sel_hi:[1,0] neg_lo:[0,1]
	v_pk_mov_b32 v[4:5], v[202:203], v[202:203] op_sel:[0,1]
	v_cos_f32_e32 v224, 0x3e000000
	v_sin_f32_e32 v225, 0xbe000000
	s_nop 0
	v_pk_mul_f32 v[206:207], v[224:225], v[224:225] op_sel:[1,1] op_sel_hi:[1,0]
	v_pk_fma_f32 v[226:227], v[224:225], v[224:225], v[206:207] op_sel_hi:[0,1,1] neg_lo:[0,0,1]
	v_pk_mul_f32 v[206:207], v[224:225], v[226:227] op_sel:[1,1] op_sel_hi:[1,0]
	v_pk_fma_f32 v[230:231], v[224:225], v[226:227], v[206:207] op_sel_hi:[0,1,1] neg_lo:[0,0,1]
	v_pk_add_f32 v[202:203], v[14:15], v[46:47]
	v_pk_add_f32 v[14:15], v[14:15], v[46:47] neg_lo:[0,1] neg_hi:[0,1]
	v_pk_add_f32 v[204:205], v[30:31], v[62:63]
	v_pk_add_f32 v[30:31], v[30:31], v[62:63] neg_lo:[0,1] neg_hi:[0,1]
	v_pk_add_f32 v[46:47], v[202:203], v[204:205]
	v_pk_add_f32 v[62:63], v[202:203], v[204:205] neg_lo:[0,1] neg_hi:[0,1]
	v_pk_add_f32 v[202:203], v[14:15], v[30:31] op_sel:[0,1] op_sel_hi:[1,0] neg_hi:[0,1]
	v_pk_add_f32 v[204:205], v[14:15], v[30:31] op_sel:[0,1] op_sel_hi:[1,0] neg_lo:[0,1]
	v_pk_mul_f32 v[14:15], v[224:225], v[202:203] op_sel:[1,1] op_sel_hi:[1,0]
	v_pk_fma_f32 v[14:15], v[224:225], v[202:203], v[14:15] op_sel_hi:[0,1,1] neg_lo:[0,0,1]
	v_pk_mul_f32 v[30:31], v[226:227], v[62:63] op_sel:[1,1] op_sel_hi:[1,0]
	v_pk_fma_f32 v[30:31], v[226:227], v[62:63], v[30:31] op_sel_hi:[0,1,1] neg_lo:[0,0,1]
	v_pk_mul_f32 v[62:63], v[230:231], v[204:205] op_sel:[1,1] op_sel_hi:[1,0]
	v_pk_fma_f32 v[62:63], v[230:231], v[204:205], v[62:63] op_sel_hi:[0,1,1] neg_lo:[0,0,1]
	v_pk_add_f32 v[202:203], v[10:11], v[42:43]
	v_pk_add_f32 v[10:11], v[10:11], v[42:43] neg_lo:[0,1] neg_hi:[0,1]
	v_pk_add_f32 v[204:205], v[26:27], v[58:59]
	v_pk_add_f32 v[26:27], v[26:27], v[58:59] neg_lo:[0,1] neg_hi:[0,1]
	v_pk_add_f32 v[42:43], v[202:203], v[204:205]
	v_pk_add_f32 v[58:59], v[202:203], v[204:205] neg_lo:[0,1] neg_hi:[0,1]
	v_pk_add_f32 v[202:203], v[10:11], v[26:27] op_sel:[0,1] op_sel_hi:[1,0] neg_hi:[0,1]
	v_pk_add_f32 v[204:205], v[10:11], v[26:27] op_sel:[0,1] op_sel_hi:[1,0] neg_lo:[0,1]
	v_pk_mul_f32 v[10:11], v[224:225], v[202:203] op_sel:[1,1] op_sel_hi:[1,0]
	v_pk_fma_f32 v[10:11], v[224:225], v[202:203], v[10:11] op_sel_hi:[0,1,1] neg_lo:[0,0,1]
	v_pk_mul_f32 v[26:27], v[226:227], v[58:59] op_sel:[1,1] op_sel_hi:[1,0]
	v_pk_fma_f32 v[26:27], v[226:227], v[58:59], v[26:27] op_sel_hi:[0,1,1] neg_lo:[0,0,1]
	v_pk_mul_f32 v[58:59], v[230:231], v[204:205] op_sel:[1,1] op_sel_hi:[1,0]
	v_pk_fma_f32 v[58:59], v[230:231], v[204:205], v[58:59] op_sel_hi:[0,1,1] neg_lo:[0,0,1]
	v_pk_add_f32 v[202:203], v[12:13], v[44:45]
	v_pk_add_f32 v[12:13], v[12:13], v[44:45] neg_lo:[0,1] neg_hi:[0,1]
	v_pk_add_f32 v[204:205], v[28:29], v[60:61]
	v_pk_add_f32 v[28:29], v[28:29], v[60:61] neg_lo:[0,1] neg_hi:[0,1]
	v_pk_add_f32 v[44:45], v[202:203], v[204:205]
	v_pk_add_f32 v[60:61], v[202:203], v[204:205] neg_lo:[0,1] neg_hi:[0,1]
	v_pk_add_f32 v[202:203], v[12:13], v[28:29] op_sel:[0,1] op_sel_hi:[1,0] neg_hi:[0,1]
	v_pk_add_f32 v[204:205], v[12:13], v[28:29] op_sel:[0,1] op_sel_hi:[1,0] neg_lo:[0,1]
	v_pk_mul_f32 v[12:13], v[224:225], v[202:203] op_sel:[1,1] op_sel_hi:[1,0]
	v_pk_fma_f32 v[12:13], v[224:225], v[202:203], v[12:13] op_sel_hi:[0,1,1] neg_lo:[0,0,1]
	v_pk_mul_f32 v[28:29], v[226:227], v[60:61] op_sel:[1,1] op_sel_hi:[1,0]
	v_pk_fma_f32 v[28:29], v[226:227], v[60:61], v[28:29] op_sel_hi:[0,1,1] neg_lo:[0,0,1]
	v_pk_mul_f32 v[60:61], v[230:231], v[204:205] op_sel:[1,1] op_sel_hi:[1,0]
; DI f32x2 cmul(f32x2 a, f32x2 b) { return mkf2(a.x * b.x - a.y * b.y, a.x * b.y + a.y * b.x); }
; DI void fft8192(f32x2* buf, const f32x2* __restrict__ tw) {
;     ...
;     for (int e = 0; e < 16; ++e) {
;       const int pi = SW(tid + 256 * e);
;       buf[pi] = mkf2(a[e].x + b[e].x, a[e].y + b[e].y);
;       buf[pi + 4096] = mkf2(a[e].x - b[e].x, a[e].y - b[e].y);
;     }
; DI void hyena_unit(KP p, int l, int c, char* smem) {
;     ...
; #pragma unroll
;       for (int j = 0; j < 32; ++j) {
;         const int f = tid + 256 * j;
;         f32x2 z = cmul(buf[SW(f)], KF[j]);
;         buf[SW(f)] = mkf2(z.x, -z.y);
;       }
	v_pk_fma_f32 v[60:61], v[230:231], v[204:205], v[60:61] op_sel_hi:[0,1,1] neg_lo:[0,0,1]
	v_pk_add_f32 v[202:203], v[16:17], v[48:49]
	v_pk_add_f32 v[16:17], v[16:17], v[48:49] neg_lo:[0,1] neg_hi:[0,1]
	v_pk_add_f32 v[204:205], v[32:33], v[64:65]
	v_pk_add_f32 v[32:33], v[32:33], v[64:65] neg_lo:[0,1] neg_hi:[0,1]
	v_pk_add_f32 v[48:49], v[202:203], v[204:205]
	v_pk_add_f32 v[64:65], v[202:203], v[204:205] neg_lo:[0,1] neg_hi:[0,1]
	v_pk_add_f32 v[202:203], v[16:17], v[32:33] op_sel:[0,1] op_sel_hi:[1,0] neg_hi:[0,1]
	v_pk_add_f32 v[204:205], v[16:17], v[32:33] op_sel:[0,1] op_sel_hi:[1,0] neg_lo:[0,1]
	v_pk_mul_f32 v[16:17], v[224:225], v[202:203] op_sel:[1,1] op_sel_hi:[1,0]
	v_pk_fma_f32 v[16:17], v[224:225], v[202:203], v[16:17] op_sel_hi:[0,1,1] neg_lo:[0,0,1]
	v_pk_mul_f32 v[32:33], v[226:227], v[64:65] op_sel:[1,1] op_sel_hi:[1,0]
	v_pk_fma_f32 v[32:33], v[226:227], v[64:65], v[32:33] op_sel_hi:[0,1,1] neg_lo:[0,0,1]
	v_pk_mul_f32 v[64:65], v[230:231], v[204:205] op_sel:[1,1] op_sel_hi:[1,0]
	v_pk_fma_f32 v[64:65], v[230:231], v[204:205], v[64:65] op_sel_hi:[0,1,1] neg_lo:[0,0,1]
	v_pk_add_f32 v[202:203], v[38:39], v[46:47]
	v_pk_add_f32 v[46:47], v[38:39], v[46:47] neg_lo:[0,1] neg_hi:[0,1]
	v_pk_mul_f32 v[38:39], v[78:79], v[202:203] op_sel:[1,1] op_sel_hi:[1,0]
	v_pk_fma_f32 v[202:203], v[78:79], v[202:203], v[38:39] op_sel_hi:[0,1,1] neg_lo:[0,0,1] neg_hi:[1,0,1]
	v_pk_mul_f32 v[38:39], v[110:111], v[46:47] op_sel:[1,1] op_sel_hi:[1,0]
	v_pk_fma_f32 v[46:47], v[110:111], v[46:47], v[38:39] op_sel_hi:[0,1,1] neg_lo:[0,0,1] neg_hi:[1,0,1]
	v_pk_add_f32 v[204:205], v[34:35], v[42:43]
	v_pk_add_f32 v[42:43], v[34:35], v[42:43] neg_lo:[0,1] neg_hi:[0,1]
	v_pk_mul_f32 v[34:35], v[80:81], v[204:205] op_sel:[1,1] op_sel_hi:[1,0]
	v_pk_fma_f32 v[204:205], v[80:81], v[204:205], v[34:35] op_sel_hi:[0,1,1] neg_lo:[0,0,1] neg_hi:[1,0,1]
	v_pk_mul_f32 v[34:35], v[112:113], v[42:43] op_sel:[1,1] op_sel_hi:[1,0]
	v_pk_fma_f32 v[42:43], v[112:113], v[42:43], v[34:35] op_sel_hi:[0,1,1] neg_lo:[0,0,1] neg_hi:[1,0,1]
	v_pk_add_f32 v[206:207], v[36:37], v[44:45]
	v_pk_add_f32 v[44:45], v[36:37], v[44:45] neg_lo:[0,1] neg_hi:[0,1]
	v_pk_mul_f32 v[36:37], v[82:83], v[206:207] op_sel:[1,1] op_sel_hi:[1,0]
	v_pk_fma_f32 v[206:207], v[82:83], v[206:207], v[36:37] op_sel_hi:[0,1,1] neg_lo:[0,0,1] neg_hi:[1,0,1]
	v_pk_mul_f32 v[36:37], v[114:115], v[44:45] op_sel:[1,1] op_sel_hi:[1,0]
	v_pk_fma_f32 v[44:45], v[114:115], v[44:45], v[36:37] op_sel_hi:[0,1,1] neg_lo:[0,0,1] neg_hi:[1,0,1]
	v_pk_add_f32 v[208:209], v[40:41], v[48:49]
	v_pk_add_f32 v[48:49], v[40:41], v[48:49] neg_lo:[0,1] neg_hi:[0,1]
	v_pk_mul_f32 v[40:41], v[84:85], v[208:209] op_sel:[1,1] op_sel_hi:[1,0]
	v_pk_fma_f32 v[208:209], v[84:85], v[208:209], v[40:41] op_sel_hi:[0,1,1] neg_lo:[0,0,1] neg_hi:[1,0,1]
	v_pk_mul_f32 v[40:41], v[116:117], v[48:49] op_sel:[1,1] op_sel_hi:[1,0]
	v_pk_fma_f32 v[48:49], v[116:117], v[48:49], v[40:41] op_sel_hi:[0,1,1] neg_lo:[0,0,1] neg_hi:[1,0,1]
	v_pk_add_f32 v[210:211], v[6:7], v[14:15]
	v_pk_add_f32 v[14:15], v[6:7], v[14:15] neg_lo:[0,1] neg_hi:[0,1]
	v_pk_mul_f32 v[6:7], v[86:87], v[210:211] op_sel:[1,1] op_sel_hi:[1,0]
	v_pk_fma_f32 v[210:211], v[86:87], v[210:211], v[6:7] op_sel_hi:[0,1,1] neg_lo:[0,0,1] neg_hi:[1,0,1]
	v_pk_mul_f32 v[6:7], v[118:119], v[14:15] op_sel:[1,1] op_sel_hi:[1,0]
	v_pk_fma_f32 v[14:15], v[118:119], v[14:15], v[6:7] op_sel_hi:[0,1,1] neg_lo:[0,0,1] neg_hi:[1,0,1]
	v_pk_add_f32 v[212:213], v[2:3], v[10:11]
	v_pk_add_f32 v[10:11], v[2:3], v[10:11] neg_lo:[0,1] neg_hi:[0,1]
	v_pk_mul_f32 v[2:3], v[88:89], v[212:213] op_sel:[1,1] op_sel_hi:[1,0]
	v_pk_fma_f32 v[212:213], v[88:89], v[212:213], v[2:3] op_sel_hi:[0,1,1] neg_lo:[0,0,1] neg_hi:[1,0,1]
	v_pk_mul_f32 v[2:3], v[120:121], v[10:11] op_sel:[1,1] op_sel_hi:[1,0]
	v_pk_fma_f32 v[10:11], v[120:121], v[10:11], v[2:3] op_sel_hi:[0,1,1] neg_lo:[0,0,1] neg_hi:[1,0,1]
	v_pk_add_f32 v[220:221], v[8:9], v[12:13]
	v_pk_add_f32 v[12:13], v[8:9], v[12:13] neg_lo:[0,1] neg_hi:[0,1]
	v_pk_mul_f32 v[8:9], v[90:91], v[220:221] op_sel:[1,1] op_sel_hi:[1,0]
	v_pk_fma_f32 v[220:221], v[90:91], v[220:221], v[8:9] op_sel_hi:[0,1,1] neg_lo:[0,0,1] neg_hi:[1,0,1]
	v_pk_mul_f32 v[8:9], v[122:123], v[12:13] op_sel:[1,1] op_sel_hi:[1,0]
	v_pk_fma_f32 v[12:13], v[122:123], v[12:13], v[8:9] op_sel_hi:[0,1,1] neg_lo:[0,0,1] neg_hi:[1,0,1]
	v_pk_add_f32 v[224:225], v[4:5], v[16:17]
	v_pk_add_f32 v[16:17], v[4:5], v[16:17] neg_lo:[0,1] neg_hi:[0,1]
	v_pk_mul_f32 v[4:5], v[92:93], v[224:225] op_sel:[1,1] op_sel_hi:[1,0]
	v_pk_fma_f32 v[224:225], v[92:93], v[224:225], v[4:5] op_sel_hi:[0,1,1] neg_lo:[0,0,1] neg_hi:[1,0,1]
	v_pk_mul_f32 v[4:5], v[124:125], v[16:17] op_sel:[1,1] op_sel_hi:[1,0]
	v_pk_fma_f32 v[16:17], v[124:125], v[16:17], v[4:5] op_sel_hi:[0,1,1] neg_lo:[0,0,1] neg_hi:[1,0,1]
	v_pk_add_f32 v[226:227], v[54:55], v[30:31]
	v_pk_add_f32 v[30:31], v[54:55], v[30:31] neg_lo:[0,1] neg_hi:[0,1]
	v_pk_mul_f32 v[54:55], v[94:95], v[226:227] op_sel:[1,1] op_sel_hi:[1,0]
	v_pk_fma_f32 v[226:227], v[94:95], v[226:227], v[54:55] op_sel_hi:[0,1,1] neg_lo:[0,0,1] neg_hi:[1,0,1]
	v_pk_mul_f32 v[54:55], v[126:127], v[30:31] op_sel:[1,1] op_sel_hi:[1,0]
	v_pk_fma_f32 v[30:31], v[126:127], v[30:31], v[54:55] op_sel_hi:[0,1,1] neg_lo:[0,0,1] neg_hi:[1,0,1]
	v_pk_add_f32 v[230:231], v[50:51], v[26:27]
	v_pk_add_f32 v[26:27], v[50:51], v[26:27] neg_lo:[0,1] neg_hi:[0,1]
	v_pk_mul_f32 v[50:51], v[96:97], v[230:231] op_sel:[1,1] op_sel_hi:[1,0]
	v_pk_fma_f32 v[230:231], v[96:97], v[230:231], v[50:51] op_sel_hi:[0,1,1] neg_lo:[0,0,1] neg_hi:[1,0,1]
	v_pk_mul_f32 v[50:51], v[128:129], v[26:27] op_sel:[1,1] op_sel_hi:[1,0]
; DI f32x2 cmul(f32x2 a, f32x2 b) { return mkf2(a.x * b.x - a.y * b.y, a.x * b.y + a.y * b.x); }
; DI void fft8192(f32x2* buf, const f32x2* __restrict__ tw) {
;     ...
;       const int i = tid + 256 * e;
;       const int pi = SW(i);
;       a[e] = buf[pi]; b[e] = buf[pi + 2048]; c[e] = buf[pi + 4096]; d[e] = buf[pi + 6144];
;     ...
;     for (int e = 0; e < 16; ++e) {
;       const int pi = SW(tid + 256 * e);
;       buf[pi] = mkf2(a[e].x + b[e].x, a[e].y + b[e].y);
;       buf[pi + 4096] = mkf2(a[e].x - b[e].x, a[e].y - b[e].y);
;     }
; DI void hyena_unit(KP p, int l, int c, char* smem) {
;     ...
; #pragma unroll
;       for (int j = 0; j < 32; ++j) {
;         const int f = tid + 256 * j;
;         f32x2 z = cmul(buf[SW(f)], KF[j]);
;         buf[SW(f)] = mkf2(z.x, -z.y);
;       }
	v_pk_fma_f32 v[26:27], v[128:129], v[26:27], v[50:51] op_sel_hi:[0,1,1] neg_lo:[0,0,1] neg_hi:[1,0,1]
	v_pk_add_f32 v[232:233], v[52:53], v[28:29]
	v_pk_add_f32 v[28:29], v[52:53], v[28:29] neg_lo:[0,1] neg_hi:[0,1]
	v_pk_mul_f32 v[52:53], v[98:99], v[232:233] op_sel:[1,1] op_sel_hi:[1,0]
	v_pk_fma_f32 v[232:233], v[98:99], v[232:233], v[52:53] op_sel_hi:[0,1,1] neg_lo:[0,0,1] neg_hi:[1,0,1]
	v_pk_mul_f32 v[52:53], v[130:131], v[28:29] op_sel:[1,1] op_sel_hi:[1,0]
	v_pk_fma_f32 v[28:29], v[130:131], v[28:29], v[52:53] op_sel_hi:[0,1,1] neg_lo:[0,0,1] neg_hi:[1,0,1]
	v_pk_add_f32 v[236:237], v[56:57], v[32:33]
	v_pk_add_f32 v[32:33], v[56:57], v[32:33] neg_lo:[0,1] neg_hi:[0,1]
	v_pk_mul_f32 v[56:57], v[100:101], v[236:237] op_sel:[1,1] op_sel_hi:[1,0]
	v_pk_fma_f32 v[236:237], v[100:101], v[236:237], v[56:57] op_sel_hi:[0,1,1] neg_lo:[0,0,1] neg_hi:[1,0,1]
	v_pk_mul_f32 v[56:57], v[132:133], v[32:33] op_sel:[1,1] op_sel_hi:[1,0]
	v_pk_fma_f32 v[32:33], v[132:133], v[32:33], v[56:57] op_sel_hi:[0,1,1] neg_lo:[0,0,1] neg_hi:[1,0,1]
	v_pk_add_f32 v[238:239], v[22:23], v[62:63]
	v_pk_add_f32 v[62:63], v[22:23], v[62:63] neg_lo:[0,1] neg_hi:[0,1]
	v_pk_mul_f32 v[22:23], v[102:103], v[238:239] op_sel:[1,1] op_sel_hi:[1,0]
	v_pk_fma_f32 v[238:239], v[102:103], v[238:239], v[22:23] op_sel_hi:[0,1,1] neg_lo:[0,0,1] neg_hi:[1,0,1]
	v_pk_mul_f32 v[22:23], v[134:135], v[62:63] op_sel:[1,1] op_sel_hi:[1,0]
	v_pk_fma_f32 v[62:63], v[134:135], v[62:63], v[22:23] op_sel_hi:[0,1,1] neg_lo:[0,0,1] neg_hi:[1,0,1]
	v_pk_add_f32 v[240:241], v[18:19], v[58:59]
	v_pk_add_f32 v[58:59], v[18:19], v[58:59] neg_lo:[0,1] neg_hi:[0,1]
	v_pk_mul_f32 v[18:19], v[104:105], v[240:241] op_sel:[1,1] op_sel_hi:[1,0]
	v_pk_fma_f32 v[240:241], v[104:105], v[240:241], v[18:19] op_sel_hi:[0,1,1] neg_lo:[0,0,1] neg_hi:[1,0,1]
	v_pk_mul_f32 v[18:19], v[136:137], v[58:59] op_sel:[1,1] op_sel_hi:[1,0]
	v_pk_fma_f32 v[58:59], v[136:137], v[58:59], v[18:19] op_sel_hi:[0,1,1] neg_lo:[0,0,1] neg_hi:[1,0,1]
	v_pk_add_f32 v[244:245], v[20:21], v[60:61]
	v_pk_add_f32 v[60:61], v[20:21], v[60:61] neg_lo:[0,1] neg_hi:[0,1]
	v_pk_mul_f32 v[20:21], v[106:107], v[244:245] op_sel:[1,1] op_sel_hi:[1,0]
	v_pk_fma_f32 v[244:245], v[106:107], v[244:245], v[20:21] op_sel_hi:[0,1,1] neg_lo:[0,0,1] neg_hi:[1,0,1]
	v_pk_mul_f32 v[20:21], v[138:139], v[60:61] op_sel:[1,1] op_sel_hi:[1,0]
	v_pk_fma_f32 v[60:61], v[138:139], v[60:61], v[20:21] op_sel_hi:[0,1,1] neg_lo:[0,0,1] neg_hi:[1,0,1]
	v_pk_add_f32 v[246:247], v[24:25], v[64:65]
	v_pk_add_f32 v[64:65], v[24:25], v[64:65] neg_lo:[0,1] neg_hi:[0,1]
	v_pk_mul_f32 v[24:25], v[108:109], v[246:247] op_sel:[1,1] op_sel_hi:[1,0]
	v_pk_fma_f32 v[246:247], v[108:109], v[246:247], v[24:25] op_sel_hi:[0,1,1] neg_lo:[0,0,1] neg_hi:[1,0,1]
	v_pk_mul_f32 v[24:25], v[140:141], v[64:65] op_sel:[1,1] op_sel_hi:[1,0]
	v_pk_fma_f32 v[64:65], v[140:141], v[64:65], v[24:25] op_sel_hi:[0,1,1] neg_lo:[0,0,1] neg_hi:[1,0,1]
	ds_write2st64_b64 v154, v[202:203], v[46:47] offset0:0 offset1:64
	ds_write2st64_b64 v154, v[204:205], v[42:43] offset0:4 offset1:68
	ds_write2st64_b64 v154, v[206:207], v[44:45] offset0:8 offset1:72
	ds_write2st64_b64 v154, v[208:209], v[48:49] offset0:12 offset1:76
	ds_write2st64_b64 v154, v[210:211], v[14:15] offset0:16 offset1:80
	ds_write2st64_b64 v154, v[212:213], v[10:11] offset0:20 offset1:84
	ds_write2st64_b64 v154, v[220:221], v[12:13] offset0:24 offset1:88
	ds_write2st64_b64 v154, v[224:225], v[16:17] offset0:28 offset1:92
	ds_write2st64_b64 v154, v[226:227], v[30:31] offset0:32 offset1:96
	ds_write2st64_b64 v154, v[230:231], v[26:27] offset0:36 offset1:100
	ds_write2st64_b64 v154, v[232:233], v[28:29] offset0:40 offset1:104
	ds_write2st64_b64 v154, v[236:237], v[32:33] offset0:44 offset1:108
	ds_write2st64_b64 v154, v[238:239], v[62:63] offset0:48 offset1:112
	ds_write2st64_b64 v154, v[240:241], v[58:59] offset0:52 offset1:116
	ds_write2st64_b64 v154, v[244:245], v[60:61] offset0:56 offset1:120
	ds_write2st64_b64 v154, v[246:247], v[64:65] offset0:60 offset1:124
	v_bfe_i32 v166, v0, 5, 1
	v_bfe_i32 v168, v0, 6, 1
	v_and_b32_e32 v166, 5, v166
	v_and_b32_e32 v168, 26, v168
	v_xor_b32_e32 v166, v166, v168
	v_xor_b32_e32 v166, v166, v0
	v_lshlrev_b32_e32 v154, 3, v166
	s_waitcnt lgkmcnt(0)
	s_barrier
; DI f32x2 cmul(f32x2 a, f32x2 b) { return mkf2(a.x * b.x - a.y * b.y, a.x * b.y + a.y * b.x); }
; DI void fft8192(f32x2* buf, const f32x2* __restrict__ tw) {
;     ...
;     __syncthreads();
; #pragma unroll
;     for (int e = 0; e < 8; ++e) {
;       const int i = tid + 256 * e;
;       const int pi = SW(i);
;       a[e] = buf[pi]; b[e] = buf[pi + 2048]; c[e] = buf[pi + 4096]; d[e] = buf[pi + 6144];
;     }
;     __syncthreads();
; #pragma unroll
;     for (int e = 0; e < 8; ++e) {
;       const int i = tid + 256 * e;
;       const int q = i & (s - 1);
;       const int ps = i - q;
;       const float rev = (float)ps * (1.f / 8192.f);
;       const f32x2 w1 = mkf2(__builtin_amdgcn_cosf(rev), -__builtin_amdgcn_sinf(rev));
;       const f32x2 w2 = cmul(w1, w1), w3 = cmul(w1, w2);
;       const f32x2 apc = mkf2(a[e].x + c[e].x, a[e].y + c[e].y), amc = mkf2(a[e].x - c[e].x, a[e].y - c[e].y);
;       const f32x2 bpd = mkf2(b[e].x + d[e].x, b[e].y + d[e].y), bmd = mkf2(b[e].x - d[e].x, b[e].y - d[e].y);
;       const int o = 4 * i - 3 * q;
;       buf[SW(o)] = mkf2(apc.x + bpd.x, apc.y + bpd.y);
;       buf[SW(o + s)] = cmul(w1, mkf2(amc.x + bmd.y, amc.y - bmd.x));
;       buf[SW(o + 2 * s)] = cmul(w2, mkf2(apc.x - bpd.x, apc.y - bpd.y));
;       buf[SW(o + 3 * s)] = cmul(w3, mkf2(amc.x - bmd.y, amc.y + bmd.x));
;     }
	ds_read2st64_b64 v[2:5], v154 offset0:0 offset1:32
	ds_read2st64_b64 v[6:9], v154 offset0:64 offset1:96
	ds_read2st64_b64 v[10:13], v154 offset0:4 offset1:36
	ds_read2st64_b64 v[14:17], v154 offset0:68 offset1:100
	ds_read2st64_b64 v[18:21], v154 offset0:8 offset1:40
	ds_read2st64_b64 v[22:25], v154 offset0:72 offset1:104
	ds_read2st64_b64 v[26:29], v154 offset0:12 offset1:44
	ds_read2st64_b64 v[30:33], v154 offset0:76 offset1:108
	ds_read2st64_b64 v[34:37], v154 offset0:16 offset1:48
	ds_read2st64_b64 v[38:41], v154 offset0:80 offset1:112
	ds_read2st64_b64 v[42:45], v154 offset0:20 offset1:52
	ds_read2st64_b64 v[46:49], v154 offset0:84 offset1:116
	ds_read2st64_b64 v[50:53], v154 offset0:24 offset1:56
	ds_read2st64_b64 v[54:57], v154 offset0:88 offset1:120
	ds_read2st64_b64 v[58:61], v154 offset0:28 offset1:60
	ds_read2st64_b64 v[62:65], v154 offset0:92 offset1:124
	v_cvt_f32_u32_e32 v201, v0
	v_lshlrev_b32_e32 v164, 4, v0
	v_bfe_i32 v166, v164, 5, 1
	v_bfe_i32 v168, v164, 6, 1
	v_and_b32_e32 v166, 5, v166
	v_and_b32_e32 v168, 26, v168
	v_xor_b32_e32 v166, v166, v168
	v_xor_b32_e32 v166, v166, v164
	v_lshlrev_b32_e32 v164, 3, v166
	v_mul_f32_e32 v201, 0x39000000, v201
	v_cos_f32_e32 v210, v201
	v_sin_f32_e64 v211, -v201
	s_waitcnt lgkmcnt(14)
	v_pk_add_f32 v[202:203], v[2:3], v[6:7]
	v_pk_add_f32 v[2:3], v[2:3], v[6:7] neg_lo:[0,1] neg_hi:[0,1]
	v_pk_add_f32 v[204:205], v[4:5], v[8:9]
	v_pk_add_f32 v[4:5], v[4:5], v[8:9] neg_lo:[0,1] neg_hi:[0,1]
	v_pk_add_f32 v[6:7], v[202:203], v[204:205]
	v_pk_add_f32 v[8:9], v[202:203], v[204:205] neg_lo:[0,1] neg_hi:[0,1]
	v_pk_add_f32 v[202:203], v[2:3], v[4:5] op_sel:[0,1] op_sel_hi:[1,0] neg_hi:[0,1]
	v_pk_add_f32 v[204:205], v[2:3], v[4:5] op_sel:[0,1] op_sel_hi:[1,0] neg_lo:[0,1]
	v_pk_mul_f32 v[206:207], v[210:211], v[210:211] op_sel:[1,1] op_sel_hi:[1,0]
	v_pk_fma_f32 v[212:213], v[210:211], v[210:211], v[206:207] op_sel_hi:[0,1,1] neg_lo:[0,0,1]
	v_pk_mul_f32 v[206:207], v[210:211], v[212:213] op_sel:[1,1] op_sel_hi:[1,0]
	v_pk_fma_f32 v[220:221], v[210:211], v[212:213], v[206:207] op_sel_hi:[0,1,1] neg_lo:[0,0,1]
	v_pk_mul_f32 v[2:3], v[210:211], v[202:203] op_sel:[1,1] op_sel_hi:[1,0]
	v_pk_fma_f32 v[2:3], v[210:211], v[202:203], v[2:3] op_sel_hi:[0,1,1] neg_lo:[0,0,1]
	v_pk_mul_f32 v[4:5], v[212:213], v[8:9] op_sel:[1,1] op_sel_hi:[1,0]
	v_pk_fma_f32 v[4:5], v[212:213], v[8:9], v[4:5] op_sel_hi:[0,1,1] neg_lo:[0,0,1]
	v_pk_mul_f32 v[8:9], v[220:221], v[204:205] op_sel:[1,1] op_sel_hi:[1,0]
	v_pk_fma_f32 v[8:9], v[220:221], v[204:205], v[8:9] op_sel_hi:[0,1,1] neg_lo:[0,0,1]
	v_add_f32_e32 v214, 0x3d000000, v201
	v_cos_f32_e32 v210, v214
	v_sin_f32_e64 v211, -v214
	s_waitcnt lgkmcnt(12)
	v_pk_add_f32 v[202:203], v[10:11], v[14:15]
	v_pk_add_f32 v[10:11], v[10:11], v[14:15] neg_lo:[0,1] neg_hi:[0,1]
	v_pk_add_f32 v[204:205], v[12:13], v[16:17]
	v_pk_add_f32 v[12:13], v[12:13], v[16:17] neg_lo:[0,1] neg_hi:[0,1]
	v_pk_add_f32 v[14:15], v[202:203], v[204:205]
	v_pk_add_f32 v[16:17], v[202:203], v[204:205] neg_lo:[0,1] neg_hi:[0,1]
	v_pk_add_f32 v[202:203], v[10:11], v[12:13] op_sel:[0,1] op_sel_hi:[1,0] neg_hi:[0,1]
	v_pk_add_f32 v[204:205], v[10:11], v[12:13] op_sel:[0,1] op_sel_hi:[1,0] neg_lo:[0,1]
	v_pk_mul_f32 v[206:207], v[210:211], v[210:211] op_sel:[1,1] op_sel_hi:[1,0]
	v_pk_fma_f32 v[212:213], v[210:211], v[210:211], v[206:207] op_sel_hi:[0,1,1] neg_lo:[0,0,1]
	v_pk_mul_f32 v[206:207], v[210:211], v[212:213] op_sel:[1,1] op_sel_hi:[1,0]
	v_pk_fma_f32 v[220:221], v[210:211], v[212:213], v[206:207] op_sel_hi:[0,1,1] neg_lo:[0,0,1]
	v_pk_mul_f32 v[10:11], v[210:211], v[202:203] op_sel:[1,1] op_sel_hi:[1,0]
	v_pk_fma_f32 v[10:11], v[210:211], v[202:203], v[10:11] op_sel_hi:[0,1,1] neg_lo:[0,0,1]
	v_pk_mul_f32 v[12:13], v[212:213], v[16:17] op_sel:[1,1] op_sel_hi:[1,0]
	v_pk_fma_f32 v[12:13], v[212:213], v[16:17], v[12:13] op_sel_hi:[0,1,1] neg_lo:[0,0,1]
	v_pk_mul_f32 v[16:17], v[220:221], v[204:205] op_sel:[1,1] op_sel_hi:[1,0]
	v_pk_fma_f32 v[16:17], v[220:221], v[204:205], v[16:17] op_sel_hi:[0,1,1] neg_lo:[0,0,1]
	v_add_f32_e32 v214, 0x3d800000, v201
	v_cos_f32_e32 v210, v214
	v_sin_f32_e64 v211, -v214
	s_waitcnt lgkmcnt(10)
	v_pk_add_f32 v[202:203], v[18:19], v[22:23]
	v_pk_add_f32 v[18:19], v[18:19], v[22:23] neg_lo:[0,1] neg_hi:[0,1]
	v_pk_add_f32 v[204:205], v[20:21], v[24:25]
	v_pk_add_f32 v[20:21], v[20:21], v[24:25] neg_lo:[0,1] neg_hi:[0,1]
	v_pk_add_f32 v[22:23], v[202:203], v[204:205]
	v_pk_add_f32 v[24:25], v[202:203], v[204:205] neg_lo:[0,1] neg_hi:[0,1]
	v_pk_add_f32 v[202:203], v[18:19], v[20:21] op_sel:[0,1] op_sel_hi:[1,0] neg_hi:[0,1]
	v_pk_add_f32 v[204:205], v[18:19], v[20:21] op_sel:[0,1] op_sel_hi:[1,0] neg_lo:[0,1]
	v_pk_mul_f32 v[206:207], v[210:211], v[210:211] op_sel:[1,1] op_sel_hi:[1,0]
	v_pk_fma_f32 v[212:213], v[210:211], v[210:211], v[206:207] op_sel_hi:[0,1,1] neg_lo:[0,0,1]
	v_pk_mul_f32 v[206:207], v[210:211], v[212:213] op_sel:[1,1] op_sel_hi:[1,0]
	v_pk_fma_f32 v[220:221], v[210:211], v[212:213], v[206:207] op_sel_hi:[0,1,1] neg_lo:[0,0,1]
	v_pk_mul_f32 v[18:19], v[210:211], v[202:203] op_sel:[1,1] op_sel_hi:[1,0]
	v_pk_fma_f32 v[18:19], v[210:211], v[202:203], v[18:19] op_sel_hi:[0,1,1] neg_lo:[0,0,1]
	v_pk_mul_f32 v[20:21], v[212:213], v[24:25] op_sel:[1,1] op_sel_hi:[1,0]
	v_pk_fma_f32 v[20:21], v[212:213], v[24:25], v[20:21] op_sel_hi:[0,1,1] neg_lo:[0,0,1]
	v_pk_mul_f32 v[24:25], v[220:221], v[204:205] op_sel:[1,1] op_sel_hi:[1,0]
	v_pk_fma_f32 v[24:25], v[220:221], v[204:205], v[24:25] op_sel_hi:[0,1,1] neg_lo:[0,0,1]
	v_add_f32_e32 v214, 0x3dc00000, v201
	v_cos_f32_e32 v210, v214
	v_sin_f32_e64 v211, -v214
	s_waitcnt lgkmcnt(8)
; DI f32x2 cmul(f32x2 a, f32x2 b) { return mkf2(a.x * b.x - a.y * b.y, a.x * b.y + a.y * b.x); }
; DI void fft8192(f32x2* buf, const f32x2* __restrict__ tw) {
;     ...
; #pragma unroll
;     for (int e = 0; e < 8; ++e) {
;       const int i = tid + 256 * e;
;       const int q = i & (s - 1);
;       const int ps = i - q;
;       const float rev = (float)ps * (1.f / 8192.f);
;       const f32x2 w1 = mkf2(__builtin_amdgcn_cosf(rev), -__builtin_amdgcn_sinf(rev));
;       const f32x2 w2 = cmul(w1, w1), w3 = cmul(w1, w2);
;       const f32x2 apc = mkf2(a[e].x + c[e].x, a[e].y + c[e].y), amc = mkf2(a[e].x - c[e].x, a[e].y - c[e].y);
;       const f32x2 bpd = mkf2(b[e].x + d[e].x, b[e].y + d[e].y), bmd = mkf2(b[e].x - d[e].x, b[e].y - d[e].y);
;       const int o = 4 * i - 3 * q;
;       buf[SW(o)] = mkf2(apc.x + bpd.x, apc.y + bpd.y);
;       buf[SW(o + s)] = cmul(w1, mkf2(amc.x + bmd.y, amc.y - bmd.x));
;       buf[SW(o + 2 * s)] = cmul(w2, mkf2(apc.x - bpd.x, apc.y - bpd.y));
;       buf[SW(o + 3 * s)] = cmul(w3, mkf2(amc.x - bmd.y, amc.y + bmd.x));
;     }
	v_pk_add_f32 v[202:203], v[26:27], v[30:31]
	v_pk_add_f32 v[26:27], v[26:27], v[30:31] neg_lo:[0,1] neg_hi:[0,1]
	v_pk_add_f32 v[204:205], v[28:29], v[32:33]
	v_pk_add_f32 v[28:29], v[28:29], v[32:33] neg_lo:[0,1] neg_hi:[0,1]
	v_pk_add_f32 v[30:31], v[202:203], v[204:205]
	v_pk_add_f32 v[32:33], v[202:203], v[204:205] neg_lo:[0,1] neg_hi:[0,1]
	v_pk_add_f32 v[202:203], v[26:27], v[28:29] op_sel:[0,1] op_sel_hi:[1,0] neg_hi:[0,1]
	v_pk_add_f32 v[204:205], v[26:27], v[28:29] op_sel:[0,1] op_sel_hi:[1,0] neg_lo:[0,1]
	v_pk_mul_f32 v[206:207], v[210:211], v[210:211] op_sel:[1,1] op_sel_hi:[1,0]
	v_pk_fma_f32 v[212:213], v[210:211], v[210:211], v[206:207] op_sel_hi:[0,1,1] neg_lo:[0,0,1]
	v_pk_mul_f32 v[206:207], v[210:211], v[212:213] op_sel:[1,1] op_sel_hi:[1,0]
	v_pk_fma_f32 v[220:221], v[210:211], v[212:213], v[206:207] op_sel_hi:[0,1,1] neg_lo:[0,0,1]
	v_pk_mul_f32 v[26:27], v[210:211], v[202:203] op_sel:[1,1] op_sel_hi:[1,0]
	v_pk_fma_f32 v[26:27], v[210:211], v[202:203], v[26:27] op_sel_hi:[0,1,1] neg_lo:[0,0,1]
	v_pk_mul_f32 v[28:29], v[212:213], v[32:33] op_sel:[1,1] op_sel_hi:[1,0]
	v_pk_fma_f32 v[28:29], v[212:213], v[32:33], v[28:29] op_sel_hi:[0,1,1] neg_lo:[0,0,1]
	v_pk_mul_f32 v[32:33], v[220:221], v[204:205] op_sel:[1,1] op_sel_hi:[1,0]
	v_pk_fma_f32 v[32:33], v[220:221], v[204:205], v[32:33] op_sel_hi:[0,1,1] neg_lo:[0,0,1]
	v_add_f32_e32 v214, 0x3e000000, v201
	v_cos_f32_e32 v210, v214
	v_sin_f32_e64 v211, -v214
	s_waitcnt lgkmcnt(6)
	v_pk_add_f32 v[202:203], v[34:35], v[38:39]
	v_pk_add_f32 v[34:35], v[34:35], v[38:39] neg_lo:[0,1] neg_hi:[0,1]
	v_pk_add_f32 v[204:205], v[36:37], v[40:41]
	v_pk_add_f32 v[36:37], v[36:37], v[40:41] neg_lo:[0,1] neg_hi:[0,1]
	v_pk_add_f32 v[38:39], v[202:203], v[204:205]
	v_pk_add_f32 v[40:41], v[202:203], v[204:205] neg_lo:[0,1] neg_hi:[0,1]
	v_pk_add_f32 v[202:203], v[34:35], v[36:37] op_sel:[0,1] op_sel_hi:[1,0] neg_hi:[0,1]
	v_pk_add_f32 v[204:205], v[34:35], v[36:37] op_sel:[0,1] op_sel_hi:[1,0] neg_lo:[0,1]
	v_pk_mul_f32 v[206:207], v[210:211], v[210:211] op_sel:[1,1] op_sel_hi:[1,0]
	v_pk_fma_f32 v[212:213], v[210:211], v[210:211], v[206:207] op_sel_hi:[0,1,1] neg_lo:[0,0,1]
	v_pk_mul_f32 v[206:207], v[210:211], v[212:213] op_sel:[1,1] op_sel_hi:[1,0]
	v_pk_fma_f32 v[220:221], v[210:211], v[212:213], v[206:207] op_sel_hi:[0,1,1] neg_lo:[0,0,1]
	v_pk_mul_f32 v[34:35], v[210:211], v[202:203] op_sel:[1,1] op_sel_hi:[1,0]
	v_pk_fma_f32 v[34:35], v[210:211], v[202:203], v[34:35] op_sel_hi:[0,1,1] neg_lo:[0,0,1]
	v_pk_mul_f32 v[36:37], v[212:213], v[40:41] op_sel:[1,1] op_sel_hi:[1,0]
	v_pk_fma_f32 v[36:37], v[212:213], v[40:41], v[36:37] op_sel_hi:[0,1,1] neg_lo:[0,0,1]
	v_pk_mul_f32 v[40:41], v[220:221], v[204:205] op_sel:[1,1] op_sel_hi:[1,0]
	v_pk_fma_f32 v[40:41], v[220:221], v[204:205], v[40:41] op_sel_hi:[0,1,1] neg_lo:[0,0,1]
	v_add_f32_e32 v214, 0x3e200000, v201
	v_cos_f32_e32 v210, v214
	v_sin_f32_e64 v211, -v214
	s_waitcnt lgkmcnt(4)
	v_pk_add_f32 v[202:203], v[42:43], v[46:47]
	v_pk_add_f32 v[42:43], v[42:43], v[46:47] neg_lo:[0,1] neg_hi:[0,1]
	v_pk_add_f32 v[204:205], v[44:45], v[48:49]
	v_pk_add_f32 v[44:45], v[44:45], v[48:49] neg_lo:[0,1] neg_hi:[0,1]
	v_pk_add_f32 v[46:47], v[202:203], v[204:205]
	v_pk_add_f32 v[48:49], v[202:203], v[204:205] neg_lo:[0,1] neg_hi:[0,1]
	v_pk_add_f32 v[202:203], v[42:43], v[44:45] op_sel:[0,1] op_sel_hi:[1,0] neg_hi:[0,1]
	v_pk_add_f32 v[204:205], v[42:43], v[44:45] op_sel:[0,1] op_sel_hi:[1,0] neg_lo:[0,1]
	v_pk_mul_f32 v[206:207], v[210:211], v[210:211] op_sel:[1,1] op_sel_hi:[1,0]
	v_pk_fma_f32 v[212:213], v[210:211], v[210:211], v[206:207] op_sel_hi:[0,1,1] neg_lo:[0,0,1]
	v_pk_mul_f32 v[206:207], v[210:211], v[212:213] op_sel:[1,1] op_sel_hi:[1,0]
	v_pk_fma_f32 v[220:221], v[210:211], v[212:213], v[206:207] op_sel_hi:[0,1,1] neg_lo:[0,0,1]
	v_pk_mul_f32 v[42:43], v[210:211], v[202:203] op_sel:[1,1] op_sel_hi:[1,0]
	v_pk_fma_f32 v[42:43], v[210:211], v[202:203], v[42:43] op_sel_hi:[0,1,1] neg_lo:[0,0,1]
	v_pk_mul_f32 v[44:45], v[212:213], v[48:49] op_sel:[1,1] op_sel_hi:[1,0]
	v_pk_fma_f32 v[44:45], v[212:213], v[48:49], v[44:45] op_sel_hi:[0,1,1] neg_lo:[0,0,1]
	v_pk_mul_f32 v[48:49], v[220:221], v[204:205] op_sel:[1,1] op_sel_hi:[1,0]
	v_pk_fma_f32 v[48:49], v[220:221], v[204:205], v[48:49] op_sel_hi:[0,1,1] neg_lo:[0,0,1]
	v_add_f32_e32 v214, 0x3e400000, v201
	v_cos_f32_e32 v210, v214
	v_sin_f32_e64 v211, -v214
	s_waitcnt lgkmcnt(2)
	v_pk_add_f32 v[202:203], v[50:51], v[54:55]
	v_pk_add_f32 v[50:51], v[50:51], v[54:55] neg_lo:[0,1] neg_hi:[0,1]
	v_pk_add_f32 v[204:205], v[52:53], v[56:57]
	v_pk_add_f32 v[52:53], v[52:53], v[56:57] neg_lo:[0,1] neg_hi:[0,1]
	v_pk_add_f32 v[54:55], v[202:203], v[204:205]
	v_pk_add_f32 v[56:57], v[202:203], v[204:205] neg_lo:[0,1] neg_hi:[0,1]
	v_pk_add_f32 v[202:203], v[50:51], v[52:53] op_sel:[0,1] op_sel_hi:[1,0] neg_hi:[0,1]
	v_pk_add_f32 v[204:205], v[50:51], v[52:53] op_sel:[0,1] op_sel_hi:[1,0] neg_lo:[0,1]
	v_pk_mul_f32 v[206:207], v[210:211], v[210:211] op_sel:[1,1] op_sel_hi:[1,0]
	v_pk_fma_f32 v[212:213], v[210:211], v[210:211], v[206:207] op_sel_hi:[0,1,1] neg_lo:[0,0,1]
	v_pk_mul_f32 v[206:207], v[210:211], v[212:213] op_sel:[1,1] op_sel_hi:[1,0]
	v_pk_fma_f32 v[220:221], v[210:211], v[212:213], v[206:207] op_sel_hi:[0,1,1] neg_lo:[0,0,1]
	v_pk_mul_f32 v[50:51], v[210:211], v[202:203] op_sel:[1,1] op_sel_hi:[1,0]
	v_pk_fma_f32 v[50:51], v[210:211], v[202:203], v[50:51] op_sel_hi:[0,1,1] neg_lo:[0,0,1]
	v_pk_mul_f32 v[52:53], v[212:213], v[56:57] op_sel:[1,1] op_sel_hi:[1,0]
	v_pk_fma_f32 v[52:53], v[212:213], v[56:57], v[52:53] op_sel_hi:[0,1,1] neg_lo:[0,0,1]
	v_pk_mul_f32 v[56:57], v[220:221], v[204:205] op_sel:[1,1] op_sel_hi:[1,0]
	v_pk_fma_f32 v[56:57], v[220:221], v[204:205], v[56:57] op_sel_hi:[0,1,1] neg_lo:[0,0,1]
	v_add_f32_e32 v214, 0x3e600000, v201
	v_cos_f32_e32 v210, v214
	v_sin_f32_e64 v211, -v214
	s_waitcnt lgkmcnt(0)
; DI f32x2 cmul(f32x2 a, f32x2 b) { return mkf2(a.x * b.x - a.y * b.y, a.x * b.y + a.y * b.x); }
; DI void fft8192(f32x2* buf, const f32x2* __restrict__ tw) {
;     ...
; #pragma unroll
;     for (int e = 0; e < 8; ++e) {
;       const int i = tid + 256 * e;
;       const int q = i & (s - 1);
;       const int ps = i - q;
;       const float rev = (float)ps * (1.f / 8192.f);
;       const f32x2 w1 = mkf2(__builtin_amdgcn_cosf(rev), -__builtin_amdgcn_sinf(rev));
;       const f32x2 w2 = cmul(w1, w1), w3 = cmul(w1, w2);
;       const f32x2 apc = mkf2(a[e].x + c[e].x, a[e].y + c[e].y), amc = mkf2(a[e].x - c[e].x, a[e].y - c[e].y);
;       const f32x2 bpd = mkf2(b[e].x + d[e].x, b[e].y + d[e].y), bmd = mkf2(b[e].x - d[e].x, b[e].y - d[e].y);
;       const int o = 4 * i - 3 * q;
;       buf[SW(o)] = mkf2(apc.x + bpd.x, apc.y + bpd.y);
;       buf[SW(o + s)] = cmul(w1, mkf2(amc.x + bmd.y, amc.y - bmd.x));
;       buf[SW(o + 2 * s)] = cmul(w2, mkf2(apc.x - bpd.x, apc.y - bpd.y));
;       buf[SW(o + 3 * s)] = cmul(w3, mkf2(amc.x - bmd.y, amc.y + bmd.x));
;     }
	v_pk_add_f32 v[202:203], v[58:59], v[62:63]
	v_pk_add_f32 v[58:59], v[58:59], v[62:63] neg_lo:[0,1] neg_hi:[0,1]
	v_pk_add_f32 v[204:205], v[60:61], v[64:65]
	v_pk_add_f32 v[60:61], v[60:61], v[64:65] neg_lo:[0,1] neg_hi:[0,1]
	v_pk_add_f32 v[62:63], v[202:203], v[204:205]
	v_pk_add_f32 v[64:65], v[202:203], v[204:205] neg_lo:[0,1] neg_hi:[0,1]
	v_pk_add_f32 v[202:203], v[58:59], v[60:61] op_sel:[0,1] op_sel_hi:[1,0] neg_hi:[0,1]
	v_pk_add_f32 v[204:205], v[58:59], v[60:61] op_sel:[0,1] op_sel_hi:[1,0] neg_lo:[0,1]
	v_pk_mul_f32 v[206:207], v[210:211], v[210:211] op_sel:[1,1] op_sel_hi:[1,0]
	v_pk_fma_f32 v[212:213], v[210:211], v[210:211], v[206:207] op_sel_hi:[0,1,1] neg_lo:[0,0,1]
	v_pk_mul_f32 v[206:207], v[210:211], v[212:213] op_sel:[1,1] op_sel_hi:[1,0]
	v_pk_fma_f32 v[220:221], v[210:211], v[212:213], v[206:207] op_sel_hi:[0,1,1] neg_lo:[0,0,1]
	v_pk_mul_f32 v[58:59], v[210:211], v[202:203] op_sel:[1,1] op_sel_hi:[1,0]
	v_pk_fma_f32 v[58:59], v[210:211], v[202:203], v[58:59] op_sel_hi:[0,1,1] neg_lo:[0,0,1]
	v_pk_mul_f32 v[60:61], v[212:213], v[64:65] op_sel:[1,1] op_sel_hi:[1,0]
	v_pk_fma_f32 v[60:61], v[212:213], v[64:65], v[60:61] op_sel_hi:[0,1,1] neg_lo:[0,0,1]
	v_pk_mul_f32 v[64:65], v[220:221], v[204:205] op_sel:[1,1] op_sel_hi:[1,0]
	v_pk_fma_f32 v[64:65], v[220:221], v[204:205], v[64:65] op_sel_hi:[0,1,1] neg_lo:[0,0,1]
	s_barrier
	v_mul_f32_e32 v214, 4.0, v201
	v_cos_f32_e32 v224, v214
	v_sin_f32_e64 v225, -v214
	s_nop 0
	v_pk_mul_f32 v[206:207], v[224:225], v[224:225] op_sel:[1,1] op_sel_hi:[1,0]
	v_pk_fma_f32 v[226:227], v[224:225], v[224:225], v[206:207] op_sel_hi:[0,1,1] neg_lo:[0,0,1]
	v_pk_mul_f32 v[206:207], v[224:225], v[226:227] op_sel:[1,1] op_sel_hi:[1,0]
	v_pk_fma_f32 v[230:231], v[224:225], v[226:227], v[206:207] op_sel_hi:[0,1,1] neg_lo:[0,0,1]
	v_pk_add_f32 v[202:203], v[6:7], v[38:39]
	v_pk_add_f32 v[6:7], v[6:7], v[38:39] neg_lo:[0,1] neg_hi:[0,1]
	v_pk_add_f32 v[204:205], v[22:23], v[54:55]
	v_pk_add_f32 v[22:23], v[22:23], v[54:55] neg_lo:[0,1] neg_hi:[0,1]
	v_pk_add_f32 v[38:39], v[202:203], v[204:205]
	v_pk_add_f32 v[54:55], v[202:203], v[204:205] neg_lo:[0,1] neg_hi:[0,1]
	v_pk_add_f32 v[202:203], v[6:7], v[22:23] op_sel:[0,1] op_sel_hi:[1,0] neg_hi:[0,1]
	v_pk_add_f32 v[204:205], v[6:7], v[22:23] op_sel:[0,1] op_sel_hi:[1,0] neg_lo:[0,1]
	v_pk_mul_f32 v[6:7], v[224:225], v[202:203] op_sel:[1,1] op_sel_hi:[1,0]
	v_pk_fma_f32 v[6:7], v[224:225], v[202:203], v[6:7] op_sel_hi:[0,1,1] neg_lo:[0,0,1]
	v_pk_mul_f32 v[22:23], v[226:227], v[54:55] op_sel:[1,1] op_sel_hi:[1,0]
	v_pk_fma_f32 v[22:23], v[226:227], v[54:55], v[22:23] op_sel_hi:[0,1,1] neg_lo:[0,0,1]
	v_pk_mul_f32 v[54:55], v[230:231], v[204:205] op_sel:[1,1] op_sel_hi:[1,0]
	v_pk_fma_f32 v[54:55], v[230:231], v[204:205], v[54:55] op_sel_hi:[0,1,1] neg_lo:[0,0,1]
	v_pk_add_f32 v[202:203], v[2:3], v[34:35]
	v_pk_add_f32 v[2:3], v[2:3], v[34:35] neg_lo:[0,1] neg_hi:[0,1]
	v_pk_add_f32 v[204:205], v[18:19], v[50:51]
	v_pk_add_f32 v[18:19], v[18:19], v[50:51] neg_lo:[0,1] neg_hi:[0,1]
	v_pk_add_f32 v[34:35], v[202:203], v[204:205]
	v_pk_add_f32 v[50:51], v[202:203], v[204:205] neg_lo:[0,1] neg_hi:[0,1]
	v_pk_add_f32 v[202:203], v[2:3], v[18:19] op_sel:[0,1] op_sel_hi:[1,0] neg_hi:[0,1]
	v_pk_add_f32 v[204:205], v[2:3], v[18:19] op_sel:[0,1] op_sel_hi:[1,0] neg_lo:[0,1]
	v_pk_mul_f32 v[2:3], v[224:225], v[202:203] op_sel:[1,1] op_sel_hi:[1,0]
	v_pk_fma_f32 v[2:3], v[224:225], v[202:203], v[2:3] op_sel_hi:[0,1,1] neg_lo:[0,0,1]
	v_pk_mul_f32 v[18:19], v[226:227], v[50:51] op_sel:[1,1] op_sel_hi:[1,0]
	v_pk_fma_f32 v[18:19], v[226:227], v[50:51], v[18:19] op_sel_hi:[0,1,1] neg_lo:[0,0,1]
	v_pk_mul_f32 v[50:51], v[230:231], v[204:205] op_sel:[1,1] op_sel_hi:[1,0]
	v_pk_fma_f32 v[50:51], v[230:231], v[204:205], v[50:51] op_sel_hi:[0,1,1] neg_lo:[0,0,1]
	v_pk_add_f32 v[202:203], v[4:5], v[36:37]
	v_pk_add_f32 v[4:5], v[4:5], v[36:37] neg_lo:[0,1] neg_hi:[0,1]
	v_pk_add_f32 v[204:205], v[20:21], v[52:53]
	v_pk_add_f32 v[20:21], v[20:21], v[52:53] neg_lo:[0,1] neg_hi:[0,1]
	v_pk_add_f32 v[36:37], v[202:203], v[204:205]
	v_pk_add_f32 v[52:53], v[202:203], v[204:205] neg_lo:[0,1] neg_hi:[0,1]
	v_pk_add_f32 v[202:203], v[4:5], v[20:21] op_sel:[0,1] op_sel_hi:[1,0] neg_hi:[0,1]
	v_pk_add_f32 v[204:205], v[4:5], v[20:21] op_sel:[0,1] op_sel_hi:[1,0] neg_lo:[0,1]
	v_pk_mul_f32 v[4:5], v[224:225], v[202:203] op_sel:[1,1] op_sel_hi:[1,0]
	v_pk_fma_f32 v[4:5], v[224:225], v[202:203], v[4:5] op_sel_hi:[0,1,1] neg_lo:[0,0,1]
	v_pk_mul_f32 v[20:21], v[226:227], v[52:53] op_sel:[1,1] op_sel_hi:[1,0]
	v_pk_fma_f32 v[20:21], v[226:227], v[52:53], v[20:21] op_sel_hi:[0,1,1] neg_lo:[0,0,1]
	v_pk_mul_f32 v[52:53], v[230:231], v[204:205] op_sel:[1,1] op_sel_hi:[1,0]
	v_pk_fma_f32 v[52:53], v[230:231], v[204:205], v[52:53] op_sel_hi:[0,1,1] neg_lo:[0,0,1]
	v_pk_add_f32 v[202:203], v[8:9], v[40:41]
	v_pk_add_f32 v[8:9], v[8:9], v[40:41] neg_lo:[0,1] neg_hi:[0,1]
	v_pk_add_f32 v[204:205], v[24:25], v[56:57]
	v_pk_add_f32 v[24:25], v[24:25], v[56:57] neg_lo:[0,1] neg_hi:[0,1]
	v_pk_add_f32 v[40:41], v[202:203], v[204:205]
	v_pk_add_f32 v[56:57], v[202:203], v[204:205] neg_lo:[0,1] neg_hi:[0,1]
	v_pk_add_f32 v[202:203], v[8:9], v[24:25] op_sel:[0,1] op_sel_hi:[1,0] neg_hi:[0,1]
	v_pk_add_f32 v[204:205], v[8:9], v[24:25] op_sel:[0,1] op_sel_hi:[1,0] neg_lo:[0,1]
	v_pk_mul_f32 v[8:9], v[224:225], v[202:203] op_sel:[1,1] op_sel_hi:[1,0]
	v_pk_fma_f32 v[8:9], v[224:225], v[202:203], v[8:9] op_sel_hi:[0,1,1] neg_lo:[0,0,1]
	v_pk_mul_f32 v[24:25], v[226:227], v[56:57] op_sel:[1,1] op_sel_hi:[1,0]
	v_pk_fma_f32 v[24:25], v[226:227], v[56:57], v[24:25] op_sel_hi:[0,1,1] neg_lo:[0,0,1]
; DI f32x2 cmul(f32x2 a, f32x2 b) { return mkf2(a.x * b.x - a.y * b.y, a.x * b.y + a.y * b.x); }
; DI void fft8192(f32x2* buf, const f32x2* __restrict__ tw) {
;     ...
; #pragma unroll
;     for (int e = 0; e < 8; ++e) {
;       const int i = tid + 256 * e;
;       const int q = i & (s - 1);
;       const int ps = i - q;
;       const float rev = (float)ps * (1.f / 8192.f);
;       const f32x2 w1 = mkf2(__builtin_amdgcn_cosf(rev), -__builtin_amdgcn_sinf(rev));
;       const f32x2 w2 = cmul(w1, w1), w3 = cmul(w1, w2);
;       const f32x2 apc = mkf2(a[e].x + c[e].x, a[e].y + c[e].y), amc = mkf2(a[e].x - c[e].x, a[e].y - c[e].y);
;       const f32x2 bpd = mkf2(b[e].x + d[e].x, b[e].y + d[e].y), bmd = mkf2(b[e].x - d[e].x, b[e].y - d[e].y);
;       const int o = 4 * i - 3 * q;
;       buf[SW(o)] = mkf2(apc.x + bpd.x, apc.y + bpd.y);
;       buf[SW(o + s)] = cmul(w1, mkf2(amc.x + bmd.y, amc.y - bmd.x));
;       buf[SW(o + 2 * s)] = cmul(w2, mkf2(apc.x - bpd.x, apc.y - bpd.y));
;       buf[SW(o + 3 * s)] = cmul(w3, mkf2(amc.x - bmd.y, amc.y + bmd.x));
;     }
	v_pk_mul_f32 v[56:57], v[230:231], v[204:205] op_sel:[1,1] op_sel_hi:[1,0]
	v_pk_fma_f32 v[56:57], v[230:231], v[204:205], v[56:57] op_sel_hi:[0,1,1] neg_lo:[0,0,1]
	v_mul_f32_e32 v214, 4.0, v201
	v_add_f32_e32 v214, 0x3e000000, v214
	v_cos_f32_e32 v224, v214
	v_sin_f32_e64 v225, -v214
	s_nop 0
	v_pk_mul_f32 v[206:207], v[224:225], v[224:225] op_sel:[1,1] op_sel_hi:[1,0]
	v_pk_fma_f32 v[226:227], v[224:225], v[224:225], v[206:207] op_sel_hi:[0,1,1] neg_lo:[0,0,1]
	v_pk_mul_f32 v[206:207], v[224:225], v[226:227] op_sel:[1,1] op_sel_hi:[1,0]
	v_pk_fma_f32 v[230:231], v[224:225], v[226:227], v[206:207] op_sel_hi:[0,1,1] neg_lo:[0,0,1]
	v_pk_add_f32 v[202:203], v[14:15], v[46:47]
	v_pk_add_f32 v[14:15], v[14:15], v[46:47] neg_lo:[0,1] neg_hi:[0,1]
	v_pk_add_f32 v[204:205], v[30:31], v[62:63]
	v_pk_add_f32 v[30:31], v[30:31], v[62:63] neg_lo:[0,1] neg_hi:[0,1]
	v_pk_add_f32 v[46:47], v[202:203], v[204:205]
	v_pk_add_f32 v[62:63], v[202:203], v[204:205] neg_lo:[0,1] neg_hi:[0,1]
	v_pk_add_f32 v[202:203], v[14:15], v[30:31] op_sel:[0,1] op_sel_hi:[1,0] neg_hi:[0,1]
	v_pk_add_f32 v[204:205], v[14:15], v[30:31] op_sel:[0,1] op_sel_hi:[1,0] neg_lo:[0,1]
	v_pk_mul_f32 v[14:15], v[224:225], v[202:203] op_sel:[1,1] op_sel_hi:[1,0]
	v_pk_fma_f32 v[14:15], v[224:225], v[202:203], v[14:15] op_sel_hi:[0,1,1] neg_lo:[0,0,1]
	v_pk_mul_f32 v[30:31], v[226:227], v[62:63] op_sel:[1,1] op_sel_hi:[1,0]
	v_pk_fma_f32 v[30:31], v[226:227], v[62:63], v[30:31] op_sel_hi:[0,1,1] neg_lo:[0,0,1]
	v_pk_mul_f32 v[62:63], v[230:231], v[204:205] op_sel:[1,1] op_sel_hi:[1,0]
	v_pk_fma_f32 v[62:63], v[230:231], v[204:205], v[62:63] op_sel_hi:[0,1,1] neg_lo:[0,0,1]
	v_pk_add_f32 v[202:203], v[10:11], v[42:43]
	v_pk_add_f32 v[10:11], v[10:11], v[42:43] neg_lo:[0,1] neg_hi:[0,1]
	v_pk_add_f32 v[204:205], v[26:27], v[58:59]
	v_pk_add_f32 v[26:27], v[26:27], v[58:59] neg_lo:[0,1] neg_hi:[0,1]
	v_pk_add_f32 v[42:43], v[202:203], v[204:205]
	v_pk_add_f32 v[58:59], v[202:203], v[204:205] neg_lo:[0,1] neg_hi:[0,1]
	v_pk_add_f32 v[202:203], v[10:11], v[26:27] op_sel:[0,1] op_sel_hi:[1,0] neg_hi:[0,1]
	v_pk_add_f32 v[204:205], v[10:11], v[26:27] op_sel:[0,1] op_sel_hi:[1,0] neg_lo:[0,1]
	v_pk_mul_f32 v[10:11], v[224:225], v[202:203] op_sel:[1,1] op_sel_hi:[1,0]
	v_pk_fma_f32 v[10:11], v[224:225], v[202:203], v[10:11] op_sel_hi:[0,1,1] neg_lo:[0,0,1]
	v_pk_mul_f32 v[26:27], v[226:227], v[58:59] op_sel:[1,1] op_sel_hi:[1,0]
	v_pk_fma_f32 v[26:27], v[226:227], v[58:59], v[26:27] op_sel_hi:[0,1,1] neg_lo:[0,0,1]
	v_pk_mul_f32 v[58:59], v[230:231], v[204:205] op_sel:[1,1] op_sel_hi:[1,0]
	v_pk_fma_f32 v[58:59], v[230:231], v[204:205], v[58:59] op_sel_hi:[0,1,1] neg_lo:[0,0,1]
	v_pk_add_f32 v[202:203], v[12:13], v[44:45]
	v_pk_add_f32 v[12:13], v[12:13], v[44:45] neg_lo:[0,1] neg_hi:[0,1]
	v_pk_add_f32 v[204:205], v[28:29], v[60:61]
	v_pk_add_f32 v[28:29], v[28:29], v[60:61] neg_lo:[0,1] neg_hi:[0,1]
	v_pk_add_f32 v[44:45], v[202:203], v[204:205]
	v_pk_add_f32 v[60:61], v[202:203], v[204:205] neg_lo:[0,1] neg_hi:[0,1]
	v_pk_add_f32 v[202:203], v[12:13], v[28:29] op_sel:[0,1] op_sel_hi:[1,0] neg_hi:[0,1]
	v_pk_add_f32 v[204:205], v[12:13], v[28:29] op_sel:[0,1] op_sel_hi:[1,0] neg_lo:[0,1]
	v_pk_mul_f32 v[12:13], v[224:225], v[202:203] op_sel:[1,1] op_sel_hi:[1,0]
	v_pk_fma_f32 v[12:13], v[224:225], v[202:203], v[12:13] op_sel_hi:[0,1,1] neg_lo:[0,0,1]
	v_pk_mul_f32 v[28:29], v[226:227], v[60:61] op_sel:[1,1] op_sel_hi:[1,0]
	v_pk_fma_f32 v[28:29], v[226:227], v[60:61], v[28:29] op_sel_hi:[0,1,1] neg_lo:[0,0,1]
	v_pk_mul_f32 v[60:61], v[230:231], v[204:205] op_sel:[1,1] op_sel_hi:[1,0]
	v_pk_fma_f32 v[60:61], v[230:231], v[204:205], v[60:61] op_sel_hi:[0,1,1] neg_lo:[0,0,1]
	v_pk_add_f32 v[202:203], v[16:17], v[48:49]
	v_pk_add_f32 v[16:17], v[16:17], v[48:49] neg_lo:[0,1] neg_hi:[0,1]
	v_pk_add_f32 v[204:205], v[32:33], v[64:65]
	v_pk_add_f32 v[32:33], v[32:33], v[64:65] neg_lo:[0,1] neg_hi:[0,1]
	v_pk_add_f32 v[48:49], v[202:203], v[204:205]
	v_pk_add_f32 v[64:65], v[202:203], v[204:205] neg_lo:[0,1] neg_hi:[0,1]
	v_pk_add_f32 v[202:203], v[16:17], v[32:33] op_sel:[0,1] op_sel_hi:[1,0] neg_hi:[0,1]
	v_pk_add_f32 v[204:205], v[16:17], v[32:33] op_sel:[0,1] op_sel_hi:[1,0] neg_lo:[0,1]
	v_pk_mul_f32 v[16:17], v[224:225], v[202:203] op_sel:[1,1] op_sel_hi:[1,0]
	v_pk_fma_f32 v[16:17], v[224:225], v[202:203], v[16:17] op_sel_hi:[0,1,1] neg_lo:[0,0,1]
	v_pk_mul_f32 v[32:33], v[226:227], v[64:65] op_sel:[1,1] op_sel_hi:[1,0]
	v_pk_fma_f32 v[32:33], v[226:227], v[64:65], v[32:33] op_sel_hi:[0,1,1] neg_lo:[0,0,1]
	v_pk_mul_f32 v[64:65], v[230:231], v[204:205] op_sel:[1,1] op_sel_hi:[1,0]
	v_pk_fma_f32 v[64:65], v[230:231], v[204:205], v[64:65] op_sel_hi:[0,1,1] neg_lo:[0,0,1]
	ds_write_b64 v164, v[38:39] offset:0
	v_xor_b32_e32 v156, 8, v164
	ds_write_b64 v156, v[34:35] offset:0
	v_xor_b32_e32 v158, 16, v164
	ds_write_b64 v158, v[36:37] offset:0
	v_xor_b32_e32 v160, 24, v164
	ds_write_b64 v160, v[40:41] offset:0
	v_xor_b32_e32 v162, 32, v164
	ds_write_b64 v162, v[6:7] offset:0
	v_xor_b32_e32 v156, 40, v164
	ds_write_b64 v156, v[2:3] offset:0
	v_xor_b32_e32 v158, 48, v164
	ds_write_b64 v158, v[4:5] offset:0
	v_xor_b32_e32 v160, 56, v164
	ds_write_b64 v160, v[8:9] offset:0
	v_xor_b32_e32 v162, 64, v164
	ds_write_b64 v162, v[22:23] offset:0
	v_xor_b32_e32 v156, 0x48, v164
	ds_write_b64 v156, v[18:19] offset:0
	v_xor_b32_e32 v158, 0x50, v164
	ds_write_b64 v158, v[20:21] offset:0
	v_xor_b32_e32 v160, 0x58, v164
	ds_write_b64 v160, v[24:25] offset:0
	v_xor_b32_e32 v162, 0x60, v164
	ds_write_b64 v162, v[54:55] offset:0
	v_xor_b32_e32 v156, 0x68, v164
	ds_write_b64 v156, v[50:51] offset:0
	v_xor_b32_e32 v158, 0x70, v164
	ds_write_b64 v158, v[52:53] offset:0
	v_xor_b32_e32 v160, 0x78, v164
	ds_write_b64 v160, v[56:57] offset:0
	ds_write_b64 v164, v[46:47] offset:32768
	v_xor_b32_e32 v162, 8, v164
	ds_write_b64 v162, v[42:43] offset:32768
	v_xor_b32_e32 v156, 16, v164
	ds_write_b64 v156, v[44:45] offset:32768
	v_xor_b32_e32 v158, 24, v164
	ds_write_b64 v158, v[48:49] offset:32768
	v_xor_b32_e32 v160, 32, v164
	ds_write_b64 v160, v[14:15] offset:32768
	v_xor_b32_e32 v162, 40, v164
	ds_write_b64 v162, v[10:11] offset:32768
	v_xor_b32_e32 v156, 48, v164
	ds_write_b64 v156, v[12:13] offset:32768
	v_xor_b32_e32 v158, 56, v164
	ds_write_b64 v158, v[16:17] offset:32768
	v_xor_b32_e32 v160, 64, v164
	ds_write_b64 v160, v[30:31] offset:32768
	v_xor_b32_e32 v162, 0x48, v164
	ds_write_b64 v162, v[26:27] offset:32768
	v_xor_b32_e32 v156, 0x50, v164
	ds_write_b64 v156, v[28:29] offset:32768
	v_xor_b32_e32 v158, 0x58, v164
	ds_write_b64 v158, v[32:33] offset:32768
	v_xor_b32_e32 v160, 0x60, v164
	ds_write_b64 v160, v[62:63] offset:32768
	v_xor_b32_e32 v162, 0x68, v164
	ds_write_b64 v162, v[58:59] offset:32768
	v_xor_b32_e32 v156, 0x70, v164
	ds_write_b64 v156, v[60:61] offset:32768
	v_xor_b32_e32 v158, 0x78, v164
	ds_write_b64 v158, v[64:65] offset:32768
	s_waitcnt lgkmcnt(0)
	s_barrier
; DI f32x2 cmul(f32x2 a, f32x2 b) { return mkf2(a.x * b.x - a.y * b.y, a.x * b.y + a.y * b.x); }
; DI void fft8192(f32x2* buf, const f32x2* __restrict__ tw) {
;     ...
; #pragma unroll
;     for (int e = 0; e < 8; ++e) {
;       const int i = tid + 256 * e;
;       const int pi = SW(i);
;       a[e] = buf[pi]; b[e] = buf[pi + 2048]; c[e] = buf[pi + 4096]; d[e] = buf[pi + 6144];
;     }
;     __syncthreads();
; #pragma unroll
;     for (int e = 0; e < 8; ++e) {
;       const int i = tid + 256 * e;
;       const int q = i & (s - 1);
;       const int ps = i - q;
;       const float rev = (float)ps * (1.f / 8192.f);
;       const f32x2 w1 = mkf2(__builtin_amdgcn_cosf(rev), -__builtin_amdgcn_sinf(rev));
;       const f32x2 w2 = cmul(w1, w1), w3 = cmul(w1, w2);
;       const f32x2 apc = mkf2(a[e].x + c[e].x, a[e].y + c[e].y), amc = mkf2(a[e].x - c[e].x, a[e].y - c[e].y);
;       const f32x2 bpd = mkf2(b[e].x + d[e].x, b[e].y + d[e].y), bmd = mkf2(b[e].x - d[e].x, b[e].y - d[e].y);
;       const int o = 4 * i - 3 * q;
;       buf[SW(o)] = mkf2(apc.x + bpd.x, apc.y + bpd.y);
;       buf[SW(o + s)] = cmul(w1, mkf2(amc.x + bmd.y, amc.y - bmd.x));
;       buf[SW(o + 2 * s)] = cmul(w2, mkf2(apc.x - bpd.x, apc.y - bpd.y));
;       buf[SW(o + 3 * s)] = cmul(w3, mkf2(amc.x - bmd.y, amc.y + bmd.x));
;     }
	ds_read2st64_b64 v[2:5], v154 offset0:0 offset1:32
	ds_read2st64_b64 v[6:9], v154 offset0:64 offset1:96
	ds_read2st64_b64 v[10:13], v154 offset0:4 offset1:36
	ds_read2st64_b64 v[14:17], v154 offset0:68 offset1:100
	ds_read2st64_b64 v[18:21], v154 offset0:8 offset1:40
	ds_read2st64_b64 v[22:25], v154 offset0:72 offset1:104
	ds_read2st64_b64 v[26:29], v154 offset0:12 offset1:44
	ds_read2st64_b64 v[30:33], v154 offset0:76 offset1:108
	ds_read2st64_b64 v[34:37], v154 offset0:16 offset1:48
	ds_read2st64_b64 v[38:41], v154 offset0:80 offset1:112
	ds_read2st64_b64 v[42:45], v154 offset0:20 offset1:52
	ds_read2st64_b64 v[46:49], v154 offset0:84 offset1:116
	ds_read2st64_b64 v[50:53], v154 offset0:24 offset1:56
	ds_read2st64_b64 v[54:57], v154 offset0:88 offset1:120
	ds_read2st64_b64 v[58:61], v154 offset0:28 offset1:60
	ds_read2st64_b64 v[62:65], v154 offset0:92 offset1:124
	v_and_b32_e32 v166, 15, v0
	v_sub_u32_e32 v168, v0, v166
	v_cvt_f32_u32_e32 v201, v168
	v_lshl_add_u32 v164, v168, 4, v166
	v_lshlrev_b32_e32 v164, 3, v164
	v_mul_f32_e32 v201, 0x39000000, v201
	v_cos_f32_e32 v210, v201
	v_sin_f32_e64 v211, -v201
	s_waitcnt lgkmcnt(14)
	v_pk_add_f32 v[202:203], v[2:3], v[6:7]
	v_pk_add_f32 v[2:3], v[2:3], v[6:7] neg_lo:[0,1] neg_hi:[0,1]
	v_pk_add_f32 v[204:205], v[4:5], v[8:9]
	v_pk_add_f32 v[4:5], v[4:5], v[8:9] neg_lo:[0,1] neg_hi:[0,1]
	v_pk_add_f32 v[6:7], v[202:203], v[204:205]
	v_pk_add_f32 v[8:9], v[202:203], v[204:205] neg_lo:[0,1] neg_hi:[0,1]
	v_pk_add_f32 v[202:203], v[2:3], v[4:5] op_sel:[0,1] op_sel_hi:[1,0] neg_hi:[0,1]
	v_pk_add_f32 v[204:205], v[2:3], v[4:5] op_sel:[0,1] op_sel_hi:[1,0] neg_lo:[0,1]
	v_pk_mul_f32 v[206:207], v[210:211], v[210:211] op_sel:[1,1] op_sel_hi:[1,0]
	v_pk_fma_f32 v[212:213], v[210:211], v[210:211], v[206:207] op_sel_hi:[0,1,1] neg_lo:[0,0,1]
	v_pk_mul_f32 v[206:207], v[210:211], v[212:213] op_sel:[1,1] op_sel_hi:[1,0]
	v_pk_fma_f32 v[220:221], v[210:211], v[212:213], v[206:207] op_sel_hi:[0,1,1] neg_lo:[0,0,1]
	v_pk_mul_f32 v[2:3], v[210:211], v[202:203] op_sel:[1,1] op_sel_hi:[1,0]
	v_pk_fma_f32 v[2:3], v[210:211], v[202:203], v[2:3] op_sel_hi:[0,1,1] neg_lo:[0,0,1]
	v_pk_mul_f32 v[4:5], v[212:213], v[8:9] op_sel:[1,1] op_sel_hi:[1,0]
	v_pk_fma_f32 v[4:5], v[212:213], v[8:9], v[4:5] op_sel_hi:[0,1,1] neg_lo:[0,0,1]
	v_pk_mul_f32 v[8:9], v[220:221], v[204:205] op_sel:[1,1] op_sel_hi:[1,0]
	v_pk_fma_f32 v[8:9], v[220:221], v[204:205], v[8:9] op_sel_hi:[0,1,1] neg_lo:[0,0,1]
	v_add_f32_e32 v214, 0x3d000000, v201
	v_cos_f32_e32 v210, v214
	v_sin_f32_e64 v211, -v214
	s_waitcnt lgkmcnt(12)
	v_pk_add_f32 v[202:203], v[10:11], v[14:15]
	v_pk_add_f32 v[10:11], v[10:11], v[14:15] neg_lo:[0,1] neg_hi:[0,1]
	v_pk_add_f32 v[204:205], v[12:13], v[16:17]
	v_pk_add_f32 v[12:13], v[12:13], v[16:17] neg_lo:[0,1] neg_hi:[0,1]
	v_pk_add_f32 v[14:15], v[202:203], v[204:205]
	v_pk_add_f32 v[16:17], v[202:203], v[204:205] neg_lo:[0,1] neg_hi:[0,1]
	v_pk_add_f32 v[202:203], v[10:11], v[12:13] op_sel:[0,1] op_sel_hi:[1,0] neg_hi:[0,1]
	v_pk_add_f32 v[204:205], v[10:11], v[12:13] op_sel:[0,1] op_sel_hi:[1,0] neg_lo:[0,1]
	v_pk_mul_f32 v[206:207], v[210:211], v[210:211] op_sel:[1,1] op_sel_hi:[1,0]
	v_pk_fma_f32 v[212:213], v[210:211], v[210:211], v[206:207] op_sel_hi:[0,1,1] neg_lo:[0,0,1]
	v_pk_mul_f32 v[206:207], v[210:211], v[212:213] op_sel:[1,1] op_sel_hi:[1,0]
	v_pk_fma_f32 v[220:221], v[210:211], v[212:213], v[206:207] op_sel_hi:[0,1,1] neg_lo:[0,0,1]
	v_pk_mul_f32 v[10:11], v[210:211], v[202:203] op_sel:[1,1] op_sel_hi:[1,0]
	v_pk_fma_f32 v[10:11], v[210:211], v[202:203], v[10:11] op_sel_hi:[0,1,1] neg_lo:[0,0,1]
	v_pk_mul_f32 v[12:13], v[212:213], v[16:17] op_sel:[1,1] op_sel_hi:[1,0]
	v_pk_fma_f32 v[12:13], v[212:213], v[16:17], v[12:13] op_sel_hi:[0,1,1] neg_lo:[0,0,1]
	v_pk_mul_f32 v[16:17], v[220:221], v[204:205] op_sel:[1,1] op_sel_hi:[1,0]
	v_pk_fma_f32 v[16:17], v[220:221], v[204:205], v[16:17] op_sel_hi:[0,1,1] neg_lo:[0,0,1]
	v_add_f32_e32 v214, 0x3d800000, v201
	v_cos_f32_e32 v210, v214
	v_sin_f32_e64 v211, -v214
	s_waitcnt lgkmcnt(10)
	v_pk_add_f32 v[202:203], v[18:19], v[22:23]
	v_pk_add_f32 v[18:19], v[18:19], v[22:23] neg_lo:[0,1] neg_hi:[0,1]
	v_pk_add_f32 v[204:205], v[20:21], v[24:25]
	v_pk_add_f32 v[20:21], v[20:21], v[24:25] neg_lo:[0,1] neg_hi:[0,1]
	v_pk_add_f32 v[22:23], v[202:203], v[204:205]
	v_pk_add_f32 v[24:25], v[202:203], v[204:205] neg_lo:[0,1] neg_hi:[0,1]
	v_pk_add_f32 v[202:203], v[18:19], v[20:21] op_sel:[0,1] op_sel_hi:[1,0] neg_hi:[0,1]
	v_pk_add_f32 v[204:205], v[18:19], v[20:21] op_sel:[0,1] op_sel_hi:[1,0] neg_lo:[0,1]
	v_pk_mul_f32 v[206:207], v[210:211], v[210:211] op_sel:[1,1] op_sel_hi:[1,0]
	v_pk_fma_f32 v[212:213], v[210:211], v[210:211], v[206:207] op_sel_hi:[0,1,1] neg_lo:[0,0,1]
	v_pk_mul_f32 v[206:207], v[210:211], v[212:213] op_sel:[1,1] op_sel_hi:[1,0]
	v_pk_fma_f32 v[220:221], v[210:211], v[212:213], v[206:207] op_sel_hi:[0,1,1] neg_lo:[0,0,1]
	v_pk_mul_f32 v[18:19], v[210:211], v[202:203] op_sel:[1,1] op_sel_hi:[1,0]
	v_pk_fma_f32 v[18:19], v[210:211], v[202:203], v[18:19] op_sel_hi:[0,1,1] neg_lo:[0,0,1]
	v_pk_mul_f32 v[20:21], v[212:213], v[24:25] op_sel:[1,1] op_sel_hi:[1,0]
	v_pk_fma_f32 v[20:21], v[212:213], v[24:25], v[20:21] op_sel_hi:[0,1,1] neg_lo:[0,0,1]
	v_pk_mul_f32 v[24:25], v[220:221], v[204:205] op_sel:[1,1] op_sel_hi:[1,0]
	v_pk_fma_f32 v[24:25], v[220:221], v[204:205], v[24:25] op_sel_hi:[0,1,1] neg_lo:[0,0,1]
	v_add_f32_e32 v214, 0x3dc00000, v201
	v_cos_f32_e32 v210, v214
	v_sin_f32_e64 v211, -v214
	s_waitcnt lgkmcnt(8)
; DI f32x2 cmul(f32x2 a, f32x2 b) { return mkf2(a.x * b.x - a.y * b.y, a.x * b.y + a.y * b.x); }
; DI void fft8192(f32x2* buf, const f32x2* __restrict__ tw) {
;     ...
; #pragma unroll
;     for (int e = 0; e < 8; ++e) {
;       const int i = tid + 256 * e;
;       const int q = i & (s - 1);
;       const int ps = i - q;
;       const float rev = (float)ps * (1.f / 8192.f);
;       const f32x2 w1 = mkf2(__builtin_amdgcn_cosf(rev), -__builtin_amdgcn_sinf(rev));
;       const f32x2 w2 = cmul(w1, w1), w3 = cmul(w1, w2);
;       const f32x2 apc = mkf2(a[e].x + c[e].x, a[e].y + c[e].y), amc = mkf2(a[e].x - c[e].x, a[e].y - c[e].y);
;       const f32x2 bpd = mkf2(b[e].x + d[e].x, b[e].y + d[e].y), bmd = mkf2(b[e].x - d[e].x, b[e].y - d[e].y);
;       const int o = 4 * i - 3 * q;
;       buf[SW(o)] = mkf2(apc.x + bpd.x, apc.y + bpd.y);
;       buf[SW(o + s)] = cmul(w1, mkf2(amc.x + bmd.y, amc.y - bmd.x));
;       buf[SW(o + 2 * s)] = cmul(w2, mkf2(apc.x - bpd.x, apc.y - bpd.y));
;       buf[SW(o + 3 * s)] = cmul(w3, mkf2(amc.x - bmd.y, amc.y + bmd.x));
;     }
	v_pk_add_f32 v[202:203], v[26:27], v[30:31]
	v_pk_add_f32 v[26:27], v[26:27], v[30:31] neg_lo:[0,1] neg_hi:[0,1]
	v_pk_add_f32 v[204:205], v[28:29], v[32:33]
	v_pk_add_f32 v[28:29], v[28:29], v[32:33] neg_lo:[0,1] neg_hi:[0,1]
	v_pk_add_f32 v[30:31], v[202:203], v[204:205]
	v_pk_add_f32 v[32:33], v[202:203], v[204:205] neg_lo:[0,1] neg_hi:[0,1]
	v_pk_add_f32 v[202:203], v[26:27], v[28:29] op_sel:[0,1] op_sel_hi:[1,0] neg_hi:[0,1]
	v_pk_add_f32 v[204:205], v[26:27], v[28:29] op_sel:[0,1] op_sel_hi:[1,0] neg_lo:[0,1]
	v_pk_mul_f32 v[206:207], v[210:211], v[210:211] op_sel:[1,1] op_sel_hi:[1,0]
	v_pk_fma_f32 v[212:213], v[210:211], v[210:211], v[206:207] op_sel_hi:[0,1,1] neg_lo:[0,0,1]
	v_pk_mul_f32 v[206:207], v[210:211], v[212:213] op_sel:[1,1] op_sel_hi:[1,0]
	v_pk_fma_f32 v[220:221], v[210:211], v[212:213], v[206:207] op_sel_hi:[0,1,1] neg_lo:[0,0,1]
	v_pk_mul_f32 v[26:27], v[210:211], v[202:203] op_sel:[1,1] op_sel_hi:[1,0]
	v_pk_fma_f32 v[26:27], v[210:211], v[202:203], v[26:27] op_sel_hi:[0,1,1] neg_lo:[0,0,1]
	v_pk_mul_f32 v[28:29], v[212:213], v[32:33] op_sel:[1,1] op_sel_hi:[1,0]
	v_pk_fma_f32 v[28:29], v[212:213], v[32:33], v[28:29] op_sel_hi:[0,1,1] neg_lo:[0,0,1]
	v_pk_mul_f32 v[32:33], v[220:221], v[204:205] op_sel:[1,1] op_sel_hi:[1,0]
	v_pk_fma_f32 v[32:33], v[220:221], v[204:205], v[32:33] op_sel_hi:[0,1,1] neg_lo:[0,0,1]
	v_add_f32_e32 v214, 0x3e000000, v201
	v_cos_f32_e32 v210, v214
	v_sin_f32_e64 v211, -v214
	s_waitcnt lgkmcnt(6)
	v_pk_add_f32 v[202:203], v[34:35], v[38:39]
	v_pk_add_f32 v[34:35], v[34:35], v[38:39] neg_lo:[0,1] neg_hi:[0,1]
	v_pk_add_f32 v[204:205], v[36:37], v[40:41]
	v_pk_add_f32 v[36:37], v[36:37], v[40:41] neg_lo:[0,1] neg_hi:[0,1]
	v_pk_add_f32 v[38:39], v[202:203], v[204:205]
	v_pk_add_f32 v[40:41], v[202:203], v[204:205] neg_lo:[0,1] neg_hi:[0,1]
	v_pk_add_f32 v[202:203], v[34:35], v[36:37] op_sel:[0,1] op_sel_hi:[1,0] neg_hi:[0,1]
	v_pk_add_f32 v[204:205], v[34:35], v[36:37] op_sel:[0,1] op_sel_hi:[1,0] neg_lo:[0,1]
	v_pk_mul_f32 v[206:207], v[210:211], v[210:211] op_sel:[1,1] op_sel_hi:[1,0]
	v_pk_fma_f32 v[212:213], v[210:211], v[210:211], v[206:207] op_sel_hi:[0,1,1] neg_lo:[0,0,1]
	v_pk_mul_f32 v[206:207], v[210:211], v[212:213] op_sel:[1,1] op_sel_hi:[1,0]
	v_pk_fma_f32 v[220:221], v[210:211], v[212:213], v[206:207] op_sel_hi:[0,1,1] neg_lo:[0,0,1]
	v_pk_mul_f32 v[34:35], v[210:211], v[202:203] op_sel:[1,1] op_sel_hi:[1,0]
	v_pk_fma_f32 v[34:35], v[210:211], v[202:203], v[34:35] op_sel_hi:[0,1,1] neg_lo:[0,0,1]
	v_pk_mul_f32 v[36:37], v[212:213], v[40:41] op_sel:[1,1] op_sel_hi:[1,0]
	v_pk_fma_f32 v[36:37], v[212:213], v[40:41], v[36:37] op_sel_hi:[0,1,1] neg_lo:[0,0,1]
	v_pk_mul_f32 v[40:41], v[220:221], v[204:205] op_sel:[1,1] op_sel_hi:[1,0]
	v_pk_fma_f32 v[40:41], v[220:221], v[204:205], v[40:41] op_sel_hi:[0,1,1] neg_lo:[0,0,1]
	v_add_f32_e32 v214, 0x3e200000, v201
	v_cos_f32_e32 v210, v214
	v_sin_f32_e64 v211, -v214
	s_waitcnt lgkmcnt(4)
	v_pk_add_f32 v[202:203], v[42:43], v[46:47]
	v_pk_add_f32 v[42:43], v[42:43], v[46:47] neg_lo:[0,1] neg_hi:[0,1]
	v_pk_add_f32 v[204:205], v[44:45], v[48:49]
	v_pk_add_f32 v[44:45], v[44:45], v[48:49] neg_lo:[0,1] neg_hi:[0,1]
	v_pk_add_f32 v[46:47], v[202:203], v[204:205]
	v_pk_add_f32 v[48:49], v[202:203], v[204:205] neg_lo:[0,1] neg_hi:[0,1]
	v_pk_add_f32 v[202:203], v[42:43], v[44:45] op_sel:[0,1] op_sel_hi:[1,0] neg_hi:[0,1]
	v_pk_add_f32 v[204:205], v[42:43], v[44:45] op_sel:[0,1] op_sel_hi:[1,0] neg_lo:[0,1]
	v_pk_mul_f32 v[206:207], v[210:211], v[210:211] op_sel:[1,1] op_sel_hi:[1,0]
	v_pk_fma_f32 v[212:213], v[210:211], v[210:211], v[206:207] op_sel_hi:[0,1,1] neg_lo:[0,0,1]
	v_pk_mul_f32 v[206:207], v[210:211], v[212:213] op_sel:[1,1] op_sel_hi:[1,0]
	v_pk_fma_f32 v[220:221], v[210:211], v[212:213], v[206:207] op_sel_hi:[0,1,1] neg_lo:[0,0,1]
	v_pk_mul_f32 v[42:43], v[210:211], v[202:203] op_sel:[1,1] op_sel_hi:[1,0]
	v_pk_fma_f32 v[42:43], v[210:211], v[202:203], v[42:43] op_sel_hi:[0,1,1] neg_lo:[0,0,1]
	v_pk_mul_f32 v[44:45], v[212:213], v[48:49] op_sel:[1,1] op_sel_hi:[1,0]
	v_pk_fma_f32 v[44:45], v[212:213], v[48:49], v[44:45] op_sel_hi:[0,1,1] neg_lo:[0,0,1]
	v_pk_mul_f32 v[48:49], v[220:221], v[204:205] op_sel:[1,1] op_sel_hi:[1,0]
	v_pk_fma_f32 v[48:49], v[220:221], v[204:205], v[48:49] op_sel_hi:[0,1,1] neg_lo:[0,0,1]
	v_add_f32_e32 v214, 0x3e400000, v201
	v_cos_f32_e32 v210, v214
	v_sin_f32_e64 v211, -v214
	s_waitcnt lgkmcnt(2)
	v_pk_add_f32 v[202:203], v[50:51], v[54:55]
	v_pk_add_f32 v[50:51], v[50:51], v[54:55] neg_lo:[0,1] neg_hi:[0,1]
	v_pk_add_f32 v[204:205], v[52:53], v[56:57]
	v_pk_add_f32 v[52:53], v[52:53], v[56:57] neg_lo:[0,1] neg_hi:[0,1]
	v_pk_add_f32 v[54:55], v[202:203], v[204:205]
	v_pk_add_f32 v[56:57], v[202:203], v[204:205] neg_lo:[0,1] neg_hi:[0,1]
	v_pk_add_f32 v[202:203], v[50:51], v[52:53] op_sel:[0,1] op_sel_hi:[1,0] neg_hi:[0,1]
	v_pk_add_f32 v[204:205], v[50:51], v[52:53] op_sel:[0,1] op_sel_hi:[1,0] neg_lo:[0,1]
	v_pk_mul_f32 v[206:207], v[210:211], v[210:211] op_sel:[1,1] op_sel_hi:[1,0]
	v_pk_fma_f32 v[212:213], v[210:211], v[210:211], v[206:207] op_sel_hi:[0,1,1] neg_lo:[0,0,1]
	v_pk_mul_f32 v[206:207], v[210:211], v[212:213] op_sel:[1,1] op_sel_hi:[1,0]
	v_pk_fma_f32 v[220:221], v[210:211], v[212:213], v[206:207] op_sel_hi:[0,1,1] neg_lo:[0,0,1]
	v_pk_mul_f32 v[50:51], v[210:211], v[202:203] op_sel:[1,1] op_sel_hi:[1,0]
	v_pk_fma_f32 v[50:51], v[210:211], v[202:203], v[50:51] op_sel_hi:[0,1,1] neg_lo:[0,0,1]
	v_pk_mul_f32 v[52:53], v[212:213], v[56:57] op_sel:[1,1] op_sel_hi:[1,0]
	v_pk_fma_f32 v[52:53], v[212:213], v[56:57], v[52:53] op_sel_hi:[0,1,1] neg_lo:[0,0,1]
	v_pk_mul_f32 v[56:57], v[220:221], v[204:205] op_sel:[1,1] op_sel_hi:[1,0]
	v_pk_fma_f32 v[56:57], v[220:221], v[204:205], v[56:57] op_sel_hi:[0,1,1] neg_lo:[0,0,1]
	v_add_f32_e32 v214, 0x3e600000, v201
	v_cos_f32_e32 v210, v214
	v_sin_f32_e64 v211, -v214
	s_waitcnt lgkmcnt(0)
; DI f32x2 cmul(f32x2 a, f32x2 b) { return mkf2(a.x * b.x - a.y * b.y, a.x * b.y + a.y * b.x); }
; DI void fft8192(f32x2* buf, const f32x2* __restrict__ tw) {
;     ...
; #pragma unroll
;     for (int e = 0; e < 8; ++e) {
;       const int i = tid + 256 * e;
;       const int q = i & (s - 1);
;       const int ps = i - q;
;       const float rev = (float)ps * (1.f / 8192.f);
;       const f32x2 w1 = mkf2(__builtin_amdgcn_cosf(rev), -__builtin_amdgcn_sinf(rev));
;       const f32x2 w2 = cmul(w1, w1), w3 = cmul(w1, w2);
;       const f32x2 apc = mkf2(a[e].x + c[e].x, a[e].y + c[e].y), amc = mkf2(a[e].x - c[e].x, a[e].y - c[e].y);
;       const f32x2 bpd = mkf2(b[e].x + d[e].x, b[e].y + d[e].y), bmd = mkf2(b[e].x - d[e].x, b[e].y - d[e].y);
;       const int o = 4 * i - 3 * q;
;       buf[SW(o)] = mkf2(apc.x + bpd.x, apc.y + bpd.y);
;       buf[SW(o + s)] = cmul(w1, mkf2(amc.x + bmd.y, amc.y - bmd.x));
;       buf[SW(o + 2 * s)] = cmul(w2, mkf2(apc.x - bpd.x, apc.y - bpd.y));
;       buf[SW(o + 3 * s)] = cmul(w3, mkf2(amc.x - bmd.y, amc.y + bmd.x));
;     }
	v_pk_add_f32 v[202:203], v[58:59], v[62:63]
	v_pk_add_f32 v[58:59], v[58:59], v[62:63] neg_lo:[0,1] neg_hi:[0,1]
	v_pk_add_f32 v[204:205], v[60:61], v[64:65]
	v_pk_add_f32 v[60:61], v[60:61], v[64:65] neg_lo:[0,1] neg_hi:[0,1]
	v_pk_add_f32 v[62:63], v[202:203], v[204:205]
	v_pk_add_f32 v[64:65], v[202:203], v[204:205] neg_lo:[0,1] neg_hi:[0,1]
	v_pk_add_f32 v[202:203], v[58:59], v[60:61] op_sel:[0,1] op_sel_hi:[1,0] neg_hi:[0,1]
	v_pk_add_f32 v[204:205], v[58:59], v[60:61] op_sel:[0,1] op_sel_hi:[1,0] neg_lo:[0,1]
	v_pk_mul_f32 v[206:207], v[210:211], v[210:211] op_sel:[1,1] op_sel_hi:[1,0]
	v_pk_fma_f32 v[212:213], v[210:211], v[210:211], v[206:207] op_sel_hi:[0,1,1] neg_lo:[0,0,1]
	v_pk_mul_f32 v[206:207], v[210:211], v[212:213] op_sel:[1,1] op_sel_hi:[1,0]
	v_pk_fma_f32 v[220:221], v[210:211], v[212:213], v[206:207] op_sel_hi:[0,1,1] neg_lo:[0,0,1]
	v_pk_mul_f32 v[58:59], v[210:211], v[202:203] op_sel:[1,1] op_sel_hi:[1,0]
	v_pk_fma_f32 v[58:59], v[210:211], v[202:203], v[58:59] op_sel_hi:[0,1,1] neg_lo:[0,0,1]
	v_pk_mul_f32 v[60:61], v[212:213], v[64:65] op_sel:[1,1] op_sel_hi:[1,0]
	v_pk_fma_f32 v[60:61], v[212:213], v[64:65], v[60:61] op_sel_hi:[0,1,1] neg_lo:[0,0,1]
	v_pk_mul_f32 v[64:65], v[220:221], v[204:205] op_sel:[1,1] op_sel_hi:[1,0]
	v_pk_fma_f32 v[64:65], v[220:221], v[204:205], v[64:65] op_sel_hi:[0,1,1] neg_lo:[0,0,1]
	s_barrier
	v_mul_f32_e32 v214, 4.0, v201
	v_cos_f32_e32 v224, v214
	v_sin_f32_e64 v225, -v214
	s_nop 0
	v_pk_mul_f32 v[206:207], v[224:225], v[224:225] op_sel:[1,1] op_sel_hi:[1,0]
	v_pk_fma_f32 v[226:227], v[224:225], v[224:225], v[206:207] op_sel_hi:[0,1,1] neg_lo:[0,0,1]
	v_pk_mul_f32 v[206:207], v[224:225], v[226:227] op_sel:[1,1] op_sel_hi:[1,0]
	v_pk_fma_f32 v[230:231], v[224:225], v[226:227], v[206:207] op_sel_hi:[0,1,1] neg_lo:[0,0,1]
	v_pk_add_f32 v[202:203], v[6:7], v[38:39]
	v_pk_add_f32 v[6:7], v[6:7], v[38:39] neg_lo:[0,1] neg_hi:[0,1]
	v_pk_add_f32 v[204:205], v[22:23], v[54:55]
	v_pk_add_f32 v[22:23], v[22:23], v[54:55] neg_lo:[0,1] neg_hi:[0,1]
	v_pk_add_f32 v[38:39], v[202:203], v[204:205]
	v_pk_add_f32 v[54:55], v[202:203], v[204:205] neg_lo:[0,1] neg_hi:[0,1]
	v_pk_add_f32 v[202:203], v[6:7], v[22:23] op_sel:[0,1] op_sel_hi:[1,0] neg_hi:[0,1]
	v_pk_add_f32 v[204:205], v[6:7], v[22:23] op_sel:[0,1] op_sel_hi:[1,0] neg_lo:[0,1]
	v_pk_mul_f32 v[6:7], v[224:225], v[202:203] op_sel:[1,1] op_sel_hi:[1,0]
	v_pk_fma_f32 v[6:7], v[224:225], v[202:203], v[6:7] op_sel_hi:[0,1,1] neg_lo:[0,0,1]
	v_pk_mul_f32 v[22:23], v[226:227], v[54:55] op_sel:[1,1] op_sel_hi:[1,0]
	v_pk_fma_f32 v[22:23], v[226:227], v[54:55], v[22:23] op_sel_hi:[0,1,1] neg_lo:[0,0,1]
	v_pk_mul_f32 v[54:55], v[230:231], v[204:205] op_sel:[1,1] op_sel_hi:[1,0]
	v_pk_fma_f32 v[54:55], v[230:231], v[204:205], v[54:55] op_sel_hi:[0,1,1] neg_lo:[0,0,1]
	v_pk_add_f32 v[202:203], v[2:3], v[34:35]
	v_pk_add_f32 v[2:3], v[2:3], v[34:35] neg_lo:[0,1] neg_hi:[0,1]
	v_pk_add_f32 v[204:205], v[18:19], v[50:51]
	v_pk_add_f32 v[18:19], v[18:19], v[50:51] neg_lo:[0,1] neg_hi:[0,1]
	v_pk_add_f32 v[34:35], v[202:203], v[204:205]
	v_pk_add_f32 v[50:51], v[202:203], v[204:205] neg_lo:[0,1] neg_hi:[0,1]
	v_pk_add_f32 v[202:203], v[2:3], v[18:19] op_sel:[0,1] op_sel_hi:[1,0] neg_hi:[0,1]
	v_pk_add_f32 v[204:205], v[2:3], v[18:19] op_sel:[0,1] op_sel_hi:[1,0] neg_lo:[0,1]
	v_pk_mul_f32 v[2:3], v[224:225], v[202:203] op_sel:[1,1] op_sel_hi:[1,0]
	v_pk_fma_f32 v[2:3], v[224:225], v[202:203], v[2:3] op_sel_hi:[0,1,1] neg_lo:[0,0,1]
	v_pk_mul_f32 v[18:19], v[226:227], v[50:51] op_sel:[1,1] op_sel_hi:[1,0]
	v_pk_fma_f32 v[18:19], v[226:227], v[50:51], v[18:19] op_sel_hi:[0,1,1] neg_lo:[0,0,1]
	v_pk_mul_f32 v[50:51], v[230:231], v[204:205] op_sel:[1,1] op_sel_hi:[1,0]
	v_pk_fma_f32 v[50:51], v[230:231], v[204:205], v[50:51] op_sel_hi:[0,1,1] neg_lo:[0,0,1]
	v_pk_add_f32 v[202:203], v[4:5], v[36:37]
	v_pk_add_f32 v[4:5], v[4:5], v[36:37] neg_lo:[0,1] neg_hi:[0,1]
	v_pk_add_f32 v[204:205], v[20:21], v[52:53]
	v_pk_add_f32 v[20:21], v[20:21], v[52:53] neg_lo:[0,1] neg_hi:[0,1]
	v_pk_add_f32 v[36:37], v[202:203], v[204:205]
	v_pk_add_f32 v[52:53], v[202:203], v[204:205] neg_lo:[0,1] neg_hi:[0,1]
	v_pk_add_f32 v[202:203], v[4:5], v[20:21] op_sel:[0,1] op_sel_hi:[1,0] neg_hi:[0,1]
	v_pk_add_f32 v[204:205], v[4:5], v[20:21] op_sel:[0,1] op_sel_hi:[1,0] neg_lo:[0,1]
	v_pk_mul_f32 v[4:5], v[224:225], v[202:203] op_sel:[1,1] op_sel_hi:[1,0]
	v_pk_fma_f32 v[4:5], v[224:225], v[202:203], v[4:5] op_sel_hi:[0,1,1] neg_lo:[0,0,1]
	v_pk_mul_f32 v[20:21], v[226:227], v[52:53] op_sel:[1,1] op_sel_hi:[1,0]
	v_pk_fma_f32 v[20:21], v[226:227], v[52:53], v[20:21] op_sel_hi:[0,1,1] neg_lo:[0,0,1]
	v_pk_mul_f32 v[52:53], v[230:231], v[204:205] op_sel:[1,1] op_sel_hi:[1,0]
	v_pk_fma_f32 v[52:53], v[230:231], v[204:205], v[52:53] op_sel_hi:[0,1,1] neg_lo:[0,0,1]
	v_pk_add_f32 v[202:203], v[8:9], v[40:41]
	v_pk_add_f32 v[8:9], v[8:9], v[40:41] neg_lo:[0,1] neg_hi:[0,1]
	v_pk_add_f32 v[204:205], v[24:25], v[56:57]
	v_pk_add_f32 v[24:25], v[24:25], v[56:57] neg_lo:[0,1] neg_hi:[0,1]
	v_pk_add_f32 v[40:41], v[202:203], v[204:205]
	v_pk_add_f32 v[56:57], v[202:203], v[204:205] neg_lo:[0,1] neg_hi:[0,1]
	v_pk_add_f32 v[202:203], v[8:9], v[24:25] op_sel:[0,1] op_sel_hi:[1,0] neg_hi:[0,1]
	v_pk_add_f32 v[204:205], v[8:9], v[24:25] op_sel:[0,1] op_sel_hi:[1,0] neg_lo:[0,1]
	v_pk_mul_f32 v[8:9], v[224:225], v[202:203] op_sel:[1,1] op_sel_hi:[1,0]
	v_pk_fma_f32 v[8:9], v[224:225], v[202:203], v[8:9] op_sel_hi:[0,1,1] neg_lo:[0,0,1]
	v_pk_mul_f32 v[24:25], v[226:227], v[56:57] op_sel:[1,1] op_sel_hi:[1,0]
	v_pk_fma_f32 v[24:25], v[226:227], v[56:57], v[24:25] op_sel_hi:[0,1,1] neg_lo:[0,0,1]
; DI f32x2 cmul(f32x2 a, f32x2 b) { return mkf2(a.x * b.x - a.y * b.y, a.x * b.y + a.y * b.x); }
; DI void fft8192(f32x2* buf, const f32x2* __restrict__ tw) {
;     ...
; #pragma unroll
;     for (int e = 0; e < 8; ++e) {
;       const int i = tid + 256 * e;
;       const int q = i & (s - 1);
;       const int ps = i - q;
;       const float rev = (float)ps * (1.f / 8192.f);
;       const f32x2 w1 = mkf2(__builtin_amdgcn_cosf(rev), -__builtin_amdgcn_sinf(rev));
;       const f32x2 w2 = cmul(w1, w1), w3 = cmul(w1, w2);
;       const f32x2 apc = mkf2(a[e].x + c[e].x, a[e].y + c[e].y), amc = mkf2(a[e].x - c[e].x, a[e].y - c[e].y);
;       const f32x2 bpd = mkf2(b[e].x + d[e].x, b[e].y + d[e].y), bmd = mkf2(b[e].x - d[e].x, b[e].y - d[e].y);
;       const int o = 4 * i - 3 * q;
;       buf[SW(o)] = mkf2(apc.x + bpd.x, apc.y + bpd.y);
;       buf[SW(o + s)] = cmul(w1, mkf2(amc.x + bmd.y, amc.y - bmd.x));
;       buf[SW(o + 2 * s)] = cmul(w2, mkf2(apc.x - bpd.x, apc.y - bpd.y));
;       buf[SW(o + 3 * s)] = cmul(w3, mkf2(amc.x - bmd.y, amc.y + bmd.x));
;     }
	v_pk_mul_f32 v[56:57], v[230:231], v[204:205] op_sel:[1,1] op_sel_hi:[1,0]
	v_pk_fma_f32 v[56:57], v[230:231], v[204:205], v[56:57] op_sel_hi:[0,1,1] neg_lo:[0,0,1]
	v_mul_f32_e32 v214, 4.0, v201
	v_add_f32_e32 v214, 0x3e000000, v214
	v_cos_f32_e32 v224, v214
	v_sin_f32_e64 v225, -v214
	s_nop 0
	v_pk_mul_f32 v[206:207], v[224:225], v[224:225] op_sel:[1,1] op_sel_hi:[1,0]
	v_pk_fma_f32 v[226:227], v[224:225], v[224:225], v[206:207] op_sel_hi:[0,1,1] neg_lo:[0,0,1]
	v_pk_mul_f32 v[206:207], v[224:225], v[226:227] op_sel:[1,1] op_sel_hi:[1,0]
	v_pk_fma_f32 v[230:231], v[224:225], v[226:227], v[206:207] op_sel_hi:[0,1,1] neg_lo:[0,0,1]
	v_pk_add_f32 v[202:203], v[14:15], v[46:47]
	v_pk_add_f32 v[14:15], v[14:15], v[46:47] neg_lo:[0,1] neg_hi:[0,1]
	v_pk_add_f32 v[204:205], v[30:31], v[62:63]
	v_pk_add_f32 v[30:31], v[30:31], v[62:63] neg_lo:[0,1] neg_hi:[0,1]
	v_pk_add_f32 v[46:47], v[202:203], v[204:205]
	v_pk_add_f32 v[62:63], v[202:203], v[204:205] neg_lo:[0,1] neg_hi:[0,1]
	v_pk_add_f32 v[202:203], v[14:15], v[30:31] op_sel:[0,1] op_sel_hi:[1,0] neg_hi:[0,1]
	v_pk_add_f32 v[204:205], v[14:15], v[30:31] op_sel:[0,1] op_sel_hi:[1,0] neg_lo:[0,1]
	v_pk_mul_f32 v[14:15], v[224:225], v[202:203] op_sel:[1,1] op_sel_hi:[1,0]
	v_pk_fma_f32 v[14:15], v[224:225], v[202:203], v[14:15] op_sel_hi:[0,1,1] neg_lo:[0,0,1]
	v_pk_mul_f32 v[30:31], v[226:227], v[62:63] op_sel:[1,1] op_sel_hi:[1,0]
	v_pk_fma_f32 v[30:31], v[226:227], v[62:63], v[30:31] op_sel_hi:[0,1,1] neg_lo:[0,0,1]
	v_pk_mul_f32 v[62:63], v[230:231], v[204:205] op_sel:[1,1] op_sel_hi:[1,0]
	v_pk_fma_f32 v[62:63], v[230:231], v[204:205], v[62:63] op_sel_hi:[0,1,1] neg_lo:[0,0,1]
	v_pk_add_f32 v[202:203], v[10:11], v[42:43]
	v_pk_add_f32 v[10:11], v[10:11], v[42:43] neg_lo:[0,1] neg_hi:[0,1]
	v_pk_add_f32 v[204:205], v[26:27], v[58:59]
	v_pk_add_f32 v[26:27], v[26:27], v[58:59] neg_lo:[0,1] neg_hi:[0,1]
	v_pk_add_f32 v[42:43], v[202:203], v[204:205]
	v_pk_add_f32 v[58:59], v[202:203], v[204:205] neg_lo:[0,1] neg_hi:[0,1]
	v_pk_add_f32 v[202:203], v[10:11], v[26:27] op_sel:[0,1] op_sel_hi:[1,0] neg_hi:[0,1]
	v_pk_add_f32 v[204:205], v[10:11], v[26:27] op_sel:[0,1] op_sel_hi:[1,0] neg_lo:[0,1]
	v_pk_mul_f32 v[10:11], v[224:225], v[202:203] op_sel:[1,1] op_sel_hi:[1,0]
	v_pk_fma_f32 v[10:11], v[224:225], v[202:203], v[10:11] op_sel_hi:[0,1,1] neg_lo:[0,0,1]
	v_pk_mul_f32 v[26:27], v[226:227], v[58:59] op_sel:[1,1] op_sel_hi:[1,0]
	v_pk_fma_f32 v[26:27], v[226:227], v[58:59], v[26:27] op_sel_hi:[0,1,1] neg_lo:[0,0,1]
	v_pk_mul_f32 v[58:59], v[230:231], v[204:205] op_sel:[1,1] op_sel_hi:[1,0]
	v_pk_fma_f32 v[58:59], v[230:231], v[204:205], v[58:59] op_sel_hi:[0,1,1] neg_lo:[0,0,1]
	v_pk_add_f32 v[202:203], v[12:13], v[44:45]
	v_pk_add_f32 v[12:13], v[12:13], v[44:45] neg_lo:[0,1] neg_hi:[0,1]
	v_pk_add_f32 v[204:205], v[28:29], v[60:61]
	v_pk_add_f32 v[28:29], v[28:29], v[60:61] neg_lo:[0,1] neg_hi:[0,1]
	v_pk_add_f32 v[44:45], v[202:203], v[204:205]
	v_pk_add_f32 v[60:61], v[202:203], v[204:205] neg_lo:[0,1] neg_hi:[0,1]
	v_pk_add_f32 v[202:203], v[12:13], v[28:29] op_sel:[0,1] op_sel_hi:[1,0] neg_hi:[0,1]
	v_pk_add_f32 v[204:205], v[12:13], v[28:29] op_sel:[0,1] op_sel_hi:[1,0] neg_lo:[0,1]
	v_pk_mul_f32 v[12:13], v[224:225], v[202:203] op_sel:[1,1] op_sel_hi:[1,0]
	v_pk_fma_f32 v[12:13], v[224:225], v[202:203], v[12:13] op_sel_hi:[0,1,1] neg_lo:[0,0,1]
	v_pk_mul_f32 v[28:29], v[226:227], v[60:61] op_sel:[1,1] op_sel_hi:[1,0]
	v_pk_fma_f32 v[28:29], v[226:227], v[60:61], v[28:29] op_sel_hi:[0,1,1] neg_lo:[0,0,1]
	v_pk_mul_f32 v[60:61], v[230:231], v[204:205] op_sel:[1,1] op_sel_hi:[1,0]
	v_pk_fma_f32 v[60:61], v[230:231], v[204:205], v[60:61] op_sel_hi:[0,1,1] neg_lo:[0,0,1]
	v_pk_add_f32 v[202:203], v[16:17], v[48:49]
	v_pk_add_f32 v[16:17], v[16:17], v[48:49] neg_lo:[0,1] neg_hi:[0,1]
	v_pk_add_f32 v[204:205], v[32:33], v[64:65]
	v_pk_add_f32 v[32:33], v[32:33], v[64:65] neg_lo:[0,1] neg_hi:[0,1]
	v_pk_add_f32 v[48:49], v[202:203], v[204:205]
	v_pk_add_f32 v[64:65], v[202:203], v[204:205] neg_lo:[0,1] neg_hi:[0,1]
	v_pk_add_f32 v[202:203], v[16:17], v[32:33] op_sel:[0,1] op_sel_hi:[1,0] neg_hi:[0,1]
	v_pk_add_f32 v[204:205], v[16:17], v[32:33] op_sel:[0,1] op_sel_hi:[1,0] neg_lo:[0,1]
	v_pk_mul_f32 v[16:17], v[224:225], v[202:203] op_sel:[1,1] op_sel_hi:[1,0]
	v_pk_fma_f32 v[16:17], v[224:225], v[202:203], v[16:17] op_sel_hi:[0,1,1] neg_lo:[0,0,1]
	v_pk_mul_f32 v[32:33], v[226:227], v[64:65] op_sel:[1,1] op_sel_hi:[1,0]
	v_pk_fma_f32 v[32:33], v[226:227], v[64:65], v[32:33] op_sel_hi:[0,1,1] neg_lo:[0,0,1]
	v_pk_mul_f32 v[64:65], v[230:231], v[204:205] op_sel:[1,1] op_sel_hi:[1,0]
	v_pk_fma_f32 v[64:65], v[230:231], v[204:205], v[64:65] op_sel_hi:[0,1,1] neg_lo:[0,0,1]
	ds_write_b64 v164, v[38:39] offset:0
	v_xor_b32_e32 v156, 0x80, v164
	ds_write_b64 v156, v[34:35] offset:0
	v_xor_b32_e32 v158, 0x128, v164
	ds_write_b64 v158, v[36:37] offset:0
	v_xor_b32_e32 v160, 0x1a8, v164
	ds_write_b64 v160, v[40:41] offset:0
	v_xor_b32_e32 v162, 0x2d0, v164
	ds_write_b64 v162, v[6:7] offset:0
	v_xor_b32_e32 v156, 0x250, v164
	ds_write_b64 v156, v[2:3] offset:0
	v_xor_b32_e32 v158, 0x3f8, v164
	ds_write_b64 v158, v[4:5] offset:0
	v_xor_b32_e32 v160, 0x378, v164
	ds_write_b64 v160, v[8:9] offset:0
	v_xor_b32_e32 v162, 0x400, v164
	ds_write_b64 v162, v[22:23] offset:0
	v_xor_b32_e32 v156, 0x480, v164
	ds_write_b64 v156, v[18:19] offset:0
	v_xor_b32_e32 v158, 0x528, v164
	ds_write_b64 v158, v[20:21] offset:0
	v_xor_b32_e32 v160, 0x5a8, v164
	ds_write_b64 v160, v[24:25] offset:0
	v_xor_b32_e32 v162, 0x6d0, v164
	ds_write_b64 v162, v[54:55] offset:0
	v_xor_b32_e32 v156, 0x650, v164
	ds_write_b64 v156, v[50:51] offset:0
	v_xor_b32_e32 v158, 0x7f8, v164
	ds_write_b64 v158, v[52:53] offset:0
	v_xor_b32_e32 v160, 0x778, v164
	ds_write_b64 v160, v[56:57] offset:0
	ds_write_b64 v164, v[46:47] offset:32768
	v_xor_b32_e32 v162, 0x80, v164
	ds_write_b64 v162, v[42:43] offset:32768
	v_xor_b32_e32 v156, 0x128, v164
	ds_write_b64 v156, v[44:45] offset:32768
	v_xor_b32_e32 v158, 0x1a8, v164
	ds_write_b64 v158, v[48:49] offset:32768
	v_xor_b32_e32 v160, 0x2d0, v164
	ds_write_b64 v160, v[14:15] offset:32768
	v_xor_b32_e32 v162, 0x250, v164
	ds_write_b64 v162, v[10:11] offset:32768
	v_xor_b32_e32 v156, 0x3f8, v164
	ds_write_b64 v156, v[12:13] offset:32768
	v_xor_b32_e32 v158, 0x378, v164
	ds_write_b64 v158, v[16:17] offset:32768
	v_xor_b32_e32 v160, 0x400, v164
	ds_write_b64 v160, v[30:31] offset:32768
	v_xor_b32_e32 v162, 0x480, v164
	ds_write_b64 v162, v[26:27] offset:32768
	v_xor_b32_e32 v156, 0x528, v164
	ds_write_b64 v156, v[28:29] offset:32768
	v_xor_b32_e32 v158, 0x5a8, v164
	ds_write_b64 v158, v[32:33] offset:32768
	v_xor_b32_e32 v160, 0x6d0, v164
	ds_write_b64 v160, v[62:63] offset:32768
	v_xor_b32_e32 v162, 0x650, v164
	ds_write_b64 v162, v[58:59] offset:32768
	v_xor_b32_e32 v156, 0x7f8, v164
	ds_write_b64 v156, v[60:61] offset:32768
	v_xor_b32_e32 v158, 0x778, v164
	ds_write_b64 v158, v[64:65] offset:32768
	s_waitcnt lgkmcnt(0)
	s_barrier
; DI f32x2 cmul(f32x2 a, f32x2 b) { return mkf2(a.x * b.x - a.y * b.y, a.x * b.y + a.y * b.x); }
; DI void fft8192(f32x2* buf, const f32x2* __restrict__ tw) {
;     ...
; #pragma unroll
;     for (int e = 0; e < 8; ++e) {
;       const int i = tid + 256 * e;
;       const int pi = SW(i);
;       a[e] = buf[pi]; b[e] = buf[pi + 2048]; c[e] = buf[pi + 4096]; d[e] = buf[pi + 6144];
;     }
;     __syncthreads();
; #pragma unroll
;     for (int e = 0; e < 8; ++e) {
;       const int i = tid + 256 * e;
;       const int q = i & (s - 1);
;       const int ps = i - q;
;       const float rev = (float)ps * (1.f / 8192.f);
;       const f32x2 w1 = mkf2(__builtin_amdgcn_cosf(rev), -__builtin_amdgcn_sinf(rev));
;       const f32x2 w2 = cmul(w1, w1), w3 = cmul(w1, w2);
;       const f32x2 apc = mkf2(a[e].x + c[e].x, a[e].y + c[e].y), amc = mkf2(a[e].x - c[e].x, a[e].y - c[e].y);
;       const f32x2 bpd = mkf2(b[e].x + d[e].x, b[e].y + d[e].y), bmd = mkf2(b[e].x - d[e].x, b[e].y - d[e].y);
;       const int o = 4 * i - 3 * q;
;       buf[SW(o)] = mkf2(apc.x + bpd.x, apc.y + bpd.y);
;       buf[SW(o + s)] = cmul(w1, mkf2(amc.x + bmd.y, amc.y - bmd.x));
;       buf[SW(o + 2 * s)] = cmul(w2, mkf2(apc.x - bpd.x, apc.y - bpd.y));
;       buf[SW(o + 3 * s)] = cmul(w3, mkf2(amc.x - bmd.y, amc.y + bmd.x));
;     }
	ds_read2st64_b64 v[2:5], v154 offset0:0 offset1:32
	ds_read2st64_b64 v[6:9], v154 offset0:64 offset1:96
	ds_read2st64_b64 v[10:13], v154 offset0:4 offset1:36
	ds_read2st64_b64 v[14:17], v154 offset0:68 offset1:100
	ds_read2st64_b64 v[18:21], v154 offset0:8 offset1:40
	ds_read2st64_b64 v[22:25], v154 offset0:72 offset1:104
	ds_read2st64_b64 v[26:29], v154 offset0:12 offset1:44
	ds_read2st64_b64 v[30:33], v154 offset0:76 offset1:108
	ds_read2st64_b64 v[34:37], v154 offset0:16 offset1:48
	ds_read2st64_b64 v[38:41], v154 offset0:80 offset1:112
	ds_read2st64_b64 v[42:45], v154 offset0:20 offset1:52
	ds_read2st64_b64 v[46:49], v154 offset0:84 offset1:116
	ds_read2st64_b64 v[50:53], v154 offset0:24 offset1:56
	ds_read2st64_b64 v[54:57], v154 offset0:88 offset1:120
	ds_read2st64_b64 v[58:61], v154 offset0:28 offset1:60
	ds_read2st64_b64 v[62:65], v154 offset0:92 offset1:124
	s_waitcnt lgkmcnt(14)
	v_pk_add_f32 v[202:203], v[2:3], v[6:7]
	v_pk_add_f32 v[2:3], v[2:3], v[6:7] neg_lo:[0,1] neg_hi:[0,1]
	v_pk_add_f32 v[204:205], v[4:5], v[8:9]
	v_pk_add_f32 v[4:5], v[4:5], v[8:9] neg_lo:[0,1] neg_hi:[0,1]
	v_pk_add_f32 v[6:7], v[202:203], v[204:205]
	v_pk_add_f32 v[8:9], v[202:203], v[204:205] neg_lo:[0,1] neg_hi:[0,1]
	v_pk_add_f32 v[202:203], v[2:3], v[4:5] op_sel:[0,1] op_sel_hi:[1,0] neg_hi:[0,1]
	v_pk_add_f32 v[4:5], v[2:3], v[4:5] op_sel:[0,1] op_sel_hi:[1,0] neg_lo:[0,1]
	v_pk_mov_b32 v[2:3], v[202:203], v[202:203] op_sel:[0,1]
	v_cos_f32_e32 v210, 0x3d000000
	v_sin_f32_e32 v211, 0xbd000000
	s_waitcnt lgkmcnt(12)
	v_pk_add_f32 v[202:203], v[10:11], v[14:15]
	v_pk_add_f32 v[10:11], v[10:11], v[14:15] neg_lo:[0,1] neg_hi:[0,1]
	v_pk_add_f32 v[204:205], v[12:13], v[16:17]
	v_pk_add_f32 v[12:13], v[12:13], v[16:17] neg_lo:[0,1] neg_hi:[0,1]
	v_pk_add_f32 v[14:15], v[202:203], v[204:205]
	v_pk_add_f32 v[16:17], v[202:203], v[204:205] neg_lo:[0,1] neg_hi:[0,1]
	v_pk_add_f32 v[202:203], v[10:11], v[12:13] op_sel:[0,1] op_sel_hi:[1,0] neg_hi:[0,1]
	v_pk_add_f32 v[204:205], v[10:11], v[12:13] op_sel:[0,1] op_sel_hi:[1,0] neg_lo:[0,1]
	v_pk_mul_f32 v[206:207], v[210:211], v[210:211] op_sel:[1,1] op_sel_hi:[1,0]
	v_pk_fma_f32 v[212:213], v[210:211], v[210:211], v[206:207] op_sel_hi:[0,1,1] neg_lo:[0,0,1]
	v_pk_mul_f32 v[206:207], v[210:211], v[212:213] op_sel:[1,1] op_sel_hi:[1,0]
	v_pk_fma_f32 v[220:221], v[210:211], v[212:213], v[206:207] op_sel_hi:[0,1,1] neg_lo:[0,0,1]
	v_pk_mul_f32 v[10:11], v[210:211], v[202:203] op_sel:[1,1] op_sel_hi:[1,0]
	v_pk_fma_f32 v[10:11], v[210:211], v[202:203], v[10:11] op_sel_hi:[0,1,1] neg_lo:[0,0,1]
	v_pk_mul_f32 v[12:13], v[212:213], v[16:17] op_sel:[1,1] op_sel_hi:[1,0]
	v_pk_fma_f32 v[12:13], v[212:213], v[16:17], v[12:13] op_sel_hi:[0,1,1] neg_lo:[0,0,1]
	v_pk_mul_f32 v[16:17], v[220:221], v[204:205] op_sel:[1,1] op_sel_hi:[1,0]
	v_pk_fma_f32 v[16:17], v[220:221], v[204:205], v[16:17] op_sel_hi:[0,1,1] neg_lo:[0,0,1]
	v_cos_f32_e32 v210, 0x3d800000
	v_sin_f32_e32 v211, 0xbd800000
	s_waitcnt lgkmcnt(10)
	v_pk_add_f32 v[202:203], v[18:19], v[22:23]
	v_pk_add_f32 v[18:19], v[18:19], v[22:23] neg_lo:[0,1] neg_hi:[0,1]
	v_pk_add_f32 v[204:205], v[20:21], v[24:25]
	v_pk_add_f32 v[20:21], v[20:21], v[24:25] neg_lo:[0,1] neg_hi:[0,1]
	v_pk_add_f32 v[22:23], v[202:203], v[204:205]
	v_pk_add_f32 v[24:25], v[202:203], v[204:205] neg_lo:[0,1] neg_hi:[0,1]
	v_pk_add_f32 v[202:203], v[18:19], v[20:21] op_sel:[0,1] op_sel_hi:[1,0] neg_hi:[0,1]
	v_pk_add_f32 v[204:205], v[18:19], v[20:21] op_sel:[0,1] op_sel_hi:[1,0] neg_lo:[0,1]
	v_pk_mul_f32 v[206:207], v[210:211], v[210:211] op_sel:[1,1] op_sel_hi:[1,0]
	v_pk_fma_f32 v[212:213], v[210:211], v[210:211], v[206:207] op_sel_hi:[0,1,1] neg_lo:[0,0,1]
	v_pk_mul_f32 v[206:207], v[210:211], v[212:213] op_sel:[1,1] op_sel_hi:[1,0]
	v_pk_fma_f32 v[220:221], v[210:211], v[212:213], v[206:207] op_sel_hi:[0,1,1] neg_lo:[0,0,1]
	v_pk_mul_f32 v[18:19], v[210:211], v[202:203] op_sel:[1,1] op_sel_hi:[1,0]
	v_pk_fma_f32 v[18:19], v[210:211], v[202:203], v[18:19] op_sel_hi:[0,1,1] neg_lo:[0,0,1]
	v_pk_mul_f32 v[20:21], v[212:213], v[24:25] op_sel:[1,1] op_sel_hi:[1,0]
	v_pk_fma_f32 v[20:21], v[212:213], v[24:25], v[20:21] op_sel_hi:[0,1,1] neg_lo:[0,0,1]
	v_pk_mul_f32 v[24:25], v[220:221], v[204:205] op_sel:[1,1] op_sel_hi:[1,0]
	v_pk_fma_f32 v[24:25], v[220:221], v[204:205], v[24:25] op_sel_hi:[0,1,1] neg_lo:[0,0,1]
	v_cos_f32_e32 v210, 0x3dc00000
	v_sin_f32_e32 v211, 0xbdc00000
	s_waitcnt lgkmcnt(8)
	v_pk_add_f32 v[202:203], v[26:27], v[30:31]
	v_pk_add_f32 v[26:27], v[26:27], v[30:31] neg_lo:[0,1] neg_hi:[0,1]
	v_pk_add_f32 v[204:205], v[28:29], v[32:33]
	v_pk_add_f32 v[28:29], v[28:29], v[32:33] neg_lo:[0,1] neg_hi:[0,1]
	v_pk_add_f32 v[30:31], v[202:203], v[204:205]
	v_pk_add_f32 v[32:33], v[202:203], v[204:205] neg_lo:[0,1] neg_hi:[0,1]
	v_pk_add_f32 v[202:203], v[26:27], v[28:29] op_sel:[0,1] op_sel_hi:[1,0] neg_hi:[0,1]
	v_pk_add_f32 v[204:205], v[26:27], v[28:29] op_sel:[0,1] op_sel_hi:[1,0] neg_lo:[0,1]
	v_pk_mul_f32 v[206:207], v[210:211], v[210:211] op_sel:[1,1] op_sel_hi:[1,0]
	v_pk_fma_f32 v[212:213], v[210:211], v[210:211], v[206:207] op_sel_hi:[0,1,1] neg_lo:[0,0,1]
	v_pk_mul_f32 v[206:207], v[210:211], v[212:213] op_sel:[1,1] op_sel_hi:[1,0]
	v_pk_fma_f32 v[220:221], v[210:211], v[212:213], v[206:207] op_sel_hi:[0,1,1] neg_lo:[0,0,1]
	v_pk_mul_f32 v[26:27], v[210:211], v[202:203] op_sel:[1,1] op_sel_hi:[1,0]
	v_pk_fma_f32 v[26:27], v[210:211], v[202:203], v[26:27] op_sel_hi:[0,1,1] neg_lo:[0,0,1]
	v_pk_mul_f32 v[28:29], v[212:213], v[32:33] op_sel:[1,1] op_sel_hi:[1,0]
	v_pk_fma_f32 v[28:29], v[212:213], v[32:33], v[28:29] op_sel_hi:[0,1,1] neg_lo:[0,0,1]
	v_pk_mul_f32 v[32:33], v[220:221], v[204:205] op_sel:[1,1] op_sel_hi:[1,0]
	v_pk_fma_f32 v[32:33], v[220:221], v[204:205], v[32:33] op_sel_hi:[0,1,1] neg_lo:[0,0,1]
	v_cos_f32_e32 v210, 0x3e000000
	v_sin_f32_e32 v211, 0xbe000000
	s_waitcnt lgkmcnt(6)
; DI f32x2 cmul(f32x2 a, f32x2 b) { return mkf2(a.x * b.x - a.y * b.y, a.x * b.y + a.y * b.x); }
; DI void fft8192(f32x2* buf, const f32x2* __restrict__ tw) {
;     ...
; #pragma unroll
;     for (int e = 0; e < 8; ++e) {
;       const int i = tid + 256 * e;
;       const int q = i & (s - 1);
;       const int ps = i - q;
;       const float rev = (float)ps * (1.f / 8192.f);
;       const f32x2 w1 = mkf2(__builtin_amdgcn_cosf(rev), -__builtin_amdgcn_sinf(rev));
;       const f32x2 w2 = cmul(w1, w1), w3 = cmul(w1, w2);
;       const f32x2 apc = mkf2(a[e].x + c[e].x, a[e].y + c[e].y), amc = mkf2(a[e].x - c[e].x, a[e].y - c[e].y);
;       const f32x2 bpd = mkf2(b[e].x + d[e].x, b[e].y + d[e].y), bmd = mkf2(b[e].x - d[e].x, b[e].y - d[e].y);
;       const int o = 4 * i - 3 * q;
;       buf[SW(o)] = mkf2(apc.x + bpd.x, apc.y + bpd.y);
;       buf[SW(o + s)] = cmul(w1, mkf2(amc.x + bmd.y, amc.y - bmd.x));
;       buf[SW(o + 2 * s)] = cmul(w2, mkf2(apc.x - bpd.x, apc.y - bpd.y));
;       buf[SW(o + 3 * s)] = cmul(w3, mkf2(amc.x - bmd.y, amc.y + bmd.x));
;     }
	v_pk_add_f32 v[202:203], v[34:35], v[38:39]
	v_pk_add_f32 v[34:35], v[34:35], v[38:39] neg_lo:[0,1] neg_hi:[0,1]
	v_pk_add_f32 v[204:205], v[36:37], v[40:41]
	v_pk_add_f32 v[36:37], v[36:37], v[40:41] neg_lo:[0,1] neg_hi:[0,1]
	v_pk_add_f32 v[38:39], v[202:203], v[204:205]
	v_pk_add_f32 v[40:41], v[202:203], v[204:205] neg_lo:[0,1] neg_hi:[0,1]
	v_pk_add_f32 v[202:203], v[34:35], v[36:37] op_sel:[0,1] op_sel_hi:[1,0] neg_hi:[0,1]
	v_pk_add_f32 v[204:205], v[34:35], v[36:37] op_sel:[0,1] op_sel_hi:[1,0] neg_lo:[0,1]
	v_pk_mul_f32 v[206:207], v[210:211], v[210:211] op_sel:[1,1] op_sel_hi:[1,0]
	v_pk_fma_f32 v[212:213], v[210:211], v[210:211], v[206:207] op_sel_hi:[0,1,1] neg_lo:[0,0,1]
	v_pk_mul_f32 v[206:207], v[210:211], v[212:213] op_sel:[1,1] op_sel_hi:[1,0]
	v_pk_fma_f32 v[220:221], v[210:211], v[212:213], v[206:207] op_sel_hi:[0,1,1] neg_lo:[0,0,1]
	v_pk_mul_f32 v[34:35], v[210:211], v[202:203] op_sel:[1,1] op_sel_hi:[1,0]
	v_pk_fma_f32 v[34:35], v[210:211], v[202:203], v[34:35] op_sel_hi:[0,1,1] neg_lo:[0,0,1]
	v_pk_mul_f32 v[36:37], v[212:213], v[40:41] op_sel:[1,1] op_sel_hi:[1,0]
	v_pk_fma_f32 v[36:37], v[212:213], v[40:41], v[36:37] op_sel_hi:[0,1,1] neg_lo:[0,0,1]
	v_pk_mul_f32 v[40:41], v[220:221], v[204:205] op_sel:[1,1] op_sel_hi:[1,0]
	v_pk_fma_f32 v[40:41], v[220:221], v[204:205], v[40:41] op_sel_hi:[0,1,1] neg_lo:[0,0,1]
	v_cos_f32_e32 v210, 0x3e200000
	v_sin_f32_e32 v211, 0xbe200000
	s_waitcnt lgkmcnt(4)
	v_pk_add_f32 v[202:203], v[42:43], v[46:47]
	v_pk_add_f32 v[42:43], v[42:43], v[46:47] neg_lo:[0,1] neg_hi:[0,1]
	v_pk_add_f32 v[204:205], v[44:45], v[48:49]
	v_pk_add_f32 v[44:45], v[44:45], v[48:49] neg_lo:[0,1] neg_hi:[0,1]
	v_pk_add_f32 v[46:47], v[202:203], v[204:205]
	v_pk_add_f32 v[48:49], v[202:203], v[204:205] neg_lo:[0,1] neg_hi:[0,1]
	v_pk_add_f32 v[202:203], v[42:43], v[44:45] op_sel:[0,1] op_sel_hi:[1,0] neg_hi:[0,1]
	v_pk_add_f32 v[204:205], v[42:43], v[44:45] op_sel:[0,1] op_sel_hi:[1,0] neg_lo:[0,1]
	v_pk_mul_f32 v[206:207], v[210:211], v[210:211] op_sel:[1,1] op_sel_hi:[1,0]
	v_pk_fma_f32 v[212:213], v[210:211], v[210:211], v[206:207] op_sel_hi:[0,1,1] neg_lo:[0,0,1]
	v_pk_mul_f32 v[206:207], v[210:211], v[212:213] op_sel:[1,1] op_sel_hi:[1,0]
	v_pk_fma_f32 v[220:221], v[210:211], v[212:213], v[206:207] op_sel_hi:[0,1,1] neg_lo:[0,0,1]
	v_pk_mul_f32 v[42:43], v[210:211], v[202:203] op_sel:[1,1] op_sel_hi:[1,0]
	v_pk_fma_f32 v[42:43], v[210:211], v[202:203], v[42:43] op_sel_hi:[0,1,1] neg_lo:[0,0,1]
	v_pk_mul_f32 v[44:45], v[212:213], v[48:49] op_sel:[1,1] op_sel_hi:[1,0]
	v_pk_fma_f32 v[44:45], v[212:213], v[48:49], v[44:45] op_sel_hi:[0,1,1] neg_lo:[0,0,1]
	v_pk_mul_f32 v[48:49], v[220:221], v[204:205] op_sel:[1,1] op_sel_hi:[1,0]
	v_pk_fma_f32 v[48:49], v[220:221], v[204:205], v[48:49] op_sel_hi:[0,1,1] neg_lo:[0,0,1]
	v_cos_f32_e32 v210, 0x3e400000
	v_sin_f32_e32 v211, 0xbe400000
	s_waitcnt lgkmcnt(2)
	v_pk_add_f32 v[202:203], v[50:51], v[54:55]
	v_pk_add_f32 v[50:51], v[50:51], v[54:55] neg_lo:[0,1] neg_hi:[0,1]
	v_pk_add_f32 v[204:205], v[52:53], v[56:57]
	v_pk_add_f32 v[52:53], v[52:53], v[56:57] neg_lo:[0,1] neg_hi:[0,1]
	v_pk_add_f32 v[54:55], v[202:203], v[204:205]
	v_pk_add_f32 v[56:57], v[202:203], v[204:205] neg_lo:[0,1] neg_hi:[0,1]
	v_pk_add_f32 v[202:203], v[50:51], v[52:53] op_sel:[0,1] op_sel_hi:[1,0] neg_hi:[0,1]
	v_pk_add_f32 v[204:205], v[50:51], v[52:53] op_sel:[0,1] op_sel_hi:[1,0] neg_lo:[0,1]
	v_pk_mul_f32 v[206:207], v[210:211], v[210:211] op_sel:[1,1] op_sel_hi:[1,0]
	v_pk_fma_f32 v[212:213], v[210:211], v[210:211], v[206:207] op_sel_hi:[0,1,1] neg_lo:[0,0,1]
	v_pk_mul_f32 v[206:207], v[210:211], v[212:213] op_sel:[1,1] op_sel_hi:[1,0]
	v_pk_fma_f32 v[220:221], v[210:211], v[212:213], v[206:207] op_sel_hi:[0,1,1] neg_lo:[0,0,1]
	v_pk_mul_f32 v[50:51], v[210:211], v[202:203] op_sel:[1,1] op_sel_hi:[1,0]
	v_pk_fma_f32 v[50:51], v[210:211], v[202:203], v[50:51] op_sel_hi:[0,1,1] neg_lo:[0,0,1]
	v_pk_mul_f32 v[52:53], v[212:213], v[56:57] op_sel:[1,1] op_sel_hi:[1,0]
	v_pk_fma_f32 v[52:53], v[212:213], v[56:57], v[52:53] op_sel_hi:[0,1,1] neg_lo:[0,0,1]
	v_pk_mul_f32 v[56:57], v[220:221], v[204:205] op_sel:[1,1] op_sel_hi:[1,0]
	v_pk_fma_f32 v[56:57], v[220:221], v[204:205], v[56:57] op_sel_hi:[0,1,1] neg_lo:[0,0,1]
	v_cos_f32_e32 v210, 0x3e600000
	v_sin_f32_e32 v211, 0xbe600000
	s_waitcnt lgkmcnt(0)
	v_pk_add_f32 v[202:203], v[58:59], v[62:63]
	v_pk_add_f32 v[58:59], v[58:59], v[62:63] neg_lo:[0,1] neg_hi:[0,1]
	v_pk_add_f32 v[204:205], v[60:61], v[64:65]
	v_pk_add_f32 v[60:61], v[60:61], v[64:65] neg_lo:[0,1] neg_hi:[0,1]
	v_pk_add_f32 v[62:63], v[202:203], v[204:205]
	v_pk_add_f32 v[64:65], v[202:203], v[204:205] neg_lo:[0,1] neg_hi:[0,1]
	v_pk_add_f32 v[202:203], v[58:59], v[60:61] op_sel:[0,1] op_sel_hi:[1,0] neg_hi:[0,1]
	v_pk_add_f32 v[204:205], v[58:59], v[60:61] op_sel:[0,1] op_sel_hi:[1,0] neg_lo:[0,1]
	v_pk_mul_f32 v[206:207], v[210:211], v[210:211] op_sel:[1,1] op_sel_hi:[1,0]
	v_pk_fma_f32 v[212:213], v[210:211], v[210:211], v[206:207] op_sel_hi:[0,1,1] neg_lo:[0,0,1]
	v_pk_mul_f32 v[206:207], v[210:211], v[212:213] op_sel:[1,1] op_sel_hi:[1,0]
	v_pk_fma_f32 v[220:221], v[210:211], v[212:213], v[206:207] op_sel_hi:[0,1,1] neg_lo:[0,0,1]
	v_pk_mul_f32 v[58:59], v[210:211], v[202:203] op_sel:[1,1] op_sel_hi:[1,0]
	v_pk_fma_f32 v[58:59], v[210:211], v[202:203], v[58:59] op_sel_hi:[0,1,1] neg_lo:[0,0,1]
	v_pk_mul_f32 v[60:61], v[212:213], v[64:65] op_sel:[1,1] op_sel_hi:[1,0]
	v_pk_fma_f32 v[60:61], v[212:213], v[64:65], v[60:61] op_sel_hi:[0,1,1] neg_lo:[0,0,1]
	v_pk_mul_f32 v[64:65], v[220:221], v[204:205] op_sel:[1,1] op_sel_hi:[1,0]
	v_pk_fma_f32 v[64:65], v[220:221], v[204:205], v[64:65] op_sel_hi:[0,1,1] neg_lo:[0,0,1]
	s_barrier
; DI f32x2 cmul(f32x2 a, f32x2 b) { return mkf2(a.x * b.x - a.y * b.y, a.x * b.y + a.y * b.x); }
; DI void fft8192(f32x2* buf, const f32x2* __restrict__ tw) {
;     ...
; #pragma unroll
;     for (int e = 0; e < 8; ++e) {
;       const int i = tid + 256 * e;
;       const int q = i & (s - 1);
;       const int ps = i - q;
;       const float rev = (float)ps * (1.f / 8192.f);
;       const f32x2 w1 = mkf2(__builtin_amdgcn_cosf(rev), -__builtin_amdgcn_sinf(rev));
;       const f32x2 w2 = cmul(w1, w1), w3 = cmul(w1, w2);
;       const f32x2 apc = mkf2(a[e].x + c[e].x, a[e].y + c[e].y), amc = mkf2(a[e].x - c[e].x, a[e].y - c[e].y);
;       const f32x2 bpd = mkf2(b[e].x + d[e].x, b[e].y + d[e].y), bmd = mkf2(b[e].x - d[e].x, b[e].y - d[e].y);
;       const int o = 4 * i - 3 * q;
;       buf[SW(o)] = mkf2(apc.x + bpd.x, apc.y + bpd.y);
;       buf[SW(o + s)] = cmul(w1, mkf2(amc.x + bmd.y, amc.y - bmd.x));
;       buf[SW(o + 2 * s)] = cmul(w2, mkf2(apc.x - bpd.x, apc.y - bpd.y));
;       buf[SW(o + 3 * s)] = cmul(w3, mkf2(amc.x - bmd.y, amc.y + bmd.x));
;     }
	v_pk_add_f32 v[202:203], v[6:7], v[38:39]
	v_pk_add_f32 v[6:7], v[6:7], v[38:39] neg_lo:[0,1] neg_hi:[0,1]
	v_pk_add_f32 v[204:205], v[22:23], v[54:55]
	v_pk_add_f32 v[22:23], v[22:23], v[54:55] neg_lo:[0,1] neg_hi:[0,1]
	v_pk_add_f32 v[38:39], v[202:203], v[204:205]
	v_pk_add_f32 v[54:55], v[202:203], v[204:205] neg_lo:[0,1] neg_hi:[0,1]
	v_pk_add_f32 v[202:203], v[6:7], v[22:23] op_sel:[0,1] op_sel_hi:[1,0] neg_hi:[0,1]
	v_pk_add_f32 v[22:23], v[6:7], v[22:23] op_sel:[0,1] op_sel_hi:[1,0] neg_lo:[0,1]
	v_pk_mov_b32 v[6:7], v[202:203], v[202:203] op_sel:[0,1]
	v_pk_add_f32 v[202:203], v[2:3], v[34:35]
	v_pk_add_f32 v[2:3], v[2:3], v[34:35] neg_lo:[0,1] neg_hi:[0,1]
	v_pk_add_f32 v[204:205], v[18:19], v[50:51]
	v_pk_add_f32 v[18:19], v[18:19], v[50:51] neg_lo:[0,1] neg_hi:[0,1]
	v_pk_add_f32 v[34:35], v[202:203], v[204:205]
	v_pk_add_f32 v[50:51], v[202:203], v[204:205] neg_lo:[0,1] neg_hi:[0,1]
	v_pk_add_f32 v[202:203], v[2:3], v[18:19] op_sel:[0,1] op_sel_hi:[1,0] neg_hi:[0,1]
	v_pk_add_f32 v[18:19], v[2:3], v[18:19] op_sel:[0,1] op_sel_hi:[1,0] neg_lo:[0,1]
	v_pk_mov_b32 v[2:3], v[202:203], v[202:203] op_sel:[0,1]
	v_pk_add_f32 v[202:203], v[8:9], v[36:37]
	v_pk_add_f32 v[8:9], v[8:9], v[36:37] neg_lo:[0,1] neg_hi:[0,1]
	v_pk_add_f32 v[204:205], v[20:21], v[52:53]
	v_pk_add_f32 v[20:21], v[20:21], v[52:53] neg_lo:[0,1] neg_hi:[0,1]
	v_pk_add_f32 v[36:37], v[202:203], v[204:205]
	v_pk_add_f32 v[52:53], v[202:203], v[204:205] neg_lo:[0,1] neg_hi:[0,1]
	v_pk_add_f32 v[202:203], v[8:9], v[20:21] op_sel:[0,1] op_sel_hi:[1,0] neg_hi:[0,1]
	v_pk_add_f32 v[20:21], v[8:9], v[20:21] op_sel:[0,1] op_sel_hi:[1,0] neg_lo:[0,1]
	v_pk_mov_b32 v[8:9], v[202:203], v[202:203] op_sel:[0,1]
	v_pk_add_f32 v[202:203], v[4:5], v[40:41]
	v_pk_add_f32 v[4:5], v[4:5], v[40:41] neg_lo:[0,1] neg_hi:[0,1]
	v_pk_add_f32 v[204:205], v[24:25], v[56:57]
	v_pk_add_f32 v[24:25], v[24:25], v[56:57] neg_lo:[0,1] neg_hi:[0,1]
	v_pk_add_f32 v[40:41], v[202:203], v[204:205]
	v_pk_add_f32 v[56:57], v[202:203], v[204:205] neg_lo:[0,1] neg_hi:[0,1]
	v_pk_add_f32 v[202:203], v[4:5], v[24:25] op_sel:[0,1] op_sel_hi:[1,0] neg_hi:[0,1]
	v_pk_add_f32 v[24:25], v[4:5], v[24:25] op_sel:[0,1] op_sel_hi:[1,0] neg_lo:[0,1]
	v_pk_mov_b32 v[4:5], v[202:203], v[202:203] op_sel:[0,1]
	v_cos_f32_e32 v224, 0x3e000000
	v_sin_f32_e32 v225, 0xbe000000
	s_nop 0
	v_pk_mul_f32 v[206:207], v[224:225], v[224:225] op_sel:[1,1] op_sel_hi:[1,0]
	v_pk_fma_f32 v[226:227], v[224:225], v[224:225], v[206:207] op_sel_hi:[0,1,1] neg_lo:[0,0,1]
	v_pk_mul_f32 v[206:207], v[224:225], v[226:227] op_sel:[1,1] op_sel_hi:[1,0]
	v_pk_fma_f32 v[230:231], v[224:225], v[226:227], v[206:207] op_sel_hi:[0,1,1] neg_lo:[0,0,1]
	v_pk_add_f32 v[202:203], v[14:15], v[46:47]
	v_pk_add_f32 v[14:15], v[14:15], v[46:47] neg_lo:[0,1] neg_hi:[0,1]
	v_pk_add_f32 v[204:205], v[30:31], v[62:63]
	v_pk_add_f32 v[30:31], v[30:31], v[62:63] neg_lo:[0,1] neg_hi:[0,1]
	v_pk_add_f32 v[46:47], v[202:203], v[204:205]
	v_pk_add_f32 v[62:63], v[202:203], v[204:205] neg_lo:[0,1] neg_hi:[0,1]
	v_pk_add_f32 v[202:203], v[14:15], v[30:31] op_sel:[0,1] op_sel_hi:[1,0] neg_hi:[0,1]
	v_pk_add_f32 v[204:205], v[14:15], v[30:31] op_sel:[0,1] op_sel_hi:[1,0] neg_lo:[0,1]
	v_pk_mul_f32 v[14:15], v[224:225], v[202:203] op_sel:[1,1] op_sel_hi:[1,0]
	v_pk_fma_f32 v[14:15], v[224:225], v[202:203], v[14:15] op_sel_hi:[0,1,1] neg_lo:[0,0,1]
	v_pk_mul_f32 v[30:31], v[226:227], v[62:63] op_sel:[1,1] op_sel_hi:[1,0]
	v_pk_fma_f32 v[30:31], v[226:227], v[62:63], v[30:31] op_sel_hi:[0,1,1] neg_lo:[0,0,1]
	v_pk_mul_f32 v[62:63], v[230:231], v[204:205] op_sel:[1,1] op_sel_hi:[1,0]
	v_pk_fma_f32 v[62:63], v[230:231], v[204:205], v[62:63] op_sel_hi:[0,1,1] neg_lo:[0,0,1]
	v_pk_add_f32 v[202:203], v[10:11], v[42:43]
	v_pk_add_f32 v[10:11], v[10:11], v[42:43] neg_lo:[0,1] neg_hi:[0,1]
	v_pk_add_f32 v[204:205], v[26:27], v[58:59]
	v_pk_add_f32 v[26:27], v[26:27], v[58:59] neg_lo:[0,1] neg_hi:[0,1]
	v_pk_add_f32 v[42:43], v[202:203], v[204:205]
	v_pk_add_f32 v[58:59], v[202:203], v[204:205] neg_lo:[0,1] neg_hi:[0,1]
	v_pk_add_f32 v[202:203], v[10:11], v[26:27] op_sel:[0,1] op_sel_hi:[1,0] neg_hi:[0,1]
	v_pk_add_f32 v[204:205], v[10:11], v[26:27] op_sel:[0,1] op_sel_hi:[1,0] neg_lo:[0,1]
	v_pk_mul_f32 v[10:11], v[224:225], v[202:203] op_sel:[1,1] op_sel_hi:[1,0]
	v_pk_fma_f32 v[10:11], v[224:225], v[202:203], v[10:11] op_sel_hi:[0,1,1] neg_lo:[0,0,1]
	v_pk_mul_f32 v[26:27], v[226:227], v[58:59] op_sel:[1,1] op_sel_hi:[1,0]
	v_pk_fma_f32 v[26:27], v[226:227], v[58:59], v[26:27] op_sel_hi:[0,1,1] neg_lo:[0,0,1]
	v_pk_mul_f32 v[58:59], v[230:231], v[204:205] op_sel:[1,1] op_sel_hi:[1,0]
	v_pk_fma_f32 v[58:59], v[230:231], v[204:205], v[58:59] op_sel_hi:[0,1,1] neg_lo:[0,0,1]
	v_pk_add_f32 v[202:203], v[12:13], v[44:45]
	v_pk_add_f32 v[12:13], v[12:13], v[44:45] neg_lo:[0,1] neg_hi:[0,1]
	v_pk_add_f32 v[204:205], v[28:29], v[60:61]
	v_pk_add_f32 v[28:29], v[28:29], v[60:61] neg_lo:[0,1] neg_hi:[0,1]
	v_pk_add_f32 v[44:45], v[202:203], v[204:205]
	v_pk_add_f32 v[60:61], v[202:203], v[204:205] neg_lo:[0,1] neg_hi:[0,1]
	v_pk_add_f32 v[202:203], v[12:13], v[28:29] op_sel:[0,1] op_sel_hi:[1,0] neg_hi:[0,1]
	v_pk_add_f32 v[204:205], v[12:13], v[28:29] op_sel:[0,1] op_sel_hi:[1,0] neg_lo:[0,1]
	v_pk_mul_f32 v[12:13], v[224:225], v[202:203] op_sel:[1,1] op_sel_hi:[1,0]
	v_pk_fma_f32 v[12:13], v[224:225], v[202:203], v[12:13] op_sel_hi:[0,1,1] neg_lo:[0,0,1]
	v_pk_mul_f32 v[28:29], v[226:227], v[60:61] op_sel:[1,1] op_sel_hi:[1,0]
	v_pk_fma_f32 v[28:29], v[226:227], v[60:61], v[28:29] op_sel_hi:[0,1,1] neg_lo:[0,0,1]
	v_pk_mul_f32 v[60:61], v[230:231], v[204:205] op_sel:[1,1] op_sel_hi:[1,0]
; DI float bf2f(u16 v) { return __uint_as_float(((unsigned)v) << 16); }
; DI void fft8192(f32x2* buf, const f32x2* __restrict__ tw) {
;     ...
;     for (int e = 0; e < 16; ++e) {
;       const int pi = SW(tid + 256 * e);
;       buf[pi] = mkf2(a[e].x + b[e].x, a[e].y + b[e].y);
;       buf[pi + 4096] = mkf2(a[e].x - b[e].x, a[e].y - b[e].y);
;     }
; DI float sconv3(const u16* row, int t, int n, float w0, float w1, float w2, float bias) {
;   float xm = (t > 0) ? bf2f(row[t - 1]) : 0.f, x0 = bf2f(row[t]), xp = (t + 1 < n) ? bf2f(row[t + 1]) : 0.f;
;   return w0 * xm + w1 * x0 + w2 * xp + bias;
; DI void hyena_unit(KP p, int l, int c, char* smem) {
;     ...
;       const u16* g0 = Zhy + (size_t)(b0 * 1536 + gcol) * 4096;
;       const u16* g1 = Zhy + (size_t)(b1 * 1536 + gcol) * 4096;
; #pragma unroll 4
;       for (int jj = 0; jj < 16; ++jj) {
;         const int t = tid + 256 * jj;
;         const f32x2 r = buf[SW(t)];
;         const float y0 = r.x * (1.f / 8192.f), y1 = -r.y * (1.f / 8192.f);
;         const float x0 = sconv3(g0, t, 4096, gw0, gw1, gw2, gb), x1 = sconv3(g1, t, 4096, gw0, gw1, gw2, gb);
	v_pk_fma_f32 v[60:61], v[230:231], v[204:205], v[60:61] op_sel_hi:[0,1,1] neg_lo:[0,0,1]
	v_pk_add_f32 v[202:203], v[16:17], v[48:49]
	v_pk_add_f32 v[16:17], v[16:17], v[48:49] neg_lo:[0,1] neg_hi:[0,1]
	v_pk_add_f32 v[204:205], v[32:33], v[64:65]
	v_pk_add_f32 v[32:33], v[32:33], v[64:65] neg_lo:[0,1] neg_hi:[0,1]
	v_pk_add_f32 v[48:49], v[202:203], v[204:205]
	v_pk_add_f32 v[64:65], v[202:203], v[204:205] neg_lo:[0,1] neg_hi:[0,1]
	v_pk_add_f32 v[202:203], v[16:17], v[32:33] op_sel:[0,1] op_sel_hi:[1,0] neg_hi:[0,1]
	v_pk_add_f32 v[204:205], v[16:17], v[32:33] op_sel:[0,1] op_sel_hi:[1,0] neg_lo:[0,1]
	v_pk_mul_f32 v[16:17], v[224:225], v[202:203] op_sel:[1,1] op_sel_hi:[1,0]
	v_pk_fma_f32 v[16:17], v[224:225], v[202:203], v[16:17] op_sel_hi:[0,1,1] neg_lo:[0,0,1]
	v_pk_mul_f32 v[32:33], v[226:227], v[64:65] op_sel:[1,1] op_sel_hi:[1,0]
	v_pk_fma_f32 v[32:33], v[226:227], v[64:65], v[32:33] op_sel_hi:[0,1,1] neg_lo:[0,0,1]
	v_pk_mul_f32 v[64:65], v[230:231], v[204:205] op_sel:[1,1] op_sel_hi:[1,0]
	v_pk_fma_f32 v[64:65], v[230:231], v[204:205], v[64:65] op_sel_hi:[0,1,1] neg_lo:[0,0,1]
	v_pk_add_f32 v[202:203], v[38:39], v[46:47]
	v_pk_add_f32 v[204:205], v[34:35], v[42:43]
	v_pk_add_f32 v[206:207], v[36:37], v[44:45]
	v_pk_add_f32 v[208:209], v[40:41], v[48:49]
	v_pk_add_f32 v[210:211], v[6:7], v[14:15]
	v_pk_add_f32 v[212:213], v[2:3], v[10:11]
	v_pk_add_f32 v[220:221], v[8:9], v[12:13]
	v_pk_add_f32 v[224:225], v[4:5], v[16:17]
	v_pk_add_f32 v[226:227], v[54:55], v[30:31]
	v_pk_add_f32 v[230:231], v[50:51], v[26:27]
	v_pk_add_f32 v[232:233], v[52:53], v[28:29]
	v_pk_add_f32 v[236:237], v[56:57], v[32:33]
	v_pk_add_f32 v[238:239], v[22:23], v[62:63]
	v_pk_add_f32 v[240:241], v[18:19], v[58:59]
	v_pk_add_f32 v[244:245], v[20:21], v[60:61]
	v_pk_add_f32 v[246:247], v[24:25], v[64:65]
	ds_write_b64 v154, v[202:203] offset:0
	ds_write_b64 v154, v[204:205] offset:2048
	ds_write_b64 v154, v[206:207] offset:4096
	ds_write_b64 v154, v[208:209] offset:6144
	ds_write_b64 v154, v[210:211] offset:8192
	ds_write_b64 v154, v[212:213] offset:10240
	ds_write_b64 v154, v[220:221] offset:12288
	ds_write_b64 v154, v[224:225] offset:14336
	ds_write_b64 v154, v[226:227] offset:16384
	ds_write_b64 v154, v[230:231] offset:18432
	ds_write_b64 v154, v[232:233] offset:20480
	ds_write_b64 v154, v[236:237] offset:22528
	ds_write_b64 v154, v[238:239] offset:24576
	ds_write_b64 v154, v[240:241] offset:26624
	ds_write_b64 v154, v[244:245] offset:28672
	ds_write_b64 v154, v[246:247] offset:30720
	s_lshl_b32 s2, s83, 11
	s_lshl_b32 s4, s78, 10
	s_sub_i32 s2, s28, s2
	s_sub_i32 s4, s6, s4
	s_ashr_i32 s3, s2, 31
	s_ashr_i32 s5, s4, 31
	s_lshl_b64 s[2:3], s[2:3], 13
	s_lshl_b64 s[4:5], s[4:5], 13
	s_add_u32 s8, s55, s2
	s_addc_u32 s9, s81, s3
	s_add_u32 s10, s55, s4
	s_addc_u32 s11, s81, s5
	s_add_i32 s2, s82, s21
	s_ashr_i32 s3, s2, 31
	s_lshl_b64 s[2:3], s[2:3], 13
	s_add_u32 s6, s80, s2
	s_addc_u32 s7, s76, s3
	s_add_i32 s4, s29, s21
	s_ashr_i32 s5, s4, 31
	s_lshl_b64 s[4:5], s[4:5], 13
	s_add_u32 s12, s80, s4
	s_addc_u32 s13, s76, s5
	s_and_b64 s[4:5], s[96:97], exec
	s_cselect_b32 s5, s25, s9
	s_cselect_b32 s4, s24, s8
	s_cselect_b32 s9, s27, s11
	s_cselect_b32 s8, s26, s10
	v_lshl_add_u64 v[4:5], s[4:5], 0, v[68:69]
	s_add_i32 s4, s77, s82
	s_ashr_i32 s5, s4, 31
	s_lshl_b64 s[4:5], s[4:5], 13
	v_lshl_add_u64 v[2:3], s[8:9], 0, v[68:69]
	v_lshl_add_u64 v[6:7], v[70:71], 0, s[4:5]
	v_lshl_add_u64 v[8:9], v[70:71], 0, s[2:3]
	s_mov_b64 s[22:23], 0
	v_mov_b32_e32 v198, v66
	s_waitcnt lgkmcnt(0)
	s_barrier
	v_lshlrev_b32_e32 v201, 1, v66
	v_xor_b32_e32 v203, v66, v155
	v_add_u32_e32 v202, 0x1000, v201
	v_lshlrev_b32_e32 v203, 3, v203
	s_mov_b64 s[8:9], 0x1000
	v_lshl_add_u64 v[204:205], v[4:5], 0, s[8:9]
	v_lshl_add_u64 v[206:207], v[2:3], 0, s[8:9]
	v_cmp_eq_u32_e64 s[8:9], 0, v66
	v_cmp_eq_u32_e32 vcc, 0xff, v66
	s_mov_b64 s[10:11], vcc
	ds_read_b64 v[224:225], v203
	ds_read_b64 v[226:227], v203 offset:2048
	ds_read_b64 v[230:231], v203 offset:4096
	ds_read_b64 v[232:233], v203 offset:6144
	ds_read_b64 v[236:237], v203 offset:8192
	ds_read_b64 v[238:239], v203 offset:10240
	ds_read_b64 v[240:241], v203 offset:12288
	ds_read_b64 v[244:245], v203 offset:14336
	global_load_ushort v10, v201, s[6:7] offset:-2
	global_load_ushort v11, v201, s[6:7] offset:0
	global_load_ushort v12, v201, s[6:7] offset:2
	global_load_ushort v13, v201, s[12:13] offset:-2
	global_load_ushort v14, v201, s[12:13] offset:0
	global_load_ushort v15, v201, s[12:13] offset:2
	global_load_ushort v16, v201, s[6:7] offset:510
	global_load_ushort v17, v201, s[6:7] offset:512
	global_load_ushort v18, v201, s[6:7] offset:514
	global_load_ushort v19, v201, s[12:13] offset:510
	global_load_ushort v20, v201, s[12:13] offset:512
	global_load_ushort v21, v201, s[12:13] offset:514
	global_load_ushort v22, v201, s[6:7] offset:1022
	global_load_ushort v23, v201, s[6:7] offset:1024
	global_load_ushort v24, v201, s[6:7] offset:1026
	global_load_ushort v25, v201, s[12:13] offset:1022
	global_load_ushort v26, v201, s[12:13] offset:1024
	global_load_ushort v27, v201, s[12:13] offset:1026
	global_load_ushort v28, v201, s[6:7] offset:1534
	global_load_ushort v29, v201, s[6:7] offset:1536
	global_load_ushort v30, v201, s[6:7] offset:1538
	global_load_ushort v31, v201, s[12:13] offset:1534
	global_load_ushort v32, v201, s[12:13] offset:1536
	global_load_ushort v34, v201, s[12:13] offset:1538
	global_load_ushort v35, v201, s[6:7] offset:2046
	global_load_ushort v36, v201, s[6:7] offset:2048
	global_load_ushort v37, v201, s[6:7] offset:2050
	global_load_ushort v38, v201, s[12:13] offset:2046
	global_load_ushort v39, v201, s[12:13] offset:2048
	global_load_ushort v40, v201, s[12:13] offset:2050
	global_load_ushort v41, v201, s[6:7] offset:2558
	global_load_ushort v42, v201, s[6:7] offset:2560
	global_load_ushort v43, v201, s[6:7] offset:2562
	global_load_ushort v44, v201, s[12:13] offset:2558
	global_load_ushort v45, v201, s[12:13] offset:2560
	global_load_ushort v46, v201, s[12:13] offset:2562
	global_load_ushort v47, v201, s[6:7] offset:3070
	global_load_ushort v48, v201, s[6:7] offset:3072
	global_load_ushort v49, v201, s[6:7] offset:3074
	global_load_ushort v50, v201, s[12:13] offset:3070
	global_load_ushort v51, v201, s[12:13] offset:3072
	global_load_ushort v52, v201, s[12:13] offset:3074
	global_load_ushort v53, v201, s[6:7] offset:3582
	global_load_ushort v54, v201, s[6:7] offset:3584
	global_load_ushort v55, v201, s[6:7] offset:3586
	global_load_ushort v56, v201, s[12:13] offset:3582
	global_load_ushort v57, v201, s[12:13] offset:3584
	global_load_ushort v58, v201, s[12:13] offset:3586
	s_waitcnt vmcnt(42)
; DI float bf2f(u16 v) { return __uint_as_float(((unsigned)v) << 16); }
; DI float sconv3(const u16* row, int t, int n, float w0, float w1, float w2, float bias) {
;   float xm = (t > 0) ? bf2f(row[t - 1]) : 0.f, x0 = bf2f(row[t]), xp = (t + 1 < n) ? bf2f(row[t + 1]) : 0.f;
;   return w0 * xm + w1 * x0 + w2 * xp + bias;
; DI void hyena_unit(KP p, int l, int c, char* smem) {
;     ...
; #pragma unroll 4
;       for (int jj = 0; jj < 16; ++jj) {
;         const int t = tid + 256 * jj;
;         const f32x2 r = buf[SW(t)];
;         const float y0 = r.x * (1.f / 8192.f), y1 = -r.y * (1.f / 8192.f);
;         const float x0 = sconv3(g0, t, 4096, gw0, gw1, gw2, gb), x1 = sconv3(g1, t, 4096, gw0, gw1, gw2, gb);
;         if (o == 0) { r0[t] = f2bf(x0 * y0); r1[t] = f2bf(x1 * y1); }
;         else { y0p[t] = f2bf(x0 * y0); y1p[t] = f2bf(x1 * y1); }
;       }
	s_waitcnt lgkmcnt(0)
	v_cndmask_b32_e64 v10, v10, 0, s[8:9]
	v_cndmask_b32_e64 v13, v13, 0, s[8:9]
	v_lshlrev_b32_e32 v10, 16, v10
	v_lshlrev_b32_e32 v11, 16, v11
	v_lshlrev_b32_e32 v12, 16, v12
	v_lshlrev_b32_e32 v13, 16, v13
	v_lshlrev_b32_e32 v14, 16, v14
	v_lshlrev_b32_e32 v15, 16, v15
	v_mul_f32_e32 v11, v196, v11
	v_mul_f32_e32 v14, v196, v14
	v_fmac_f32_e32 v11, v74, v10
	v_fmac_f32_e32 v14, v74, v13
	v_fmac_f32_e32 v11, v75, v12
	v_fmac_f32_e32 v14, v75, v15
	v_mul_f32_e32 v10, 0x39000000, v224
	v_mul_f32_e32 v13, 0xb9000000, v225
	v_add_f32_e32 v11, v195, v11
	v_add_f32_e32 v14, v195, v14
	v_mul_f32_e32 v10, v10, v11
	v_mul_f32_e32 v13, v13, v14
	v_cvt_pk_bf16_f32 v10, v10, v10
	v_cvt_pk_bf16_f32 v13, v13, v13
	global_store_short v[4:5], v10, off
	global_store_short v[2:3], v13, off
	s_nop 0
	global_load_ushort v10, v202, s[6:7] offset:-2
	global_load_ushort v11, v202, s[6:7] offset:0
	global_load_ushort v12, v202, s[6:7] offset:2
	global_load_ushort v13, v202, s[12:13] offset:-2
	global_load_ushort v14, v202, s[12:13] offset:0
	global_load_ushort v15, v202, s[12:13] offset:2
	s_waitcnt vmcnt(44)
	v_lshlrev_b32_e32 v16, 16, v16
	v_lshlrev_b32_e32 v17, 16, v17
	v_lshlrev_b32_e32 v18, 16, v18
	v_lshlrev_b32_e32 v19, 16, v19
	v_lshlrev_b32_e32 v20, 16, v20
	v_lshlrev_b32_e32 v21, 16, v21
	v_mul_f32_e32 v17, v196, v17
	v_mul_f32_e32 v20, v196, v20
	v_fmac_f32_e32 v17, v74, v16
	v_fmac_f32_e32 v20, v74, v19
	v_fmac_f32_e32 v17, v75, v18
	v_fmac_f32_e32 v20, v75, v21
	v_mul_f32_e32 v16, 0x39000000, v226
	v_mul_f32_e32 v19, 0xb9000000, v227
	v_add_f32_e32 v17, v195, v17
	v_add_f32_e32 v20, v195, v20
	v_mul_f32_e32 v16, v16, v17
	v_mul_f32_e32 v19, v19, v20
	v_cvt_pk_bf16_f32 v16, v16, v16
	v_cvt_pk_bf16_f32 v19, v19, v19
	global_store_short v[4:5], v16, off offset:512
	global_store_short v[2:3], v19, off offset:512
	s_nop 0
	global_load_ushort v16, v202, s[6:7] offset:510
	global_load_ushort v17, v202, s[6:7] offset:512
	global_load_ushort v18, v202, s[6:7] offset:514
	global_load_ushort v19, v202, s[12:13] offset:510
	global_load_ushort v20, v202, s[12:13] offset:512
	global_load_ushort v21, v202, s[12:13] offset:514
	s_waitcnt vmcnt(46)
	v_lshlrev_b32_e32 v22, 16, v22
	v_lshlrev_b32_e32 v23, 16, v23
	v_lshlrev_b32_e32 v24, 16, v24
	v_lshlrev_b32_e32 v25, 16, v25
	v_lshlrev_b32_e32 v26, 16, v26
	v_lshlrev_b32_e32 v27, 16, v27
	v_mul_f32_e32 v23, v196, v23
	v_mul_f32_e32 v26, v196, v26
	v_fmac_f32_e32 v23, v74, v22
	v_fmac_f32_e32 v26, v74, v25
	v_fmac_f32_e32 v23, v75, v24
	v_fmac_f32_e32 v26, v75, v27
	v_mul_f32_e32 v22, 0x39000000, v230
	v_mul_f32_e32 v25, 0xb9000000, v231
	v_add_f32_e32 v23, v195, v23
	v_add_f32_e32 v26, v195, v26
	v_mul_f32_e32 v22, v22, v23
	v_mul_f32_e32 v25, v25, v26
	v_cvt_pk_bf16_f32 v22, v22, v22
	v_cvt_pk_bf16_f32 v25, v25, v25
	global_store_short v[4:5], v22, off offset:1024
	global_store_short v[2:3], v25, off offset:1024
	s_nop 0
	global_load_ushort v22, v202, s[6:7] offset:1022
	global_load_ushort v23, v202, s[6:7] offset:1024
	global_load_ushort v24, v202, s[6:7] offset:1026
	global_load_ushort v25, v202, s[12:13] offset:1022
	global_load_ushort v26, v202, s[12:13] offset:1024
	global_load_ushort v27, v202, s[12:13] offset:1026
	s_waitcnt vmcnt(48)
	v_lshlrev_b32_e32 v28, 16, v28
	v_lshlrev_b32_e32 v29, 16, v29
	v_lshlrev_b32_e32 v30, 16, v30
	v_lshlrev_b32_e32 v31, 16, v31
	v_lshlrev_b32_e32 v32, 16, v32
	v_lshlrev_b32_e32 v34, 16, v34
	v_mul_f32_e32 v29, v196, v29
	v_mul_f32_e32 v32, v196, v32
	v_fmac_f32_e32 v29, v74, v28
	v_fmac_f32_e32 v32, v74, v31
	v_fmac_f32_e32 v29, v75, v30
	v_fmac_f32_e32 v32, v75, v34
	v_mul_f32_e32 v28, 0x39000000, v232
	v_mul_f32_e32 v31, 0xb9000000, v233
	v_add_f32_e32 v29, v195, v29
	v_add_f32_e32 v32, v195, v32
	v_mul_f32_e32 v28, v28, v29
	v_mul_f32_e32 v31, v31, v32
	v_cvt_pk_bf16_f32 v28, v28, v28
	v_cvt_pk_bf16_f32 v31, v31, v31
	global_store_short v[4:5], v28, off offset:1536
	global_store_short v[2:3], v31, off offset:1536
	s_nop 0
	global_load_ushort v28, v202, s[6:7] offset:1534
	global_load_ushort v29, v202, s[6:7] offset:1536
	global_load_ushort v30, v202, s[6:7] offset:1538
	global_load_ushort v31, v202, s[12:13] offset:1534
	global_load_ushort v32, v202, s[12:13] offset:1536
	global_load_ushort v34, v202, s[12:13] offset:1538
	s_waitcnt vmcnt(50)
	v_lshlrev_b32_e32 v35, 16, v35
	v_lshlrev_b32_e32 v36, 16, v36
	v_lshlrev_b32_e32 v37, 16, v37
	v_lshlrev_b32_e32 v38, 16, v38
	v_lshlrev_b32_e32 v39, 16, v39
	v_lshlrev_b32_e32 v40, 16, v40
	v_mul_f32_e32 v36, v196, v36
	v_mul_f32_e32 v39, v196, v39
	v_fmac_f32_e32 v36, v74, v35
	v_fmac_f32_e32 v39, v74, v38
	v_fmac_f32_e32 v36, v75, v37
	v_fmac_f32_e32 v39, v75, v40
	v_mul_f32_e32 v35, 0x39000000, v236
	v_mul_f32_e32 v38, 0xb9000000, v237
	v_add_f32_e32 v36, v195, v36
	v_add_f32_e32 v39, v195, v39
	v_mul_f32_e32 v35, v35, v36
	v_mul_f32_e32 v38, v38, v39
	v_cvt_pk_bf16_f32 v35, v35, v35
	v_cvt_pk_bf16_f32 v38, v38, v38
	global_store_short v[4:5], v35, off offset:2048
	global_store_short v[2:3], v38, off offset:2048
	s_nop 0
	global_load_ushort v35, v202, s[6:7] offset:2046
	global_load_ushort v36, v202, s[6:7] offset:2048
	global_load_ushort v37, v202, s[6:7] offset:2050
	global_load_ushort v38, v202, s[12:13] offset:2046
	global_load_ushort v39, v202, s[12:13] offset:2048
	global_load_ushort v40, v202, s[12:13] offset:2050
	s_waitcnt vmcnt(52)
; DI float bf2f(u16 v) { return __uint_as_float(((unsigned)v) << 16); }
; DI float sconv3(const u16* row, int t, int n, float w0, float w1, float w2, float bias) {
;   float xm = (t > 0) ? bf2f(row[t - 1]) : 0.f, x0 = bf2f(row[t]), xp = (t + 1 < n) ? bf2f(row[t + 1]) : 0.f;
;   return w0 * xm + w1 * x0 + w2 * xp + bias;
; DI void hyena_unit(KP p, int l, int c, char* smem) {
;     ...
; #pragma unroll 4
;       for (int jj = 0; jj < 16; ++jj) {
;         const int t = tid + 256 * jj;
;         const f32x2 r = buf[SW(t)];
;         const float y0 = r.x * (1.f / 8192.f), y1 = -r.y * (1.f / 8192.f);
;         const float x0 = sconv3(g0, t, 4096, gw0, gw1, gw2, gb), x1 = sconv3(g1, t, 4096, gw0, gw1, gw2, gb);
;         if (o == 0) { r0[t] = f2bf(x0 * y0); r1[t] = f2bf(x1 * y1); }
;         else { y0p[t] = f2bf(x0 * y0); y1p[t] = f2bf(x1 * y1); }
;       }
	v_lshlrev_b32_e32 v41, 16, v41
	v_lshlrev_b32_e32 v42, 16, v42
	v_lshlrev_b32_e32 v43, 16, v43
	v_lshlrev_b32_e32 v44, 16, v44
	v_lshlrev_b32_e32 v45, 16, v45
	v_lshlrev_b32_e32 v46, 16, v46
	v_mul_f32_e32 v42, v196, v42
	v_mul_f32_e32 v45, v196, v45
	v_fmac_f32_e32 v42, v74, v41
	v_fmac_f32_e32 v45, v74, v44
	v_fmac_f32_e32 v42, v75, v43
	v_fmac_f32_e32 v45, v75, v46
	v_mul_f32_e32 v41, 0x39000000, v238
	v_mul_f32_e32 v44, 0xb9000000, v239
	v_add_f32_e32 v42, v195, v42
	v_add_f32_e32 v45, v195, v45
	v_mul_f32_e32 v41, v41, v42
	v_mul_f32_e32 v44, v44, v45
	v_cvt_pk_bf16_f32 v41, v41, v41
	v_cvt_pk_bf16_f32 v44, v44, v44
	global_store_short v[4:5], v41, off offset:2560
	global_store_short v[2:3], v44, off offset:2560
	s_nop 0
	global_load_ushort v41, v202, s[6:7] offset:2558
	global_load_ushort v42, v202, s[6:7] offset:2560
	global_load_ushort v43, v202, s[6:7] offset:2562
	global_load_ushort v44, v202, s[12:13] offset:2558
	global_load_ushort v45, v202, s[12:13] offset:2560
	global_load_ushort v46, v202, s[12:13] offset:2562
	s_waitcnt vmcnt(54)
	v_lshlrev_b32_e32 v47, 16, v47
	v_lshlrev_b32_e32 v48, 16, v48
	v_lshlrev_b32_e32 v49, 16, v49
	v_lshlrev_b32_e32 v50, 16, v50
	v_lshlrev_b32_e32 v51, 16, v51
	v_lshlrev_b32_e32 v52, 16, v52
	v_mul_f32_e32 v48, v196, v48
	v_mul_f32_e32 v51, v196, v51
	v_fmac_f32_e32 v48, v74, v47
	v_fmac_f32_e32 v51, v74, v50
	v_fmac_f32_e32 v48, v75, v49
	v_fmac_f32_e32 v51, v75, v52
	v_mul_f32_e32 v47, 0x39000000, v240
	v_mul_f32_e32 v50, 0xb9000000, v241
	v_add_f32_e32 v48, v195, v48
	v_add_f32_e32 v51, v195, v51
	v_mul_f32_e32 v47, v47, v48
	v_mul_f32_e32 v50, v50, v51
	v_cvt_pk_bf16_f32 v47, v47, v47
	v_cvt_pk_bf16_f32 v50, v50, v50
	global_store_short v[4:5], v47, off offset:3072
	global_store_short v[2:3], v50, off offset:3072
	s_nop 0
	global_load_ushort v47, v202, s[6:7] offset:3070
	global_load_ushort v48, v202, s[6:7] offset:3072
	global_load_ushort v49, v202, s[6:7] offset:3074
	global_load_ushort v50, v202, s[12:13] offset:3070
	global_load_ushort v51, v202, s[12:13] offset:3072
	global_load_ushort v52, v202, s[12:13] offset:3074
	s_waitcnt vmcnt(56)
	v_lshlrev_b32_e32 v53, 16, v53
	v_lshlrev_b32_e32 v54, 16, v54
	v_lshlrev_b32_e32 v55, 16, v55
	v_lshlrev_b32_e32 v56, 16, v56
	v_lshlrev_b32_e32 v57, 16, v57
	v_lshlrev_b32_e32 v58, 16, v58
	v_mul_f32_e32 v54, v196, v54
	v_mul_f32_e32 v57, v196, v57
	v_fmac_f32_e32 v54, v74, v53
	v_fmac_f32_e32 v57, v74, v56
	v_fmac_f32_e32 v54, v75, v55
	v_fmac_f32_e32 v57, v75, v58
	v_mul_f32_e32 v53, 0x39000000, v244
	v_mul_f32_e32 v56, 0xb9000000, v245
	v_add_f32_e32 v54, v195, v54
	v_add_f32_e32 v57, v195, v57
	v_mul_f32_e32 v53, v53, v54
	v_mul_f32_e32 v56, v56, v57
	v_cvt_pk_bf16_f32 v53, v53, v53
	v_cvt_pk_bf16_f32 v56, v56, v56
	global_store_short v[4:5], v53, off offset:3584
	global_store_short v[2:3], v56, off offset:3584
	s_nop 0
	global_load_ushort v53, v202, s[6:7] offset:3582
	global_load_ushort v54, v202, s[6:7] offset:3584
	global_load_ushort v55, v202, s[6:7] offset:3586
	global_load_ushort v56, v202, s[12:13] offset:3582
	global_load_ushort v57, v202, s[12:13] offset:3584
	global_load_ushort v58, v202, s[12:13] offset:3586
	ds_read_b64 v[224:225], v203 offset:16384
	ds_read_b64 v[226:227], v203 offset:18432
	ds_read_b64 v[230:231], v203 offset:20480
	ds_read_b64 v[232:233], v203 offset:22528
	ds_read_b64 v[236:237], v203 offset:24576
	ds_read_b64 v[238:239], v203 offset:26624
	ds_read_b64 v[240:241], v203 offset:28672
	ds_read_b64 v[244:245], v203 offset:30720
	s_waitcnt vmcnt(56)
	s_waitcnt lgkmcnt(0)
	v_lshlrev_b32_e32 v10, 16, v10
	v_lshlrev_b32_e32 v11, 16, v11
	v_lshlrev_b32_e32 v12, 16, v12
	v_lshlrev_b32_e32 v13, 16, v13
	v_lshlrev_b32_e32 v14, 16, v14
	v_lshlrev_b32_e32 v15, 16, v15
	v_mul_f32_e32 v11, v196, v11
	v_mul_f32_e32 v14, v196, v14
	v_fmac_f32_e32 v11, v74, v10
	v_fmac_f32_e32 v14, v74, v13
	v_fmac_f32_e32 v11, v75, v12
	v_fmac_f32_e32 v14, v75, v15
	v_mul_f32_e32 v10, 0x39000000, v224
	v_mul_f32_e32 v13, 0xb9000000, v225
	v_add_f32_e32 v11, v195, v11
	v_add_f32_e32 v14, v195, v14
	v_mul_f32_e32 v10, v10, v11
	v_mul_f32_e32 v13, v13, v14
	v_cvt_pk_bf16_f32 v10, v10, v10
	v_cvt_pk_bf16_f32 v13, v13, v13
	global_store_short v[204:205], v10, off
	global_store_short v[206:207], v13, off
	s_waitcnt vmcnt(50)
	v_lshlrev_b32_e32 v16, 16, v16
	v_lshlrev_b32_e32 v17, 16, v17
	v_lshlrev_b32_e32 v18, 16, v18
	v_lshlrev_b32_e32 v19, 16, v19
	v_lshlrev_b32_e32 v20, 16, v20
	v_lshlrev_b32_e32 v21, 16, v21
	v_mul_f32_e32 v17, v196, v17
	v_mul_f32_e32 v20, v196, v20
	v_fmac_f32_e32 v17, v74, v16
	v_fmac_f32_e32 v20, v74, v19
	v_fmac_f32_e32 v17, v75, v18
	v_fmac_f32_e32 v20, v75, v21
	v_mul_f32_e32 v16, 0x39000000, v226
	v_mul_f32_e32 v19, 0xb9000000, v227
	v_add_f32_e32 v17, v195, v17
	v_add_f32_e32 v20, v195, v20
	v_mul_f32_e32 v16, v16, v17
	v_mul_f32_e32 v19, v19, v20
	v_cvt_pk_bf16_f32 v16, v16, v16
	v_cvt_pk_bf16_f32 v19, v19, v19
	global_store_short v[204:205], v16, off offset:512
	global_store_short v[206:207], v19, off offset:512
	s_waitcnt vmcnt(44)
; DI float bf2f(u16 v) { return __uint_as_float(((unsigned)v) << 16); }
; DI float sconv3(const u16* row, int t, int n, float w0, float w1, float w2, float bias) {
;   float xm = (t > 0) ? bf2f(row[t - 1]) : 0.f, x0 = bf2f(row[t]), xp = (t + 1 < n) ? bf2f(row[t + 1]) : 0.f;
;   return w0 * xm + w1 * x0 + w2 * xp + bias;
; DI void hyena_unit(KP p, int l, int c, char* smem) {
;     ...
; #pragma unroll 4
;       for (int jj = 0; jj < 16; ++jj) {
;         const int t = tid + 256 * jj;
;         const f32x2 r = buf[SW(t)];
;         const float y0 = r.x * (1.f / 8192.f), y1 = -r.y * (1.f / 8192.f);
;         const float x0 = sconv3(g0, t, 4096, gw0, gw1, gw2, gb), x1 = sconv3(g1, t, 4096, gw0, gw1, gw2, gb);
;         if (o == 0) { r0[t] = f2bf(x0 * y0); r1[t] = f2bf(x1 * y1); }
;         else { y0p[t] = f2bf(x0 * y0); y1p[t] = f2bf(x1 * y1); }
;       }
	v_lshlrev_b32_e32 v22, 16, v22
	v_lshlrev_b32_e32 v23, 16, v23
	v_lshlrev_b32_e32 v24, 16, v24
	v_lshlrev_b32_e32 v25, 16, v25
	v_lshlrev_b32_e32 v26, 16, v26
	v_lshlrev_b32_e32 v27, 16, v27
	v_mul_f32_e32 v23, v196, v23
	v_mul_f32_e32 v26, v196, v26
	v_fmac_f32_e32 v23, v74, v22
	v_fmac_f32_e32 v26, v74, v25
	v_fmac_f32_e32 v23, v75, v24
	v_fmac_f32_e32 v26, v75, v27
	v_mul_f32_e32 v22, 0x39000000, v230
	v_mul_f32_e32 v25, 0xb9000000, v231
	v_add_f32_e32 v23, v195, v23
	v_add_f32_e32 v26, v195, v26
	v_mul_f32_e32 v22, v22, v23
	v_mul_f32_e32 v25, v25, v26
	v_cvt_pk_bf16_f32 v22, v22, v22
	v_cvt_pk_bf16_f32 v25, v25, v25
	global_store_short v[204:205], v22, off offset:1024
	global_store_short v[206:207], v25, off offset:1024
	s_waitcnt vmcnt(38)
	v_lshlrev_b32_e32 v28, 16, v28
	v_lshlrev_b32_e32 v29, 16, v29
	v_lshlrev_b32_e32 v30, 16, v30
	v_lshlrev_b32_e32 v31, 16, v31
	v_lshlrev_b32_e32 v32, 16, v32
	v_lshlrev_b32_e32 v34, 16, v34
	v_mul_f32_e32 v29, v196, v29
	v_mul_f32_e32 v32, v196, v32
	v_fmac_f32_e32 v29, v74, v28
	v_fmac_f32_e32 v32, v74, v31
	v_fmac_f32_e32 v29, v75, v30
	v_fmac_f32_e32 v32, v75, v34
	v_mul_f32_e32 v28, 0x39000000, v232
	v_mul_f32_e32 v31, 0xb9000000, v233
	v_add_f32_e32 v29, v195, v29
	v_add_f32_e32 v32, v195, v32
	v_mul_f32_e32 v28, v28, v29
	v_mul_f32_e32 v31, v31, v32
	v_cvt_pk_bf16_f32 v28, v28, v28
	v_cvt_pk_bf16_f32 v31, v31, v31
	global_store_short v[204:205], v28, off offset:1536
	global_store_short v[206:207], v31, off offset:1536
	s_waitcnt vmcnt(32)
	v_lshlrev_b32_e32 v35, 16, v35
	v_lshlrev_b32_e32 v36, 16, v36
	v_lshlrev_b32_e32 v37, 16, v37
	v_lshlrev_b32_e32 v38, 16, v38
	v_lshlrev_b32_e32 v39, 16, v39
	v_lshlrev_b32_e32 v40, 16, v40
	v_mul_f32_e32 v36, v196, v36
	v_mul_f32_e32 v39, v196, v39
	v_fmac_f32_e32 v36, v74, v35
	v_fmac_f32_e32 v39, v74, v38
	v_fmac_f32_e32 v36, v75, v37
	v_fmac_f32_e32 v39, v75, v40
	v_mul_f32_e32 v35, 0x39000000, v236
	v_mul_f32_e32 v38, 0xb9000000, v237
	v_add_f32_e32 v36, v195, v36
	v_add_f32_e32 v39, v195, v39
	v_mul_f32_e32 v35, v35, v36
	v_mul_f32_e32 v38, v38, v39
	v_cvt_pk_bf16_f32 v35, v35, v35
	v_cvt_pk_bf16_f32 v38, v38, v38
	global_store_short v[204:205], v35, off offset:2048
	global_store_short v[206:207], v38, off offset:2048
	s_waitcnt vmcnt(26)
	v_lshlrev_b32_e32 v41, 16, v41
	v_lshlrev_b32_e32 v42, 16, v42
	v_lshlrev_b32_e32 v43, 16, v43
	v_lshlrev_b32_e32 v44, 16, v44
	v_lshlrev_b32_e32 v45, 16, v45
	v_lshlrev_b32_e32 v46, 16, v46
	v_mul_f32_e32 v42, v196, v42
	v_mul_f32_e32 v45, v196, v45
	v_fmac_f32_e32 v42, v74, v41
	v_fmac_f32_e32 v45, v74, v44
	v_fmac_f32_e32 v42, v75, v43
	v_fmac_f32_e32 v45, v75, v46
	v_mul_f32_e32 v41, 0x39000000, v238
	v_mul_f32_e32 v44, 0xb9000000, v239
	v_add_f32_e32 v42, v195, v42
	v_add_f32_e32 v45, v195, v45
	v_mul_f32_e32 v41, v41, v42
	v_mul_f32_e32 v44, v44, v45
	v_cvt_pk_bf16_f32 v41, v41, v41
	v_cvt_pk_bf16_f32 v44, v44, v44
	global_store_short v[204:205], v41, off offset:2560
	global_store_short v[206:207], v44, off offset:2560
	s_waitcnt vmcnt(20)
	v_lshlrev_b32_e32 v47, 16, v47
	v_lshlrev_b32_e32 v48, 16, v48
	v_lshlrev_b32_e32 v49, 16, v49
	v_lshlrev_b32_e32 v50, 16, v50
	v_lshlrev_b32_e32 v51, 16, v51
	v_lshlrev_b32_e32 v52, 16, v52
	v_mul_f32_e32 v48, v196, v48
	v_mul_f32_e32 v51, v196, v51
	v_fmac_f32_e32 v48, v74, v47
	v_fmac_f32_e32 v51, v74, v50
	v_fmac_f32_e32 v48, v75, v49
	v_fmac_f32_e32 v51, v75, v52
	v_mul_f32_e32 v47, 0x39000000, v240
	v_mul_f32_e32 v50, 0xb9000000, v241
	v_add_f32_e32 v48, v195, v48
	v_add_f32_e32 v51, v195, v51
	v_mul_f32_e32 v47, v47, v48
	v_mul_f32_e32 v50, v50, v51
	v_cvt_pk_bf16_f32 v47, v47, v47
	v_cvt_pk_bf16_f32 v50, v50, v50
	global_store_short v[204:205], v47, off offset:3072
	global_store_short v[206:207], v50, off offset:3072
	s_waitcnt vmcnt(14)
	v_cndmask_b32_e64 v55, v55, 0, s[10:11]
	v_cndmask_b32_e64 v58, v58, 0, s[10:11]
	v_lshlrev_b32_e32 v53, 16, v53
	v_lshlrev_b32_e32 v54, 16, v54
	v_lshlrev_b32_e32 v55, 16, v55
	v_lshlrev_b32_e32 v56, 16, v56
	v_lshlrev_b32_e32 v57, 16, v57
	v_lshlrev_b32_e32 v58, 16, v58
	v_mul_f32_e32 v54, v196, v54
	v_mul_f32_e32 v57, v196, v57
	v_fmac_f32_e32 v54, v74, v53
	v_fmac_f32_e32 v57, v74, v56
	v_fmac_f32_e32 v54, v75, v55
	v_fmac_f32_e32 v57, v75, v58
	v_mul_f32_e32 v53, 0x39000000, v244
	v_mul_f32_e32 v56, 0xb9000000, v245
	v_add_f32_e32 v54, v195, v54
	v_add_f32_e32 v57, v195, v57
	v_mul_f32_e32 v53, v53, v54
	v_mul_f32_e32 v56, v56, v57
	v_cvt_pk_bf16_f32 v53, v53, v53
	v_cvt_pk_bf16_f32 v56, v56, v56
	global_store_short v[204:205], v53, off offset:3584
	global_store_short v[206:207], v56, off offset:3584
	s_branch .LBB0_936

;     ...
;     float A = 1.f, Bv = 0.f;
; #pragma unroll
;     for (int e = 0; e < 34; ++e) { A *= ab[e].x; Bv = ab[e].x * Bv + ab[e].y; }
;     ((f32x2*)carry)[(part * 2 + dir) * 64 + c] = mkf2(A, Bv);
;   }
;   __syncthreads();
;   const int th = w >> 1, chh = w & 1;
;   f32x16 acc[4];
; #pragma unroll
;   for (int m = 0; m < 4; ++m) zero_acc(acc[m]);
;   const u16* Wl = (const u16*)(p->ws + OFF_W) + W_LRU + (size_t)g * 256 * 64;
; #pragma unroll
;   for (int s = 0; s < 4; ++s) {
;     bf16x8 a = *(const bf16x8*)(Au + (th * 32 + l31) * 72 + s * 16 + hh * 8);
; #pragma unroll
;     for (int m = 0; m < 4; ++m) {
;       bf16x8 bb = *(const bf16x8*)(Wl + (size_t)(m * 64 + chh * 32 + l31) * 64 + s * 16 + hh * 8);
.Llru_carry_done:
	s_waitcnt vmcnt(0)
	v_mov_b32_e32 v41, v39
	v_fmac_f32_e32 v3, 0, v2
	v_fmac_f32_e32 v7, v3, v6
	v_fmac_f32_e32 v9, v7, v8
	v_fmac_f32_e32 v11, v9, v10
	v_fmac_f32_e32 v13, v11, v12
	v_fmac_f32_e32 v15, v13, v14
	v_fmac_f32_e32 v17, v15, v16
	v_fmac_f32_e32 v19, v17, v18
	v_fmac_f32_e32 v21, v19, v20
	v_fmac_f32_e32 v23, v21, v22
	v_fmac_f32_e32 v25, v23, v24
	v_fmac_f32_e32 v27, v25, v26
	v_fmac_f32_e32 v29, v27, v28
	v_fmac_f32_e32 v31, v29, v30
	v_fmac_f32_e32 v33, v31, v32
	v_fmac_f32_e32 v35, v33, v34
	v_fmac_f32_e32 v37, v35, v36
	v_mul_f32_e32 v40, v2, v6
	v_fmac_f32_e32 v41, v37, v38
	v_mov_b32_e32 v9, v42
	v_pk_mul_f32 v[2:3], v[40:41], v[8:9]
	v_pk_fma_f32 v[4:5], v[40:41], v[8:9], v[42:43]
	v_pk_mul_f32 v[2:3], v[2:3], v[10:11]
	v_mov_b32_e32 v13, v44
	v_mov_b32_e32 v4, v2
	v_pk_mul_f32 v[2:3], v[2:3], v[12:13]
	v_pk_fma_f32 v[4:5], v[4:5], v[12:13], v[44:45]
	v_pk_mul_f32 v[2:3], v[2:3], v[14:15]
	v_mov_b32_e32 v17, v46
	v_mov_b32_e32 v3, v5
	v_pk_mul_f32 v[4:5], v[2:3], v[16:17]
	v_pk_fma_f32 v[2:3], v[2:3], v[16:17], v[46:47]
	v_pk_mul_f32 v[4:5], v[4:5], v[18:19]
	v_mov_b32_e32 v21, v48
	v_mov_b32_e32 v2, v4
	v_pk_mul_f32 v[4:5], v[4:5], v[20:21]
	v_pk_fma_f32 v[2:3], v[2:3], v[20:21], v[48:49]
	v_pk_mul_f32 v[4:5], v[4:5], v[22:23]
	v_mov_b32_e32 v25, v50
	v_mov_b32_e32 v5, v3
	v_pk_mul_f32 v[2:3], v[4:5], v[24:25]
	v_pk_fma_f32 v[4:5], v[4:5], v[24:25], v[50:51]
	v_pk_mul_f32 v[2:3], v[2:3], v[26:27]
	v_mov_b32_e32 v29, v52
	v_mov_b32_e32 v4, v2
	v_pk_mul_f32 v[2:3], v[2:3], v[28:29]
	v_pk_fma_f32 v[4:5], v[4:5], v[28:29], v[52:53]
	v_pk_mul_f32 v[2:3], v[2:3], v[30:31]
	v_mov_b32_e32 v33, v54
	v_mov_b32_e32 v3, v5
	v_pk_mul_f32 v[4:5], v[2:3], v[32:33]
	v_pk_fma_f32 v[2:3], v[2:3], v[32:33], v[54:55]
	v_pk_mul_f32 v[4:5], v[4:5], v[34:35]
	v_mov_b32_e32 v37, v56
	v_lshlrev_b32_e32 v39, 9, v79
	v_mov_b32_e32 v2, v4
	v_pk_mul_f32 v[4:5], v[4:5], v[36:37]
	v_pk_fma_f32 v[2:3], v[2:3], v[36:37], v[56:57]
	v_pk_mul_f32 v[4:5], v[4:5], v[38:39]
	v_mov_b32_e32 v43, v58
	v_mov_b32_e32 v5, v3
	v_pk_mul_f32 v[2:3], v[4:5], v[42:43]
	v_pk_fma_f32 v[4:5], v[4:5], v[42:43], v[58:59]
	v_pk_mul_f32 v[2:3], v[2:3], v[44:45]
	v_mov_b32_e32 v47, v60
	v_mov_b32_e32 v4, v2
	v_pk_mul_f32 v[2:3], v[2:3], v[46:47]
	v_pk_fma_f32 v[4:5], v[4:5], v[46:47], v[60:61]
	v_pk_mul_f32 v[2:3], v[2:3], v[48:49]
	v_mov_b32_e32 v51, v62
	v_mov_b32_e32 v3, v5
	v_pk_mul_f32 v[4:5], v[2:3], v[50:51]
	v_pk_fma_f32 v[2:3], v[2:3], v[50:51], v[62:63]
	v_pk_mul_f32 v[4:5], v[4:5], v[52:53]
	v_mov_b32_e32 v55, v64
	v_mov_b32_e32 v2, v4
	v_pk_mul_f32 v[4:5], v[4:5], v[54:55]
	v_pk_fma_f32 v[2:3], v[2:3], v[54:55], v[64:65]
	v_pk_mul_f32 v[4:5], v[4:5], v[56:57]
	v_mov_b32_e32 v59, v66
	v_mov_b32_e32 v5, v3
	v_pk_mul_f32 v[2:3], v[4:5], v[58:59]
	v_pk_fma_f32 v[4:5], v[4:5], v[58:59], v[66:67]
	v_pk_mul_f32 v[2:3], v[2:3], v[60:61]
	v_mov_b32_e32 v63, v68
	v_mov_b32_e32 v4, v2
	v_pk_mul_f32 v[2:3], v[2:3], v[62:63]
	v_pk_fma_f32 v[4:5], v[4:5], v[62:63], v[68:69]
	v_pk_mul_f32 v[2:3], v[2:3], v[64:65]
	v_mov_b32_e32 v67, v70
	v_mov_b32_e32 v3, v5
	v_pk_mul_f32 v[4:5], v[2:3], v[66:67]
	v_pk_fma_f32 v[2:3], v[2:3], v[66:67], v[70:71]
	v_pk_mul_f32 v[4:5], v[4:5], v[68:69]
	v_mov_b32_e32 v71, v72
	v_mov_b32_e32 v2, v4
	v_pk_mul_f32 v[4:5], v[4:5], v[70:71]
	v_pk_fma_f32 v[2:3], v[2:3], v[70:71], v[72:73]
	v_and_b32_e32 v75, 0xffffff80, v76
	v_pk_mul_f32 v[4:5], v[4:5], v[72:73]
	v_lshl_or_b32 v2, v75, 3, v39
	v_and_b32_e32 v82, 31, v76
	v_lshrrev_b32_e32 v74, 5, v77
	v_mov_b32_e32 v5, v3
	v_lshl_add_u32 v2, v77, 3, v2
	s_lshl_b32 s2, s29, 15
	v_lshlrev_b32_e32 v77, 5, v78
	ds_write_b64 v2, v[4:5] offset:59136
	s_add_u32 s2, s6, s2
	v_or_b32_e32 v2, v77, v82
	v_lshlrev_b32_e32 v198, 4, v74
	s_addc_u32 s3, s7, 0
	v_mad_u64_u32 v[80:81], s[4:5], v2, s60, v[198:199]
	v_lshl_add_u64 v[90:91], s[2:3], 0, v[198:199]
	s_mov_b64 s[2:3], 0xe3e0000
	v_lshl_or_b32 v81, v79, 5, v82
	v_lshl_add_u64 v[10:11], v[90:91], 0, s[2:3]
	v_lshlrev_b32_e32 v12, 7, v81
	v_mov_b32_e32 v13, v199
	v_lshl_add_u64 v[72:73], v[10:11], 0, v[12:13]
	s_waitcnt lgkmcnt(0)
	s_barrier
; #define MFMA32(a, b, c) __builtin_amdgcn_mfma_f32_32x32x16_bf16((a), (b), (c), 0, 0, 0)
;     ...
;   const u16* Wl = (const u16*)(p->ws + OFF_W) + W_LRU + (size_t)g * 256 * 64;
; #pragma unroll
;   for (int s = 0; s < 4; ++s) {
;     bf16x8 a = *(const bf16x8*)(Au + (th * 32 + l31) * 72 + s * 16 + hh * 8);
; #pragma unroll
;     for (int m = 0; m < 4; ++m) {
;       bf16x8 bb = *(const bf16x8*)(Wl + (size_t)(m * 64 + chh * 32 + l31) * 64 + s * 16 + hh * 8);
;       acc[m] = MFMA32(a, bb, acc[m]);
;     }
;   }
;   asm volatile("s_nop 15\n\ts_nop 15" ::: "memory");
;   const int cl = chh * 32 + l31, cg = g * 64 + cl;
;   float hsum[16];
; #pragma unroll
;   for (int dir = 0; dir < 2; ++dir) {
;     const float ba = p->lru_ba[(l * 2 + dir) * 512 + cg], bx = p->lru_bx[(l * 2 + dir) * 512 + cg];
;     const float lam = p->lru_lam[(l * 2 + dir) * 512 + cg];
;     const float ex = __expf(-lam);
;     const float sp = (ex < 0.03f) ? ex * (1.f - ex * (0.5f - ex * (0.33333334f - 0.25f * ex))) : __logf(1.f + ex);
	s_mov_b64 vcc, 0x2000
	v_lshl_add_u64 v[120:121], v[72:73], 0, vcc
	v_lshl_add_u64 v[122:123], v[120:121], 0, vcc
	v_lshl_add_u64 v[124:125], v[122:123], 0, vcc
	ds_read_b128 v[104:107], v80
	ds_read_b128 v[108:111], v80 offset:32
	ds_read_b128 v[112:115], v80 offset:64
	ds_read_b128 v[116:119], v80 offset:96
	global_load_dwordx4 v[132:135], v[72:73], off
	global_load_dwordx4 v[148:151], v[120:121], off
	global_load_dwordx4 v[164:167], v[122:123], off
	global_load_dwordx4 v[180:183], v[124:125], off
	global_load_dwordx4 v[136:139], v[72:73], off offset:32
	global_load_dwordx4 v[152:155], v[120:121], off offset:32
	global_load_dwordx4 v[168:171], v[122:123], off offset:32
	global_load_dwordx4 v[184:187], v[124:125], off offset:32
	global_load_dwordx4 v[140:143], v[72:73], off offset:64
	global_load_dwordx4 v[156:159], v[120:121], off offset:64
	global_load_dwordx4 v[172:175], v[122:123], off offset:64
	global_load_dwordx4 v[188:191], v[124:125], off offset:64
	global_load_dwordx4 v[144:147], v[72:73], off offset:96
	global_load_dwordx4 v[160:163], v[120:121], off offset:96
	global_load_dwordx4 v[176:179], v[122:123], off offset:96
	global_load_dwordx4 v[192:195], v[124:125], off offset:96
	s_waitcnt lgkmcnt(1)
	s_nop 0
	s_waitcnt lgkmcnt(0)
	s_waitcnt lgkmcnt(0)
	v_or_b32_e32 v72, s28, v81
	s_waitcnt lgkmcnt(0)
	s_nop 15
	s_nop 15
	s_load_dwordx2 s[2:3], s[16:17], 0x80
	s_load_dwordx4 s[8:11], s[16:17], 0x90
	v_or_b32_e32 v66, s74, v72
	v_mov_b32_e32 v67, v199
	v_lshlrev_b64 v[70:71], 2, v[66:67]
	s_waitcnt lgkmcnt(0)
	v_lshl_add_u64 v[66:67], s[2:3], 0, v[70:71]
	v_lshl_add_u64 v[68:69], s[8:9], 0, v[70:71]
	v_lshl_add_u64 v[70:71], s[10:11], 0, v[70:71]
	s_waitcnt lgkmcnt(0)
	s_waitcnt vmcnt(15)
	v_mfma_f32_32x32x16_bf16 v[50:65], v[104:107], v[132:135], 0
	s_waitcnt vmcnt(14)
	v_mfma_f32_32x32x16_bf16 v[34:49], v[104:107], v[148:151], 0
	s_waitcnt vmcnt(13)
	v_mfma_f32_32x32x16_bf16 v[18:33], v[104:107], v[164:167], 0
	s_waitcnt vmcnt(12)
	v_mfma_f32_32x32x16_bf16 v[2:17], v[104:107], v[180:183], 0
	s_waitcnt vmcnt(11)
	v_mfma_f32_32x32x16_bf16 v[50:65], v[108:111], v[136:139], v[50:65]
	s_waitcnt vmcnt(10)
	v_mfma_f32_32x32x16_bf16 v[34:49], v[108:111], v[152:155], v[34:49]
	s_waitcnt vmcnt(9)
	v_mfma_f32_32x32x16_bf16 v[18:33], v[108:111], v[168:171], v[18:33]
	s_waitcnt vmcnt(8)
	v_mfma_f32_32x32x16_bf16 v[2:17], v[108:111], v[184:187], v[2:17]
	s_waitcnt vmcnt(7)
	v_mfma_f32_32x32x16_bf16 v[50:65], v[112:115], v[140:143], v[50:65]
	s_waitcnt vmcnt(6)
	v_mfma_f32_32x32x16_bf16 v[34:49], v[112:115], v[156:159], v[34:49]
	s_waitcnt vmcnt(5)
	v_mfma_f32_32x32x16_bf16 v[18:33], v[112:115], v[172:175], v[18:33]
	s_waitcnt vmcnt(4)
	v_mfma_f32_32x32x16_bf16 v[2:17], v[112:115], v[188:191], v[2:17]
	s_waitcnt vmcnt(3)
	v_mfma_f32_32x32x16_bf16 v[50:65], v[116:119], v[144:147], v[50:65]
	s_waitcnt vmcnt(2)
	v_mfma_f32_32x32x16_bf16 v[34:49], v[116:119], v[160:163], v[34:49]
	s_waitcnt vmcnt(1)
	v_mfma_f32_32x32x16_bf16 v[18:33], v[116:119], v[176:179], v[18:33]
	s_waitcnt vmcnt(0)
	v_mfma_f32_32x32x16_bf16 v[2:17], v[116:119], v[192:195], v[2:17]
	global_load_dword v73, v[70:71], off
	global_load_dword v79, v[66:67], off
	global_load_dword v78, v[68:69], off
	s_mov_b32 s2, 0x3cf5c28f
	s_waitcnt vmcnt(2)
	v_mul_f32_e32 v73, 0xbfb8aa3b, v73
	v_exp_f32_e32 v73, v73
	s_nop 0
	v_cmp_ngt_f32_e32 vcc, s2, v73
	s_and_saveexec_b64 s[2:3], vcc
	s_xor_b64 s[10:11], exec, s[2:3]
	s_cbranch_execz .LBB0_1514
	v_add_f32_e32 v73, 1.0, v73
	s_mov_b32 s2, 0x800000
	v_cmp_gt_f32_e32 vcc, s2, v73
	s_mov_b32 s2, 0x3f317217
	s_nop 0
	v_cndmask_b32_e64 v80, 0, 32, vcc
	v_ldexp_f32 v73, v73, v80
	v_log_f32_e32 v73, v73
	s_nop 0
	v_mul_f32_e32 v80, 0x3f317217, v73
	v_fma_f32 v80, v73, s2, -v80
	v_fmac_f32_e32 v80, 0x3377d1cf, v73
	s_mov_b32 s2, 0x7f800000
	v_fmac_f32_e32 v80, 0x3f317217, v73
	v_cmp_lt_f32_e64 s[8:9], |v73|, s2
	s_nop 1
	v_cndmask_b32_e64 v73, v73, v80, s[8:9]
	v_mov_b32_e32 v80, 0x41b17218
	v_cndmask_b32_e32 v80, 0, v80, vcc
	v_sub_f32_e32 v80, v73, v80
